# GEMM epilogue bf16 stores merged pairwise into dwordx4 via v_permlane16_swap (E, odd-A, even-A); on top of LDS-DMA GEMM+MoBA and PEER trims
# speedup vs baseline: 1.0813x; 1.0259x over previous
; template <int MI, bool SWAP, bool F8 = false>
; __device__ __forceinline__ void gemm_core(const bf16_t* __restrict__ A, int lda, const bf16_t* __restrict__ B, int ldb,
;                                           int K, char* smem, f32x4 (&acc)[MI][4]) {
;     ...
;   for (int kt = 0; kt < nk; ++kt) {
;     __syncthreads();
; #pragma unroll
;     for (int i = 0; i < MI; ++i) *(u32x4*)(smem + woff + i * 4096) = ra[i];
; #pragma unroll
;     for (int i = 0; i < 4; ++i) *(u32x4*)(smem + 32768 + woff + i * 4096) = rb[i];
;     __syncthreads();
;     if (kt + 1 < nk) {
; #pragma unroll
;       for (int i = 0; i < MI; ++i) ra[i] = *(const u32x4*)(ap + (size_t)(32 * i) * lda + (kt + 1) * 64);
; #pragma unroll
;       for (int i = 0; i < 4; ++i) rb[i] = *(const u32x4*)(bp + (size_t)(32 * i) * ldb + (kt + 1) * 64);
;     }
;     if (F8) {
;       const int c0 = (g ^ (li & 7)) << 4, c1 = ((4 + g) ^ (li & 7)) << 4;
;       i32x8 wf8[4];
; #pragma unroll
;       for (int j = 0; j < 4; ++j) {
;         const char* rp = smem + wrow + ((j & 1) * 16 + (j >> 1) * 64) * 128;
;         const u32x4 lo = *(const u32x4*)(rp + c0), hi = *(const u32x4*)(rp + c1);
;         wf8[j] = (i32x8){(int)lo.x, (int)lo.y, (int)lo.z, (int)lo.w, (int)hi.x, (int)hi.y, (int)hi.z, (int)hi.w};
;       }
; #pragma unroll
;       for (int i = 0; i < MI; ++i) {
;         const char* rp = smem + xrow + i * 2048;
;         const u32x4 lo = *(const u32x4*)(rp + c0), hi = *(const u32x4*)(rp + c1);
;         const i32x8 xf8 = {(int)lo.x, (int)lo.y, (int)lo.z, (int)lo.w, (int)hi.x, (int)hi.y, (int)hi.z, (int)hi.w};
; #pragma unroll
;         for (int j = 0; j < 4; ++j)
;           acc[i][j] = __builtin_amdgcn_mfma_scale_f32_16x16x128_f8f6f4(wf8[j], xf8, acc[i][j], 0, 0, 0, 0x77777777, 0, 0x7f7f7f7f);
;       }
;     } else {
; #pragma unroll
;     for (int kk = 0; kk < 2; ++kk) {
;       const int ch = ((kk * 4 + g) ^ (li & 7)) << 4;
;       bf16x8 xf[MI], wf[4];
; #pragma unroll
;       for (int j = 0; j < 4; ++j) wf[j] = *(const bf16x8*)(smem + wrow + ((j & 1) * 16 + (j >> 1) * 64) * 128 + ch);
; #pragma unroll
;       for (int i = 0; i < MI; ++i) xf[i] = *(const bf16x8*)(smem + xrow + i * 2048 + ch);
; #pragma unroll
;       for (int i = 0; i < MI; ++i)
; #pragma unroll
;         for (int j = 0; j < 4; ++j) {
.LBB0_120:
	s_barrier
	s_mov_b32 m0, s62
	s_nop 0
	global_load_lds_dwordx4 v252, s[56:57]
	s_add_u32 m0, s62, 0x1000
	s_nop 0
	global_load_lds_dwordx4 v253, s[56:57]
	s_add_u32 s56, s56, 0x20000
	s_addc_u32 s57, s57, 0
	s_add_u32 m0, s62, 0x2000
	s_nop 0
	global_load_lds_dwordx4 v252, s[56:57]
	s_add_u32 m0, s62, 0x3000
	s_nop 0
	global_load_lds_dwordx4 v253, s[56:57]
	s_add_u32 s56, s56, 0x20000
	s_addc_u32 s57, s57, 0
	s_add_u32 m0, s62, 0x4000
	s_nop 0
	global_load_lds_dwordx4 v252, s[56:57]
	s_add_u32 m0, s62, 0x5000
	s_nop 0
	global_load_lds_dwordx4 v253, s[56:57]
	s_add_u32 s56, s56, 0x20000
	s_addc_u32 s57, s57, 0
	s_add_u32 m0, s62, 0x6000
	s_nop 0
	global_load_lds_dwordx4 v252, s[56:57]
	s_add_u32 m0, s62, 0x7000
	s_nop 0
	global_load_lds_dwordx4 v253, s[56:57]
	s_sub_u32 s56, s56, 0x60000
	s_subb_u32 s57, s57, 0
	s_add_u32 m0, s62, 0x8000
	s_nop 0
	global_load_lds_dwordx4 v252, s[58:59]
	s_add_u32 m0, s62, 0x9000
	s_nop 0
	global_load_lds_dwordx4 v253, s[58:59]
	s_add_u32 s58, s58, 0x20000
	s_addc_u32 s59, s59, 0
	s_add_u32 m0, s62, 0xa000
	s_nop 0
	global_load_lds_dwordx4 v252, s[58:59]
	s_add_u32 m0, s62, 0xb000
	s_nop 0
	global_load_lds_dwordx4 v253, s[58:59]
	s_sub_u32 s58, s58, 0x20000
	s_subb_u32 s59, s59, 0
	v_add_u32_e32 v252, 0x80, v252
	v_add_u32_e32 v253, 0x80, v253
	s_waitcnt vmcnt(0)
	s_barrier
	ds_read_b128 v[148:151], v215 offset:32768
	ds_read_b128 v[152:155], v215 offset:34816
	ds_read_b128 v[156:159], v213
	ds_read_b128 v[160:163], v213 offset:2048
	ds_read_b128 v[164:167], v215 offset:40960
	ds_read_b128 v[168:171], v215 offset:43008
	s_waitcnt lgkmcnt(3)
	v_mfma_f32_16x16x32_bf16 v[140:143], v[148:151], v[156:159], v[140:143]
	v_mfma_f32_16x16x32_bf16 v[136:139], v[152:155], v[156:159], v[136:139]
	s_waitcnt lgkmcnt(1)
	v_mfma_f32_16x16x32_bf16 v[132:135], v[164:167], v[156:159], v[132:135]
	s_waitcnt lgkmcnt(0)
	v_mfma_f32_16x16x32_bf16 v[128:131], v[168:171], v[156:159], v[128:131]
	v_mfma_f32_16x16x32_bf16 v[124:127], v[148:151], v[160:163], v[124:127]
	v_mfma_f32_16x16x32_bf16 v[120:123], v[152:155], v[160:163], v[120:123]
	v_mfma_f32_16x16x32_bf16 v[116:119], v[164:167], v[160:163], v[116:119]
	v_mfma_f32_16x16x32_bf16 v[104:107], v[168:171], v[160:163], v[104:107]
	ds_read_b128 v[156:159], v213 offset:4096
	ds_read_b128 v[160:163], v213 offset:6144
	s_waitcnt lgkmcnt(1)
	v_mfma_f32_16x16x32_bf16 v[88:91], v[148:151], v[156:159], v[88:91]
	v_mfma_f32_16x16x32_bf16 v[84:87], v[152:155], v[156:159], v[84:87]
	v_mfma_f32_16x16x32_bf16 v[80:83], v[164:167], v[156:159], v[80:83]
	v_mfma_f32_16x16x32_bf16 v[76:79], v[168:171], v[156:159], v[76:79]
	s_waitcnt lgkmcnt(0)
	v_mfma_f32_16x16x32_bf16 v[72:75], v[148:151], v[160:163], v[72:75]
	v_mfma_f32_16x16x32_bf16 v[68:71], v[152:155], v[160:163], v[68:71]
	v_mfma_f32_16x16x32_bf16 v[64:67], v[164:167], v[160:163], v[64:67]
	v_mfma_f32_16x16x32_bf16 v[60:63], v[168:171], v[160:163], v[60:63]
	ds_read_b128 v[156:159], v213 offset:8192
	ds_read_b128 v[160:163], v213 offset:10240
	s_waitcnt lgkmcnt(1)
	v_mfma_f32_16x16x32_bf16 v[44:47], v[148:151], v[156:159], v[44:47]
	v_mfma_f32_16x16x32_bf16 v[40:43], v[152:155], v[156:159], v[40:43]
	v_mfma_f32_16x16x32_bf16 v[36:39], v[164:167], v[156:159], v[36:39]
	v_mfma_f32_16x16x32_bf16 v[32:35], v[168:171], v[156:159], v[32:35]
	s_waitcnt lgkmcnt(0)
	v_mfma_f32_16x16x32_bf16 v[28:31], v[148:151], v[160:163], v[28:31]
	v_mfma_f32_16x16x32_bf16 v[24:27], v[152:155], v[160:163], v[24:27]
	v_mfma_f32_16x16x32_bf16 v[20:23], v[164:167], v[160:163], v[20:23]
	v_mfma_f32_16x16x32_bf16 v[52:55], v[168:171], v[160:163], v[52:55]
	ds_read_b128 v[156:159], v213 offset:12288
	ds_read_b128 v[160:163], v213 offset:14336
	ds_read_b128 v[172:175], v206 offset:32768
	ds_read_b128 v[180:183], v206 offset:34816
	s_waitcnt lgkmcnt(3)
	v_mfma_f32_16x16x32_bf16 v[48:51], v[148:151], v[156:159], v[48:51]
	v_mfma_f32_16x16x32_bf16 v[56:59], v[152:155], v[156:159], v[56:59]
	s_waitcnt lgkmcnt(2)
	v_mfma_f32_16x16x32_bf16 v[100:103], v[148:151], v[160:163], v[100:103]
	v_mfma_f32_16x16x32_bf16 v[96:99], v[152:155], v[160:163], v[96:99]
	ds_read_b128 v[148:151], v0
	ds_read_b128 v[152:155], v0 offset:2048
	ds_read_b128 v[192:195], v206 offset:40960
	ds_read_b128 v[196:199], v206 offset:43008
	s_waitcnt lgkmcnt(3)
	v_mfma_f32_16x16x32_bf16 v[140:143], v[172:175], v[148:151], v[140:143]
	v_mfma_f32_16x16x32_bf16 v[136:139], v[180:183], v[148:151], v[136:139]
	s_waitcnt lgkmcnt(1)
	v_mfma_f32_16x16x32_bf16 v[132:135], v[192:195], v[148:151], v[132:135]
	s_waitcnt lgkmcnt(0)
	v_mfma_f32_16x16x32_bf16 v[128:131], v[196:199], v[148:151], v[128:131]
	v_mfma_f32_16x16x32_bf16 v[124:127], v[172:175], v[152:155], v[124:127]
	v_mfma_f32_16x16x32_bf16 v[120:123], v[180:183], v[152:155], v[120:123]
	v_mfma_f32_16x16x32_bf16 v[116:119], v[192:195], v[152:155], v[116:119]
	v_mfma_f32_16x16x32_bf16 v[104:107], v[196:199], v[152:155], v[104:107]
	ds_read_b128 v[148:151], v0 offset:4096
	ds_read_b128 v[152:155], v0 offset:6144
	v_mfma_f32_16x16x32_bf16 v[112:115], v[164:167], v[156:159], v[112:115]
	v_mfma_f32_16x16x32_bf16 v[92:95], v[164:167], v[160:163], v[92:95]
	v_mfma_f32_16x16x32_bf16 v[108:111], v[168:171], v[156:159], v[108:111]
	v_mfma_f32_16x16x32_bf16 v[144:147], v[168:171], v[160:163], v[144:147]
	s_waitcnt lgkmcnt(0)
; template <int MI, bool SWAP, bool F8 = false>
; __device__ __forceinline__ void gemm_core(const bf16_t* __restrict__ A, int lda, const bf16_t* __restrict__ B, int ldb,
;                                           int K, char* smem, f32x4 (&acc)[MI][4]) {
;     ...
;   for (int kt = 0; kt < nk; ++kt) {
;     __syncthreads();
; #pragma unroll
;     for (int i = 0; i < MI; ++i) *(u32x4*)(smem + woff + i * 4096) = ra[i];
; #pragma unroll
;     for (int i = 0; i < 4; ++i) *(u32x4*)(smem + 32768 + woff + i * 4096) = rb[i];
;     __syncthreads();
;     if (kt + 1 < nk) {
; #pragma unroll
;       for (int i = 0; i < MI; ++i) ra[i] = *(const u32x4*)(ap + (size_t)(32 * i) * lda + (kt + 1) * 64);
; #pragma unroll
;       for (int i = 0; i < 4; ++i) rb[i] = *(const u32x4*)(bp + (size_t)(32 * i) * ldb + (kt + 1) * 64);
;     }
;     if (F8) {
;       const int c0 = (g ^ (li & 7)) << 4, c1 = ((4 + g) ^ (li & 7)) << 4;
;       i32x8 wf8[4];
; #pragma unroll
;       for (int j = 0; j < 4; ++j) {
;         const char* rp = smem + wrow + ((j & 1) * 16 + (j >> 1) * 64) * 128;
;         const u32x4 lo = *(const u32x4*)(rp + c0), hi = *(const u32x4*)(rp + c1);
;         wf8[j] = (i32x8){(int)lo.x, (int)lo.y, (int)lo.z, (int)lo.w, (int)hi.x, (int)hi.y, (int)hi.z, (int)hi.w};
;       }
; #pragma unroll
;       for (int i = 0; i < MI; ++i) {
;         const char* rp = smem + xrow + i * 2048;
;         const u32x4 lo = *(const u32x4*)(rp + c0), hi = *(const u32x4*)(rp + c1);
;         const i32x8 xf8 = {(int)lo.x, (int)lo.y, (int)lo.z, (int)lo.w, (int)hi.x, (int)hi.y, (int)hi.z, (int)hi.w};
; #pragma unroll
;         for (int j = 0; j < 4; ++j)
;           acc[i][j] = __builtin_amdgcn_mfma_scale_f32_16x16x128_f8f6f4(wf8[j], xf8, acc[i][j], 0, 0, 0, 0x77777777, 0, 0x7f7f7f7f);
;       }
;     } else {
; #pragma unroll
;     for (int kk = 0; kk < 2; ++kk) {
;       const int ch = ((kk * 4 + g) ^ (li & 7)) << 4;
;       bf16x8 xf[MI], wf[4];
; #pragma unroll
;       for (int j = 0; j < 4; ++j) wf[j] = *(const bf16x8*)(smem + wrow + ((j & 1) * 16 + (j >> 1) * 64) * 128 + ch);
; #pragma unroll
;       for (int i = 0; i < MI; ++i) xf[i] = *(const bf16x8*)(smem + xrow + i * 2048 + ch);
; #pragma unroll
;       for (int i = 0; i < MI; ++i)
; #pragma unroll
;         for (int j = 0; j < 4; ++j) {
	v_mfma_f32_16x16x32_bf16 v[72:75], v[172:175], v[152:155], v[72:75]
	v_mfma_f32_16x16x32_bf16 v[68:71], v[180:183], v[152:155], v[68:71]
	v_mfma_f32_16x16x32_bf16 v[64:67], v[192:195], v[152:155], v[64:67]
	v_mfma_f32_16x16x32_bf16 v[60:63], v[196:199], v[152:155], v[60:63]
	v_mfma_f32_16x16x32_bf16 v[88:91], v[172:175], v[148:151], v[88:91]
	v_mfma_f32_16x16x32_bf16 v[84:87], v[180:183], v[148:151], v[84:87]
	v_mfma_f32_16x16x32_bf16 v[80:83], v[192:195], v[148:151], v[80:83]
	v_mfma_f32_16x16x32_bf16 v[76:79], v[196:199], v[148:151], v[76:79]
	ds_read_b128 v[148:151], v0 offset:8192
	ds_read_b128 v[156:159], v0 offset:10240
	ds_read_b128 v[160:163], v0 offset:12288
	ds_read_b128 v[200:203], v0 offset:14336
	s_waitcnt lgkmcnt(3)
	v_mfma_f32_16x16x32_bf16 v[44:47], v[172:175], v[148:151], v[44:47]
	v_mfma_f32_16x16x32_bf16 v[40:43], v[180:183], v[148:151], v[40:43]
	v_mfma_f32_16x16x32_bf16 v[36:39], v[192:195], v[148:151], v[36:39]
	v_mfma_f32_16x16x32_bf16 v[32:35], v[196:199], v[148:151], v[32:35]
	s_waitcnt lgkmcnt(2)
	v_mfma_f32_16x16x32_bf16 v[28:31], v[172:175], v[156:159], v[28:31]
	v_mfma_f32_16x16x32_bf16 v[24:27], v[180:183], v[156:159], v[24:27]
	v_mfma_f32_16x16x32_bf16 v[20:23], v[192:195], v[156:159], v[20:23]
	v_mfma_f32_16x16x32_bf16 v[52:55], v[196:199], v[156:159], v[52:55]
	s_waitcnt lgkmcnt(1)
	v_mfma_f32_16x16x32_bf16 v[48:51], v[172:175], v[160:163], v[48:51]
	v_mfma_f32_16x16x32_bf16 v[56:59], v[180:183], v[160:163], v[56:59]
	v_mfma_f32_16x16x32_bf16 v[112:115], v[192:195], v[160:163], v[112:115]
	v_mfma_f32_16x16x32_bf16 v[108:111], v[196:199], v[160:163], v[108:111]
	s_waitcnt lgkmcnt(0)
	v_mfma_f32_16x16x32_bf16 v[100:103], v[172:175], v[200:203], v[100:103]
	v_mfma_f32_16x16x32_bf16 v[96:99], v[180:183], v[200:203], v[96:99]
	v_mfma_f32_16x16x32_bf16 v[92:95], v[192:195], v[200:203], v[92:95]
	v_mfma_f32_16x16x32_bf16 v[144:147], v[196:199], v[200:203], v[144:147]
	s_add_u32 s22, s22, 0x80
	s_addc_u32 s23, s23, 0
	s_cmpk_lg_i32 s22, 0x780
	s_cbranch_scc1 .LBB0_120
	s_barrier
	s_mov_b32 m0, s62
	s_nop 0
	global_load_lds_dwordx4 v252, s[56:57]
	s_add_u32 m0, s62, 0x1000
	s_nop 0
	global_load_lds_dwordx4 v253, s[56:57]
	s_add_u32 s56, s56, 0x20000
	s_addc_u32 s57, s57, 0
	s_add_u32 m0, s62, 0x2000
	s_nop 0
	global_load_lds_dwordx4 v252, s[56:57]
	s_add_u32 m0, s62, 0x3000
	s_nop 0
	global_load_lds_dwordx4 v253, s[56:57]
	s_add_u32 s56, s56, 0x20000
	s_addc_u32 s57, s57, 0
	s_add_u32 m0, s62, 0x4000
	s_nop 0
	global_load_lds_dwordx4 v252, s[56:57]
	s_add_u32 m0, s62, 0x5000
	s_nop 0
	global_load_lds_dwordx4 v253, s[56:57]
	s_add_u32 s56, s56, 0x20000
	s_addc_u32 s57, s57, 0
	s_add_u32 m0, s62, 0x6000
	s_nop 0
	global_load_lds_dwordx4 v252, s[56:57]
	s_add_u32 m0, s62, 0x7000
	s_nop 0
	global_load_lds_dwordx4 v253, s[56:57]
	s_sub_u32 s56, s56, 0x60000
	s_subb_u32 s57, s57, 0
	s_add_u32 m0, s62, 0x8000
	s_nop 0
	global_load_lds_dwordx4 v252, s[58:59]
	s_add_u32 m0, s62, 0x9000
	s_nop 0
	global_load_lds_dwordx4 v253, s[58:59]
	s_add_u32 s58, s58, 0x20000
	s_addc_u32 s59, s59, 0
	s_add_u32 m0, s62, 0xa000
	s_nop 0
	global_load_lds_dwordx4 v252, s[58:59]
	s_add_u32 m0, s62, 0xb000
	s_nop 0
	global_load_lds_dwordx4 v253, s[58:59]
	s_sub_u32 s58, s58, 0x20000
	s_subb_u32 s59, s59, 0
	s_waitcnt vmcnt(0)
	s_barrier
	v_bfe_u32 v12, v208, 4, 1
	v_mul_u32_u24_e32 v12, 24, v12
	v_mov_b32_e32 v13, 0
	ds_read_b128 v[148:151], v215 offset:32768
	ds_read_b128 v[152:155], v215 offset:34816
	ds_read_b128 v[156:159], v215 offset:40960
	ds_read_b128 v[160:163], v215 offset:43008
	ds_read_b128 v[164:167], v213
	ds_read_b128 v[168:171], v213 offset:2048
	ds_read_b128 v[172:175], v213 offset:4096
	ds_read_b128 v[176:179], v213 offset:6144
	ds_read_b128 v[180:183], v213 offset:8192
	ds_read_b128 v[184:187], v213 offset:10240
	ds_read_b128 v[188:191], v213 offset:12288
	ds_read_b128 v[192:195], v213 offset:14336
	s_waitcnt lgkmcnt(7)
	v_mfma_f32_16x16x32_bf16 v[140:143], v[148:151], v[164:167], v[140:143]
	s_mul_hi_i32 s11, s10, 0x180000
	s_mul_i32 s10, s10, 0x180000
	s_add_u32 s22, s8, s10
	v_mfma_f32_16x16x32_bf16 v[136:139], v[152:155], v[164:167], v[136:139]
	s_addc_u32 s23, s9, s11
	s_lshl_b64 s[10:11], s[20:21], 1
	s_add_u32 s10, s22, s10
	v_mfma_f32_16x16x32_bf16 v[132:135], v[156:159], v[164:167], v[132:135]
	s_addc_u32 s11, s23, s11
	s_movk_i32 s20, 0x1800
	s_add_i32 s28, s28, s78
	v_mfma_f32_16x16x32_bf16 v[128:131], v[160:163], v[164:167], v[128:131]
	s_add_i32 s27, s27, s71
	s_cmpk_gt_i32 s28, 0x5ff
	s_waitcnt lgkmcnt(6)
	v_mfma_f32_16x16x32_bf16 v[124:127], v[148:151], v[168:171], v[124:127]
	v_mfma_f32_16x16x32_bf16 v[120:123], v[152:155], v[168:171], v[120:123]
	v_mfma_f32_16x16x32_bf16 v[116:119], v[156:159], v[168:171], v[116:119]
	v_mfma_f32_16x16x32_bf16 v[104:107], v[160:163], v[168:171], v[104:107]
	s_waitcnt lgkmcnt(5)
	v_mfma_f32_16x16x32_bf16 v[88:91], v[148:151], v[172:175], v[88:91]
	v_mfma_f32_16x16x32_bf16 v[84:87], v[152:155], v[172:175], v[84:87]
	v_mfma_f32_16x16x32_bf16 v[80:83], v[156:159], v[172:175], v[80:83]
	v_mfma_f32_16x16x32_bf16 v[76:79], v[160:163], v[172:175], v[76:79]
	s_waitcnt lgkmcnt(4)
	v_mfma_f32_16x16x32_bf16 v[72:75], v[148:151], v[176:179], v[72:75]
	v_mfma_f32_16x16x32_bf16 v[68:71], v[152:155], v[176:179], v[68:71]
	v_mfma_f32_16x16x32_bf16 v[64:67], v[156:159], v[176:179], v[64:67]
	v_mfma_f32_16x16x32_bf16 v[60:63], v[160:163], v[176:179], v[60:63]
	s_waitcnt lgkmcnt(3)
	v_mfma_f32_16x16x32_bf16 v[44:47], v[148:151], v[180:183], v[44:47]
	v_mfma_f32_16x16x32_bf16 v[40:43], v[152:155], v[180:183], v[40:43]
	v_mfma_f32_16x16x32_bf16 v[36:39], v[156:159], v[180:183], v[36:39]
	v_mfma_f32_16x16x32_bf16 v[32:35], v[160:163], v[180:183], v[32:35]
	s_waitcnt lgkmcnt(2)
; template <int MI, bool SWAP, bool F8 = false>
; __device__ __forceinline__ void gemm_core(const bf16_t* __restrict__ A, int lda, const bf16_t* __restrict__ B, int ldb,
;                                           int K, char* smem, f32x4 (&acc)[MI][4]) {
;     ...
;     for (int kk = 0; kk < 2; ++kk) {
;       const int ch = ((kk * 4 + g) ^ (li & 7)) << 4;
;       bf16x8 xf[MI], wf[4];
; #pragma unroll
;       for (int j = 0; j < 4; ++j) wf[j] = *(const bf16x8*)(smem + wrow + ((j & 1) * 16 + (j >> 1) * 64) * 128 + ch);
; #pragma unroll
;       for (int i = 0; i < MI; ++i) xf[i] = *(const bf16x8*)(smem + xrow + i * 2048 + ch);
; #pragma unroll
;       for (int i = 0; i < MI; ++i)
; #pragma unroll
;         for (int j = 0; j < 4; ++j) {
;           if (SWAP) acc[i][j] = __builtin_amdgcn_mfma_f32_16x16x32_bf16(xf[i], wf[j], acc[i][j], 0, 0, 0);
;           else acc[i][j] = __builtin_amdgcn_mfma_f32_16x16x32_bf16(wf[j], xf[i], acc[i][j], 0, 0, 0);
;         }
;     }
; template <int MI, bool F8 = false>
; __device__ void gemm_tile_bf16(const bf16_t* A, int lda, const bf16_t* B, int ldb, int K, bf16_t* C, int ldc, char* smem) {
;     ...
; #pragma unroll
;   for (int i = 0; i < MI; ++i)
; #pragma unroll
;     for (int j = 0; j < 4; ++j) {
;       u32x2 v;
;       v.x = pk_bf16(acc[i][j][0], acc[i][j][1]);
;       v.y = pk_bf16(acc[i][j][2], acc[i][j][3]);
;       *(u32x2*)(C + (size_t)MROW(i) * ldc + NCOL(j)) = v;
;     }
	v_mfma_f32_16x16x32_bf16 v[28:31], v[148:151], v[184:187], v[28:31]
	v_mfma_f32_16x16x32_bf16 v[24:27], v[152:155], v[184:187], v[24:27]
	v_mfma_f32_16x16x32_bf16 v[20:23], v[156:159], v[184:187], v[20:23]
	v_mfma_f32_16x16x32_bf16 v[52:55], v[160:163], v[184:187], v[52:55]
	s_waitcnt lgkmcnt(1)
	v_mfma_f32_16x16x32_bf16 v[48:51], v[148:151], v[188:191], v[48:51]
	v_mfma_f32_16x16x32_bf16 v[164:167], v[152:155], v[188:191], v[56:59]
	v_mfma_f32_16x16x32_bf16 v[168:171], v[156:159], v[188:191], v[112:115]
	v_mfma_f32_16x16x32_bf16 v[172:175], v[160:163], v[188:191], v[108:111]
	s_waitcnt lgkmcnt(0)
	v_mfma_f32_16x16x32_bf16 v[148:151], v[148:151], v[192:195], v[100:103]
	v_mfma_f32_16x16x32_bf16 v[152:155], v[152:155], v[192:195], v[96:99]
	v_mfma_f32_16x16x32_bf16 v[156:159], v[156:159], v[192:195], v[92:95]
	v_mfma_f32_16x16x32_bf16 v[144:147], v[160:163], v[192:195], v[144:147]
	ds_read_b128 v[160:163], v206 offset:32768
	ds_read_b128 v[176:179], v206 offset:34816
	ds_read_b128 v[180:183], v206 offset:40960
	ds_read_b128 v[184:187], v206 offset:43008
	ds_read_b128 v[56:59], v0
	ds_read_b128 v[92:95], v0 offset:2048
	ds_read_b128 v[96:99], v0 offset:4096
	ds_read_b128 v[188:191], v0 offset:6144
	ds_read_b128 v[192:195], v0 offset:8192
	ds_read_b128 v[196:199], v0 offset:10240
	ds_read_b128 v[200:203], v0 offset:12288
	ds_read_b128 v[204:207], v0 offset:14336
	s_waitcnt lgkmcnt(7)
	v_mfma_f32_16x16x32_bf16 v[140:143], v[160:163], v[56:59], v[140:143]
	v_mfma_f32_16x16x32_bf16 v[136:139], v[176:179], v[56:59], v[136:139]
	v_mfma_f32_16x16x32_bf16 v[132:135], v[180:183], v[56:59], v[132:135]
	s_nop 5
	v_cvt_pk_bf16_f32 v140, v140, v141
	v_cvt_pk_bf16_f32 v141, v142, v143
	v_cvt_pk_bf16_f32 v136, v136, v137
	v_mfma_f32_16x16x32_bf16 v[128:131], v[184:187], v[56:59], v[128:131]
	v_cvt_pk_bf16_f32 v137, v138, v139
	v_cvt_pk_bf16_f32 v132, v132, v133
	v_cvt_pk_bf16_f32 v133, v134, v135
	s_waitcnt lgkmcnt(2)
	v_mfma_f32_16x16x32_bf16 v[56:59], v[180:183], v[196:199], v[20:23]
	s_waitcnt lgkmcnt(0)
	v_mfma_f32_16x16x32_bf16 v[20:23], v[184:187], v[204:207], v[144:147]
	s_nop 0
	v_cvt_pk_bf16_f32 v128, v128, v129
	v_cvt_pk_bf16_f32 v129, v130, v131
	s_nop 2
	v_cvt_pk_bf16_f32 v56, v56, v57
	v_mov_b32_e32 v146, v208
	v_mfma_f32_16x16x32_bf16 v[124:127], v[160:163], v[92:95], v[124:127]
	v_lshrrev_b32_e32 v0, 1, v146
	v_and_b32_e32 v0, 32, v0
	v_lshrrev_b32_e32 v2, 2, v146
	v_and_b32_e32 v147, 0xffffff8f, v146
	v_and_or_b32 v0, v2, 12, v0
	v_mov_b64_e32 v[2:3], s[10:11]
	v_mfma_f32_16x16x32_bf16 v[216:219], v[180:183], v[92:95], v[116:119]
	v_mad_i64_i32 v[144:145], s[10:11], v147, s20, v[2:3]
	v_lshlrev_b32_e32 v0, 1, v0
	v_mfma_f32_16x16x32_bf16 v[116:119], v[184:187], v[92:95], v[104:107]
	v_lshl_add_u64 v[142:143], v[144:145], 0, v[0:1]
	global_store_dwordx2 v[142:143], v[128:129], off offset:160
	v_or_b32_e32 v128, 16, v147
	v_mfma_f32_16x16x32_bf16 v[112:115], v[160:163], v[96:99], v[88:91]
	v_mad_i64_i32 v[128:129], s[10:11], v128, s20, v[2:3]
	v_cvt_pk_bf16_f32 v124, v124, v125
	v_mfma_f32_16x16x32_bf16 v[100:103], v[184:187], v[96:99], v[76:79]
	v_cvt_pk_bf16_f32 v125, v126, v127
	v_lshl_add_u64 v[126:127], v[128:129], 0, v[0:1]
	v_cvt_pk_bf16_f32 v116, v116, v117
	v_cvt_pk_bf16_f32 v117, v118, v119
	global_store_dwordx2 v[126:127], v[116:117], off offset:160
	v_or_b32_e32 v116, 32, v147
	v_mfma_f32_16x16x32_bf16 v[108:111], v[176:179], v[96:99], v[84:87]
	v_mad_i64_i32 v[116:117], s[10:11], v116, s20, v[2:3]
	v_cvt_pk_bf16_f32 v112, v112, v113
	v_mfma_f32_16x16x32_bf16 v[104:107], v[180:183], v[96:99], v[80:83]
	v_cvt_pk_bf16_f32 v113, v114, v115
	v_lshl_add_u64 v[114:115], v[116:117], 0, v[0:1]
	v_cvt_pk_bf16_f32 v100, v100, v101
	v_mfma_f32_16x16x32_bf16 v[96:99], v[160:163], v[188:191], v[72:75]
	v_cvt_pk_bf16_f32 v101, v102, v103
	global_store_dwordx2 v[114:115], v[100:101], off offset:160
	v_or_b32_e32 v100, 48, v147
	v_mfma_f32_16x16x32_bf16 v[84:87], v[184:187], v[188:191], v[60:63]
	v_mad_i64_i32 v[100:101], s[10:11], v100, s20, v[2:3]
	s_nop 2
	v_cvt_pk_bf16_f32 v96, v96, v97
	v_mfma_f32_16x16x32_bf16 v[120:123], v[176:179], v[92:95], v[120:123]
	v_cvt_pk_bf16_f32 v97, v98, v99
	v_lshl_add_u64 v[98:99], v[100:101], 0, v[0:1]
	v_cvt_pk_bf16_f32 v84, v84, v85
	v_mfma_f32_16x16x32_bf16 v[92:95], v[176:179], v[188:191], v[68:71]
	v_cvt_pk_bf16_f32 v85, v86, v87
	global_store_dwordx2 v[98:99], v[84:85], off offset:160
	v_or_b32_e32 v84, 64, v147
	v_mfma_f32_16x16x32_bf16 v[80:83], v[160:163], v[192:195], v[44:47]
	v_mad_i64_i32 v[84:85], s[10:11], v84, s20, v[2:3]
	v_cvt_pk_bf16_f32 v120, v120, v121
	v_mfma_f32_16x16x32_bf16 v[68:71], v[184:187], v[192:195], v[32:35]
	v_cvt_pk_bf16_f32 v121, v122, v123
	s_nop 3
	v_cvt_pk_bf16_f32 v80, v80, v81
	v_cvt_pk_bf16_f32 v81, v82, v83
	v_mfma_f32_16x16x32_bf16 v[88:91], v[180:183], v[188:191], v[64:67]
	v_lshl_add_u64 v[82:83], v[84:85], 0, v[0:1]
	v_cvt_pk_bf16_f32 v68, v68, v69
	v_cvt_pk_bf16_f32 v69, v70, v71
	v_mfma_f32_16x16x32_bf16 v[64:67], v[160:163], v[196:199], v[28:31]
; template <int MI, bool F8 = false>
; __device__ void gemm_tile_bf16(const bf16_t* A, int lda, const bf16_t* B, int ldb, int K, bf16_t* C, int ldc, char* smem) {
;     ...
; #pragma unroll
;   for (int i = 0; i < MI; ++i)
; #pragma unroll
;     for (int j = 0; j < 4; ++j) {
;       u32x2 v;
;       v.x = pk_bf16(acc[i][j][0], acc[i][j][1]);
;       v.y = pk_bf16(acc[i][j][2], acc[i][j][3]);
;       *(u32x2*)(C + (size_t)MROW(i) * ldc + NCOL(j)) = v;
;     }
	global_store_dwordx2 v[82:83], v[68:69], off offset:160
	v_or_b32_e32 v68, 0x50, v147
	v_mad_i64_i32 v[68:69], s[10:11], v68, s20, v[2:3]
	v_mfma_f32_16x16x32_bf16 v[52:55], v[184:187], v[196:199], v[52:55]
	s_nop 3
	v_cvt_pk_bf16_f32 v64, v64, v65
	v_cvt_pk_bf16_f32 v65, v66, v67
	v_lshl_add_u64 v[66:67], v[68:69], 0, v[0:1]
	v_mfma_f32_16x16x32_bf16 v[72:75], v[180:183], v[192:195], v[36:39]
	global_store_dwordx2 v[126:127], v[120:121], off offset:32
	v_cvt_pk_bf16_f32 v52, v52, v53
	v_cvt_pk_bf16_f32 v53, v54, v55
	v_mfma_f32_16x16x32_bf16 v[48:51], v[160:163], v[200:203], v[48:51]
	global_store_dwordx2 v[66:67], v[52:53], off offset:160
	v_or_b32_e32 v52, 0x60, v147
	v_mad_i64_i32 v[52:53], s[10:11], v52, s20, v[2:3]
	v_mfma_f32_16x16x32_bf16 v[36:39], v[184:187], v[200:203], v[172:175]
	s_nop 3
	v_cvt_pk_bf16_f32 v48, v48, v49
	v_cvt_pk_bf16_f32 v49, v50, v51
	v_lshl_add_u64 v[50:51], v[52:53], 0, v[0:1]
	v_mfma_f32_16x16x32_bf16 v[76:79], v[176:179], v[192:195], v[40:43]
	v_cvt_pk_bf16_f32 v120, v216, v217
	v_cvt_pk_bf16_f32 v36, v36, v37
	v_cvt_pk_bf16_f32 v37, v38, v39
	v_mfma_f32_16x16x32_bf16 v[60:63], v[176:179], v[196:199], v[24:27]
	global_store_dwordx2 v[50:51], v[36:37], off offset:160
	v_or_b32_e32 v36, 0x70, v146
	v_mad_i64_i32 v[2:3], s[10:11], v36, s20, v[2:3]
	v_mfma_f32_16x16x32_bf16 v[44:47], v[176:179], v[200:203], v[164:167]
	v_cvt_pk_bf16_f32 v121, v218, v219
	v_cvt_pk_bf16_f32 v108, v108, v109
	v_cvt_pk_bf16_f32 v109, v110, v111
	v_mfma_f32_16x16x32_bf16 v[40:43], v[180:183], v[200:203], v[168:171]
	v_cvt_pk_bf16_f32 v104, v104, v105
	v_cvt_pk_bf16_f32 v105, v106, v107
	v_cvt_pk_bf16_f32 v92, v92, v93
	v_mfma_f32_16x16x32_bf16 v[32:35], v[160:163], v[204:207], v[148:151]
	v_cvt_pk_bf16_f32 v93, v94, v95
	v_cvt_pk_bf16_f32 v88, v88, v89
	v_cvt_pk_bf16_f32 v89, v90, v91
	v_mfma_f32_16x16x32_bf16 v[28:31], v[176:179], v[204:207], v[152:155]
	v_cvt_pk_bf16_f32 v76, v76, v77
	v_cvt_pk_bf16_f32 v77, v78, v79
	v_cvt_pk_bf16_f32 v72, v72, v73
	v_mfma_f32_16x16x32_bf16 v[24:27], v[180:183], v[204:207], v[156:159]
	v_cvt_pk_bf16_f32 v73, v74, v75
	v_cvt_pk_bf16_f32 v60, v60, v61
	v_cvt_pk_bf16_f32 v61, v62, v63
	v_cvt_pk_bf16_f32 v57, v58, v59
	v_cvt_pk_bf16_f32 v44, v44, v45
	v_cvt_pk_bf16_f32 v45, v46, v47
	v_cvt_pk_bf16_f32 v40, v40, v41
	v_cvt_pk_bf16_f32 v41, v42, v43
	v_cvt_pk_bf16_f32 v32, v32, v33
	v_cvt_pk_bf16_f32 v33, v34, v35
	v_lshl_add_u64 v[2:3], v[2:3], 0, v[0:1]
	v_cvt_pk_bf16_f32 v28, v28, v29
	v_cvt_pk_bf16_f32 v29, v30, v31
	v_cvt_pk_bf16_f32 v24, v24, v25
	v_cvt_pk_bf16_f32 v25, v26, v27
	v_cvt_pk_bf16_f32 v20, v20, v21
	v_cvt_pk_bf16_f32 v21, v22, v23
	v_mov_b64_e32 v[4:5], v[140:141]
	v_mov_b64_e32 v[6:7], v[136:137]
	s_nop 1
	v_permlane16_swap_b32_e32 v4, v6
	v_permlane16_swap_b32_e32 v5, v7
	v_lshl_add_u64 v[14:15], v[142:143], 0, v[12:13]
	global_store_dwordx4 v[14:15], v[4:7], off
	global_store_dwordx2 v[142:143], v[132:133], off offset:128
	global_store_dwordx2 v[126:127], v[124:125], off
	global_store_dwordx2 v[126:127], v[120:121], off offset:128
	v_mov_b64_e32 v[8:9], v[112:113]
	v_mov_b64_e32 v[10:11], v[108:109]
	s_nop 1
	v_permlane16_swap_b32_e32 v8, v10
	v_permlane16_swap_b32_e32 v9, v11
	v_lshl_add_u64 v[14:15], v[114:115], 0, v[12:13]
	global_store_dwordx4 v[14:15], v[8:11], off
	global_store_dwordx2 v[114:115], v[104:105], off offset:128
	v_mov_b64_e32 v[4:5], v[96:97]
	v_mov_b64_e32 v[6:7], v[92:93]
	s_nop 1
	v_permlane16_swap_b32_e32 v4, v6
	v_permlane16_swap_b32_e32 v5, v7
	v_lshl_add_u64 v[14:15], v[98:99], 0, v[12:13]
	global_store_dwordx4 v[14:15], v[4:7], off
	global_store_dwordx2 v[98:99], v[88:89], off offset:128
	v_mov_b64_e32 v[8:9], v[80:81]
	v_mov_b64_e32 v[10:11], v[76:77]
	s_nop 1
	v_permlane16_swap_b32_e32 v8, v10
	v_permlane16_swap_b32_e32 v9, v11
	v_lshl_add_u64 v[14:15], v[82:83], 0, v[12:13]
	global_store_dwordx4 v[14:15], v[8:11], off
	global_store_dwordx2 v[82:83], v[72:73], off offset:128
	v_mov_b64_e32 v[4:5], v[64:65]
	v_mov_b64_e32 v[6:7], v[60:61]
	s_nop 1
	v_permlane16_swap_b32_e32 v4, v6
	v_permlane16_swap_b32_e32 v5, v7
	v_lshl_add_u64 v[14:15], v[66:67], 0, v[12:13]
	global_store_dwordx4 v[14:15], v[4:7], off
	global_store_dwordx2 v[66:67], v[56:57], off offset:128
	v_mov_b64_e32 v[8:9], v[48:49]
	v_mov_b64_e32 v[10:11], v[44:45]
	s_nop 1
	v_permlane16_swap_b32_e32 v8, v10
	v_permlane16_swap_b32_e32 v9, v11
	v_lshl_add_u64 v[14:15], v[50:51], 0, v[12:13]
	global_store_dwordx4 v[14:15], v[8:11], off
	global_store_dwordx2 v[50:51], v[40:41], off offset:128
	v_mov_b64_e32 v[4:5], v[32:33]
	v_mov_b64_e32 v[6:7], v[28:29]
	s_nop 1
	v_permlane16_swap_b32_e32 v4, v6
	v_permlane16_swap_b32_e32 v5, v7
	v_lshl_add_u64 v[14:15], v[2:3], 0, v[12:13]
	global_store_dwordx4 v[14:15], v[4:7], off
	v_mov_b64_e32 v[8:9], v[24:25]
	v_mov_b64_e32 v[10:11], v[20:21]
	s_nop 1
	v_permlane16_swap_b32_e32 v8, v10
	v_permlane16_swap_b32_e32 v9, v11
	v_lshl_add_u64 v[14:15], v[2:3], 0, v[12:13]
	global_store_dwordx4 v[14:15], v[8:11], off offset:128
	s_cbranch_scc0 .LBB0_119

; template <int MI, bool SWAP, bool F8 = false>
; __device__ __forceinline__ void gemm_core(const bf16_t* __restrict__ A, int lda, const bf16_t* __restrict__ B, int ldb,
;                                           int K, char* smem, f32x4 (&acc)[MI][4]) {
;     ...
;   for (int kt = 0; kt < nk; ++kt) {
;     __syncthreads();
; #pragma unroll
;     for (int i = 0; i < MI; ++i) *(u32x4*)(smem + woff + i * 4096) = ra[i];
; #pragma unroll
;     for (int i = 0; i < 4; ++i) *(u32x4*)(smem + 32768 + woff + i * 4096) = rb[i];
;     __syncthreads();
;     if (kt + 1 < nk) {
; #pragma unroll
;       for (int i = 0; i < MI; ++i) ra[i] = *(const u32x4*)(ap + (size_t)(32 * i) * lda + (kt + 1) * 64);
; #pragma unroll
;       for (int i = 0; i < 4; ++i) rb[i] = *(const u32x4*)(bp + (size_t)(32 * i) * ldb + (kt + 1) * 64);
;     }
;     if (F8) {
;       const int c0 = (g ^ (li & 7)) << 4, c1 = ((4 + g) ^ (li & 7)) << 4;
;       i32x8 wf8[4];
; #pragma unroll
;       for (int j = 0; j < 4; ++j) {
;         const char* rp = smem + wrow + ((j & 1) * 16 + (j >> 1) * 64) * 128;
;         const u32x4 lo = *(const u32x4*)(rp + c0), hi = *(const u32x4*)(rp + c1);
;         wf8[j] = (i32x8){(int)lo.x, (int)lo.y, (int)lo.z, (int)lo.w, (int)hi.x, (int)hi.y, (int)hi.z, (int)hi.w};
;       }
; #pragma unroll
;       for (int i = 0; i < MI; ++i) {
;         const char* rp = smem + xrow + i * 2048;
;         const u32x4 lo = *(const u32x4*)(rp + c0), hi = *(const u32x4*)(rp + c1);
;         const i32x8 xf8 = {(int)lo.x, (int)lo.y, (int)lo.z, (int)lo.w, (int)hi.x, (int)hi.y, (int)hi.z, (int)hi.w};
; #pragma unroll
;         for (int j = 0; j < 4; ++j)
;           acc[i][j] = __builtin_amdgcn_mfma_scale_f32_16x16x128_f8f6f4(wf8[j], xf8, acc[i][j], 0, 0, 0, 0x77777777, 0, 0x7f7f7f7f);
;       }
;     } else {
; #pragma unroll
;     for (int kk = 0; kk < 2; ++kk) {
;       const int ch = ((kk * 4 + g) ^ (li & 7)) << 4;
;       bf16x8 xf[MI], wf[4];
; #pragma unroll
;       for (int j = 0; j < 4; ++j) wf[j] = *(const bf16x8*)(smem + wrow + ((j & 1) * 16 + (j >> 1) * 64) * 128 + ch);
; #pragma unroll
;       for (int i = 0; i < MI; ++i) xf[i] = *(const bf16x8*)(smem + xrow + i * 2048 + ch);
; #pragma unroll
;       for (int i = 0; i < MI; ++i)
; #pragma unroll
;         for (int j = 0; j < 4; ++j) {
.LBB0_301:
	v_add_u32_e32 v213, v204, v205
	s_barrier
	s_mov_b32 m0, s62
	s_nop 0
	global_load_lds_dwordx4 v252, s[56:57]
	s_add_u32 m0, s62, 0x1000
	s_nop 0
	global_load_lds_dwordx4 v253, s[56:57]
	s_add_u32 s56, s56, 0x20000
	s_addc_u32 s57, s57, 0
	s_add_u32 m0, s62, 0x2000
	s_nop 0
	global_load_lds_dwordx4 v252, s[56:57]
	s_add_u32 m0, s62, 0x3000
	s_nop 0
	global_load_lds_dwordx4 v253, s[56:57]
	s_add_u32 s56, s56, 0x20000
	s_addc_u32 s57, s57, 0
	s_add_u32 m0, s62, 0x4000
	s_nop 0
	global_load_lds_dwordx4 v252, s[56:57]
	s_add_u32 m0, s62, 0x5000
	s_nop 0
	global_load_lds_dwordx4 v253, s[56:57]
	s_add_u32 s56, s56, 0x20000
	s_addc_u32 s57, s57, 0
	s_add_u32 m0, s62, 0x6000
	s_nop 0
	global_load_lds_dwordx4 v252, s[56:57]
	s_add_u32 m0, s62, 0x7000
	s_nop 0
	global_load_lds_dwordx4 v253, s[56:57]
	s_sub_u32 s56, s56, 0x60000
	s_subb_u32 s57, s57, 0
	s_add_u32 m0, s62, 0x8000
	s_nop 0
	global_load_lds_dwordx4 v252, s[58:59]
	s_add_u32 m0, s62, 0x9000
	s_nop 0
	global_load_lds_dwordx4 v253, s[58:59]
	s_add_u32 s58, s58, 0x20000
	s_addc_u32 s59, s59, 0
	s_add_u32 m0, s62, 0xa000
	s_nop 0
	global_load_lds_dwordx4 v252, s[58:59]
	s_add_u32 m0, s62, 0xb000
	s_nop 0
	global_load_lds_dwordx4 v253, s[58:59]
	s_sub_u32 s58, s58, 0x20000
	s_subb_u32 s59, s59, 0
	v_add_u32_e32 v252, 0x80, v252
	v_add_u32_e32 v253, 0x80, v253
	s_waitcnt vmcnt(0)
	s_barrier
	v_add_u32_e32 v0, v203, v205
	ds_read_b128 v[136:139], v213 offset:32768
	ds_read_b128 v[144:147], v213 offset:34816
	ds_read_b128 v[152:155], v0
	ds_read_b128 v[156:159], v0 offset:2048
	ds_read_b128 v[164:167], v213 offset:40960
	ds_read_b128 v[168:171], v213 offset:43008
	s_waitcnt lgkmcnt(3)
	v_mfma_f32_16x16x32_bf16 v[148:151], v[136:139], v[152:155], v[148:151]
	v_add_u32_e32 v215, v204, v206
	v_add_u32_e32 v207, v203, v206
	v_mfma_f32_16x16x32_bf16 v[140:143], v[144:147], v[152:155], v[140:143]
	s_waitcnt lgkmcnt(1)
	v_mfma_f32_16x16x32_bf16 v[132:135], v[164:167], v[152:155], v[132:135]
	s_waitcnt lgkmcnt(0)
	v_mfma_f32_16x16x32_bf16 v[128:131], v[168:171], v[152:155], v[128:131]
	v_mfma_f32_16x16x32_bf16 v[124:127], v[136:139], v[156:159], v[124:127]
	v_mfma_f32_16x16x32_bf16 v[120:123], v[144:147], v[156:159], v[120:123]
	v_mfma_f32_16x16x32_bf16 v[116:119], v[164:167], v[156:159], v[116:119]
	v_mfma_f32_16x16x32_bf16 v[112:115], v[168:171], v[156:159], v[112:115]
	ds_read_b128 v[152:155], v0 offset:4096
	ds_read_b128 v[156:159], v0 offset:6144
	s_waitcnt lgkmcnt(1)
	v_mfma_f32_16x16x32_bf16 v[108:111], v[136:139], v[152:155], v[108:111]
	v_mfma_f32_16x16x32_bf16 v[104:107], v[144:147], v[152:155], v[104:107]
	v_mfma_f32_16x16x32_bf16 v[100:103], v[164:167], v[152:155], v[100:103]
	v_mfma_f32_16x16x32_bf16 v[96:99], v[168:171], v[152:155], v[96:99]
	s_waitcnt lgkmcnt(0)
	v_mfma_f32_16x16x32_bf16 v[92:95], v[136:139], v[156:159], v[92:95]
	v_mfma_f32_16x16x32_bf16 v[88:91], v[144:147], v[156:159], v[88:91]
	v_mfma_f32_16x16x32_bf16 v[84:87], v[164:167], v[156:159], v[84:87]
	v_mfma_f32_16x16x32_bf16 v[80:83], v[168:171], v[156:159], v[80:83]
	ds_read_b128 v[152:155], v0 offset:8192
	ds_read_b128 v[156:159], v0 offset:10240
	s_waitcnt lgkmcnt(1)
	v_mfma_f32_16x16x32_bf16 v[68:71], v[136:139], v[152:155], v[68:71]
	v_mfma_f32_16x16x32_bf16 v[64:67], v[144:147], v[152:155], v[64:67]
	v_mfma_f32_16x16x32_bf16 v[60:63], v[164:167], v[152:155], v[60:63]
	v_mfma_f32_16x16x32_bf16 v[56:59], v[168:171], v[152:155], v[56:59]
	s_waitcnt lgkmcnt(0)
	v_mfma_f32_16x16x32_bf16 v[48:51], v[136:139], v[156:159], v[48:51]
	v_mfma_f32_16x16x32_bf16 v[44:47], v[144:147], v[156:159], v[44:47]
	v_mfma_f32_16x16x32_bf16 v[40:43], v[164:167], v[156:159], v[40:43]
	v_mfma_f32_16x16x32_bf16 v[36:39], v[168:171], v[156:159], v[36:39]
	ds_read_b128 v[152:155], v0 offset:12288
	ds_read_b128 v[156:159], v0 offset:14336
	ds_read_b128 v[172:175], v215 offset:32768
	ds_read_b128 v[180:183], v215 offset:34816
	s_waitcnt lgkmcnt(3)
	v_mfma_f32_16x16x32_bf16 v[28:31], v[136:139], v[152:155], v[28:31]
	v_mfma_f32_16x16x32_bf16 v[24:27], v[144:147], v[152:155], v[24:27]
	v_mfma_f32_16x16x32_bf16 v[76:79], v[164:167], v[152:155], v[76:79]
	v_mfma_f32_16x16x32_bf16 v[72:75], v[168:171], v[152:155], v[72:75]
	s_waitcnt lgkmcnt(2)
	v_mfma_f32_16x16x32_bf16 v[52:55], v[136:139], v[156:159], v[52:55]
	v_mfma_f32_16x16x32_bf16 v[32:35], v[144:147], v[156:159], v[32:35]
	ds_read_b128 v[136:139], v207
	ds_read_b128 v[144:147], v207 offset:2048
	ds_read_b128 v[192:195], v215 offset:40960
	ds_read_b128 v[196:199], v215 offset:43008
	v_mfma_f32_16x16x32_bf16 v[20:23], v[164:167], v[156:159], v[20:23]
	v_mfma_f32_16x16x32_bf16 v[160:163], v[168:171], v[156:159], v[160:163]
	s_waitcnt lgkmcnt(3)
	v_mfma_f32_16x16x32_bf16 v[148:151], v[172:175], v[136:139], v[148:151]
	v_mfma_f32_16x16x32_bf16 v[140:143], v[180:183], v[136:139], v[140:143]
	s_waitcnt lgkmcnt(1)
	v_mfma_f32_16x16x32_bf16 v[132:135], v[192:195], v[136:139], v[132:135]
	s_waitcnt lgkmcnt(0)
	v_mfma_f32_16x16x32_bf16 v[128:131], v[196:199], v[136:139], v[128:131]
	v_mfma_f32_16x16x32_bf16 v[124:127], v[172:175], v[144:147], v[124:127]
	v_mfma_f32_16x16x32_bf16 v[120:123], v[180:183], v[144:147], v[120:123]
	v_mfma_f32_16x16x32_bf16 v[116:119], v[192:195], v[144:147], v[116:119]
	v_mfma_f32_16x16x32_bf16 v[112:115], v[196:199], v[144:147], v[112:115]
	ds_read_b128 v[136:139], v207 offset:4096
	ds_read_b128 v[144:147], v207 offset:6144
	s_waitcnt lgkmcnt(1)
; template <int MI, bool SWAP, bool F8 = false>
; __device__ __forceinline__ void gemm_core(const bf16_t* __restrict__ A, int lda, const bf16_t* __restrict__ B, int ldb,
;                                           int K, char* smem, f32x4 (&acc)[MI][4]) {
;     ...
;   for (int kt = 0; kt < nk; ++kt) {
;     __syncthreads();
; #pragma unroll
;     for (int i = 0; i < MI; ++i) *(u32x4*)(smem + woff + i * 4096) = ra[i];
; #pragma unroll
;     for (int i = 0; i < 4; ++i) *(u32x4*)(smem + 32768 + woff + i * 4096) = rb[i];
;     __syncthreads();
;     if (kt + 1 < nk) {
; #pragma unroll
;       for (int i = 0; i < MI; ++i) ra[i] = *(const u32x4*)(ap + (size_t)(32 * i) * lda + (kt + 1) * 64);
; #pragma unroll
;       for (int i = 0; i < 4; ++i) rb[i] = *(const u32x4*)(bp + (size_t)(32 * i) * ldb + (kt + 1) * 64);
;     }
;     if (F8) {
;       const int c0 = (g ^ (li & 7)) << 4, c1 = ((4 + g) ^ (li & 7)) << 4;
;       i32x8 wf8[4];
; #pragma unroll
;       for (int j = 0; j < 4; ++j) {
;         const char* rp = smem + wrow + ((j & 1) * 16 + (j >> 1) * 64) * 128;
;         const u32x4 lo = *(const u32x4*)(rp + c0), hi = *(const u32x4*)(rp + c1);
;         wf8[j] = (i32x8){(int)lo.x, (int)lo.y, (int)lo.z, (int)lo.w, (int)hi.x, (int)hi.y, (int)hi.z, (int)hi.w};
;       }
; #pragma unroll
;       for (int i = 0; i < MI; ++i) {
;         const char* rp = smem + xrow + i * 2048;
;         const u32x4 lo = *(const u32x4*)(rp + c0), hi = *(const u32x4*)(rp + c1);
;         const i32x8 xf8 = {(int)lo.x, (int)lo.y, (int)lo.z, (int)lo.w, (int)hi.x, (int)hi.y, (int)hi.z, (int)hi.w};
; #pragma unroll
;         for (int j = 0; j < 4; ++j)
;           acc[i][j] = __builtin_amdgcn_mfma_scale_f32_16x16x128_f8f6f4(wf8[j], xf8, acc[i][j], 0, 0, 0, 0x77777777, 0, 0x7f7f7f7f);
;       }
;     } else {
; #pragma unroll
;     for (int kk = 0; kk < 2; ++kk) {
;       const int ch = ((kk * 4 + g) ^ (li & 7)) << 4;
;       bf16x8 xf[MI], wf[4];
; #pragma unroll
;       for (int j = 0; j < 4; ++j) wf[j] = *(const bf16x8*)(smem + wrow + ((j & 1) * 16 + (j >> 1) * 64) * 128 + ch);
; #pragma unroll
;       for (int i = 0; i < MI; ++i) xf[i] = *(const bf16x8*)(smem + xrow + i * 2048 + ch);
; #pragma unroll
;       for (int i = 0; i < MI; ++i)
; #pragma unroll
;         for (int j = 0; j < 4; ++j) {
	v_mfma_f32_16x16x32_bf16 v[108:111], v[172:175], v[136:139], v[108:111]
	ds_read_b128 v[152:155], v207 offset:12288
	ds_read_b128 v[216:219], v207 offset:14336
	v_mfma_f32_16x16x32_bf16 v[104:107], v[180:183], v[136:139], v[104:107]
	v_mfma_f32_16x16x32_bf16 v[100:103], v[192:195], v[136:139], v[100:103]
	v_mfma_f32_16x16x32_bf16 v[96:99], v[196:199], v[136:139], v[96:99]
	ds_read_b128 v[136:139], v207 offset:8192
	s_waitcnt lgkmcnt(3)
	v_mfma_f32_16x16x32_bf16 v[92:95], v[172:175], v[144:147], v[92:95]
	v_mfma_f32_16x16x32_bf16 v[88:91], v[180:183], v[144:147], v[88:91]
	v_mfma_f32_16x16x32_bf16 v[84:87], v[192:195], v[144:147], v[84:87]
	v_mfma_f32_16x16x32_bf16 v[80:83], v[196:199], v[144:147], v[80:83]
	ds_read_b128 v[144:147], v207 offset:10240
	s_waitcnt lgkmcnt(1)
	v_mfma_f32_16x16x32_bf16 v[68:71], v[172:175], v[136:139], v[68:71]
	v_mfma_f32_16x16x32_bf16 v[64:67], v[180:183], v[136:139], v[64:67]
	v_mfma_f32_16x16x32_bf16 v[60:63], v[192:195], v[136:139], v[60:63]
	v_mfma_f32_16x16x32_bf16 v[56:59], v[196:199], v[136:139], v[56:59]
	s_waitcnt lgkmcnt(0)
	v_mfma_f32_16x16x32_bf16 v[48:51], v[172:175], v[144:147], v[48:51]
	v_mfma_f32_16x16x32_bf16 v[44:47], v[180:183], v[144:147], v[44:47]
	v_mfma_f32_16x16x32_bf16 v[40:43], v[192:195], v[144:147], v[40:43]
	v_mfma_f32_16x16x32_bf16 v[36:39], v[196:199], v[144:147], v[36:39]
	v_mfma_f32_16x16x32_bf16 v[28:31], v[172:175], v[152:155], v[28:31]
	v_mfma_f32_16x16x32_bf16 v[24:27], v[180:183], v[152:155], v[24:27]
	v_mfma_f32_16x16x32_bf16 v[76:79], v[192:195], v[152:155], v[76:79]
	v_mfma_f32_16x16x32_bf16 v[72:75], v[196:199], v[152:155], v[72:75]
	v_mfma_f32_16x16x32_bf16 v[52:55], v[172:175], v[216:219], v[52:55]
	v_mfma_f32_16x16x32_bf16 v[32:35], v[180:183], v[216:219], v[32:35]
	v_mfma_f32_16x16x32_bf16 v[20:23], v[192:195], v[216:219], v[20:23]
	v_mfma_f32_16x16x32_bf16 v[160:163], v[196:199], v[216:219], v[160:163]
	s_add_u32 s26, s26, 0x80
	s_addc_u32 s27, s27, 0
	s_cmpk_lg_i32 s26, 0x780
	s_cbranch_scc1 .LBB0_301
	s_barrier
	s_mov_b32 m0, s62
	s_nop 0
	global_load_lds_dwordx4 v252, s[56:57]
	s_add_u32 m0, s62, 0x1000
	s_nop 0
	global_load_lds_dwordx4 v253, s[56:57]
	s_add_u32 s56, s56, 0x20000
	s_addc_u32 s57, s57, 0
	s_add_u32 m0, s62, 0x2000
	s_nop 0
	global_load_lds_dwordx4 v252, s[56:57]
	s_add_u32 m0, s62, 0x3000
	s_nop 0
	global_load_lds_dwordx4 v253, s[56:57]
	s_add_u32 s56, s56, 0x20000
	s_addc_u32 s57, s57, 0
	s_add_u32 m0, s62, 0x4000
	s_nop 0
	global_load_lds_dwordx4 v252, s[56:57]
	s_add_u32 m0, s62, 0x5000
	s_nop 0
	global_load_lds_dwordx4 v253, s[56:57]
	s_add_u32 s56, s56, 0x20000
	s_addc_u32 s57, s57, 0
	s_add_u32 m0, s62, 0x6000
	s_nop 0
	global_load_lds_dwordx4 v252, s[56:57]
	s_add_u32 m0, s62, 0x7000
	s_nop 0
	global_load_lds_dwordx4 v253, s[56:57]
	s_sub_u32 s56, s56, 0x60000
	s_subb_u32 s57, s57, 0
	s_add_u32 m0, s62, 0x8000
	s_nop 0
	global_load_lds_dwordx4 v252, s[58:59]
	s_add_u32 m0, s62, 0x9000
	s_nop 0
	global_load_lds_dwordx4 v253, s[58:59]
	s_add_u32 s58, s58, 0x20000
	s_addc_u32 s59, s59, 0
	s_add_u32 m0, s62, 0xa000
	s_nop 0
	global_load_lds_dwordx4 v252, s[58:59]
	s_add_u32 m0, s62, 0xb000
	s_nop 0
	global_load_lds_dwordx4 v253, s[58:59]
	s_sub_u32 s58, s58, 0x20000
	s_subb_u32 s59, s59, 0
	s_waitcnt vmcnt(0)
	s_barrier
	v_bfe_u32 v12, v208, 4, 1
	v_mul_u32_u24_e32 v12, 24, v12
	v_mov_b32_e32 v13, 0
	ds_read_b128 v[136:139], v213 offset:32768
	ds_read_b128 v[144:147], v213 offset:34816
	ds_read_b128 v[152:155], v0
	ds_read_b128 v[156:159], v0 offset:2048
	ds_read_b128 v[164:167], v213 offset:40960
	ds_read_b128 v[168:171], v213 offset:43008
	s_waitcnt lgkmcnt(3)
	v_mfma_f32_16x16x32_bf16 v[148:151], v[136:139], v[152:155], v[148:151]
	s_cmp_eq_u32 s42, 6
	s_cselect_b64 s[26:27], -1, 0
	s_cmp_lg_u32 s42, 6
	v_mfma_f32_16x16x32_bf16 v[140:143], v[144:147], v[152:155], v[140:143]
	s_cselect_b64 s[30:31], -1, 0
	s_and_b64 vcc, exec, s[26:27]
	s_waitcnt lgkmcnt(1)
	v_mfma_f32_16x16x32_bf16 v[132:135], v[164:167], v[152:155], v[132:135]
	s_waitcnt lgkmcnt(0)
	v_mfma_f32_16x16x32_bf16 v[128:131], v[168:171], v[152:155], v[128:131]
	v_mfma_f32_16x16x32_bf16 v[172:175], v[136:139], v[156:159], v[124:127]
	s_nop 2
	ds_read_b128 v[124:127], v0 offset:4096
	ds_read_b128 v[152:155], v0 offset:6144
	s_waitcnt lgkmcnt(0)
	v_mfma_f32_16x16x32_bf16 v[176:179], v[164:167], v[152:155], v[84:87]
	v_mfma_f32_16x16x32_bf16 v[180:183], v[168:171], v[152:155], v[80:83]
	s_nop 2
	ds_read_b128 v[80:83], v0 offset:8192
	ds_read_b128 v[84:87], v0 offset:10240
	s_waitcnt lgkmcnt(1)
	v_mfma_f32_16x16x32_bf16 v[196:199], v[168:171], v[80:83], v[56:59]
	s_waitcnt lgkmcnt(0)
	v_mfma_f32_16x16x32_bf16 v[200:203], v[136:139], v[84:87], v[48:51]
	s_nop 2
	ds_read_b128 v[48:51], v0 offset:12288
	ds_read_b128 v[56:59], v0 offset:14336
	v_mfma_f32_16x16x32_bf16 v[116:119], v[164:167], v[156:159], v[116:119]
	v_mfma_f32_16x16x32_bf16 v[112:115], v[168:171], v[156:159], v[112:115]
	v_mfma_f32_16x16x32_bf16 v[100:103], v[164:167], v[124:127], v[100:103]
	v_mfma_f32_16x16x32_bf16 v[96:99], v[168:171], v[124:127], v[96:99]
	v_mfma_f32_16x16x32_bf16 v[192:195], v[164:167], v[80:83], v[60:63]
	v_mfma_f32_16x16x32_bf16 v[40:43], v[164:167], v[84:87], v[40:43]
	v_mfma_f32_16x16x32_bf16 v[36:39], v[168:171], v[84:87], v[36:39]
	s_waitcnt lgkmcnt(1)
	v_mfma_f32_16x16x32_bf16 v[28:31], v[136:139], v[48:51], v[28:31]
	v_mfma_f32_16x16x32_bf16 v[24:27], v[144:147], v[48:51], v[24:27]
	v_mfma_f32_16x16x32_bf16 v[76:79], v[164:167], v[48:51], v[76:79]
	v_mfma_f32_16x16x32_bf16 v[216:219], v[168:171], v[48:51], v[72:75]
	s_waitcnt lgkmcnt(0)
; template <int MI, bool SWAP, bool F8 = false>
; __device__ __forceinline__ void gemm_core(const bf16_t* __restrict__ A, int lda, const bf16_t* __restrict__ B, int ldb,
;                                           int K, char* smem, f32x4 (&acc)[MI][4]) {
;     ...
;     for (int kk = 0; kk < 2; ++kk) {
;       const int ch = ((kk * 4 + g) ^ (li & 7)) << 4;
;       bf16x8 xf[MI], wf[4];
; #pragma unroll
;       for (int j = 0; j < 4; ++j) wf[j] = *(const bf16x8*)(smem + wrow + ((j & 1) * 16 + (j >> 1) * 64) * 128 + ch);
; #pragma unroll
;       for (int i = 0; i < MI; ++i) xf[i] = *(const bf16x8*)(smem + xrow + i * 2048 + ch);
; #pragma unroll
;       for (int i = 0; i < MI; ++i)
; #pragma unroll
;         for (int j = 0; j < 4; ++j) {
;           if (SWAP) acc[i][j] = __builtin_amdgcn_mfma_f32_16x16x32_bf16(xf[i], wf[j], acc[i][j], 0, 0, 0);
;           else acc[i][j] = __builtin_amdgcn_mfma_f32_16x16x32_bf16(wf[j], xf[i], acc[i][j], 0, 0, 0);
;         }
;     }
; __device__ void even_in_tile(const P& p, int li_even, int tm, int tn, char* smem) {
;     ...
; #pragma unroll
;     for (int i = 0; i < MI; ++i) {
;       const int s = s0 + MROW(i);
; #pragma unroll
;       for (int jj = 0; jj < 2; ++jj) {
;         const int d = wn * 32 + jj * 16 + g * 4;
;         const f32x4 c = *(const f32x4*)(ctab + s * 64 + d);
;         const f32x4 sn = *(const f32x4*)(stab + s * 64 + d);
; #pragma unroll
;         for (int r = 0; r < 4; ++r) {
;           const float a = acc[i][jj][r], bb = acc[i][jj + 2][r];
;           acc[i][jj][r] = a * c[r] - bb * sn[r];
;           acc[i][jj + 2][r] = bb * c[r] + a * sn[r];
;         }
;       }
;     }
;   }
	v_mfma_f32_16x16x32_bf16 v[224:227], v[144:147], v[56:59], v[32:35]
	v_mfma_f32_16x16x32_bf16 v[20:23], v[164:167], v[56:59], v[20:23]
	ds_read_b128 v[164:167], v215 offset:32768
	v_mfma_f32_16x16x32_bf16 v[160:163], v[168:171], v[56:59], v[160:163]
	ds_read_b128 v[168:171], v215 offset:34816
	ds_read_b128 v[32:35], v207
	ds_read_b128 v[48:51], v207 offset:2048
	ds_read_b128 v[228:231], v215 offset:40960
	ds_read_b128 v[232:235], v215 offset:43008
	v_mfma_f32_16x16x32_bf16 v[120:123], v[144:147], v[156:159], v[120:123]
	v_mov_b32_e32 v215, v208
	v_mfma_f32_16x16x32_bf16 v[108:111], v[136:139], v[124:127], v[108:111]
	v_mfma_f32_16x16x32_bf16 v[104:107], v[144:147], v[124:127], v[104:107]
	v_mfma_f32_16x16x32_bf16 v[92:95], v[136:139], v[152:155], v[92:95]
	v_mfma_f32_16x16x32_bf16 v[156:159], v[144:147], v[152:155], v[88:91]
	v_mfma_f32_16x16x32_bf16 v[184:187], v[136:139], v[80:83], v[68:71]
	v_mfma_f32_16x16x32_bf16 v[188:191], v[144:147], v[80:83], v[64:67]
	v_mfma_f32_16x16x32_bf16 v[44:47], v[144:147], v[84:87], v[44:47]
	v_mfma_f32_16x16x32_bf16 v[220:223], v[136:139], v[56:59], v[52:55]
	s_waitcnt lgkmcnt(3)
	v_mfma_f32_16x16x32_bf16 v[124:127], v[164:167], v[32:35], v[148:151]
	v_mfma_f32_16x16x32_bf16 v[150:153], v[168:171], v[32:35], v[140:143]
	s_waitcnt lgkmcnt(1)
	v_mfma_f32_16x16x32_bf16 v[88:91], v[228:231], v[32:35], v[132:135]
	s_waitcnt lgkmcnt(0)
	v_mfma_f32_16x16x32_bf16 v[84:87], v[232:235], v[32:35], v[128:131]
	v_mfma_f32_16x16x32_bf16 v[134:137], v[164:167], v[48:51], v[172:175]
	v_mfma_f32_16x16x32_bf16 v[138:141], v[168:171], v[48:51], v[120:123]
	v_mfma_f32_16x16x32_bf16 v[80:83], v[228:231], v[48:51], v[116:119]
	v_mfma_f32_16x16x32_bf16 v[72:75], v[232:235], v[48:51], v[112:115]
	ds_read_b128 v[32:35], v207 offset:4096
	ds_read_b128 v[48:51], v207 offset:6144
	s_waitcnt lgkmcnt(1)
	v_mfma_f32_16x16x32_bf16 v[142:145], v[164:167], v[32:35], v[108:111]
	v_mfma_f32_16x16x32_bf16 v[146:149], v[168:171], v[32:35], v[104:107]
	v_mfma_f32_16x16x32_bf16 v[68:71], v[228:231], v[32:35], v[100:103]
	v_mfma_f32_16x16x32_bf16 v[64:67], v[232:235], v[32:35], v[96:99]
	s_waitcnt lgkmcnt(0)
	v_mfma_f32_16x16x32_bf16 v[128:131], v[164:167], v[48:51], v[92:95]
	ds_read_b128 v[32:35], v207 offset:8192
	s_nop 1
	ds_read_b128 v[92:95], v207 offset:10240
	v_mfma_f32_16x16x32_bf16 v[120:123], v[168:171], v[48:51], v[156:159]
	v_mfma_f32_16x16x32_bf16 v[60:63], v[228:231], v[48:51], v[176:179]
	v_mfma_f32_16x16x32_bf16 v[56:59], v[232:235], v[48:51], v[180:183]
	s_waitcnt lgkmcnt(1)
	v_mfma_f32_16x16x32_bf16 v[112:115], v[164:167], v[32:35], v[184:187]
	v_mfma_f32_16x16x32_bf16 v[108:111], v[168:171], v[32:35], v[188:191]
	v_mfma_f32_16x16x32_bf16 v[52:55], v[228:231], v[32:35], v[192:195]
	v_mfma_f32_16x16x32_bf16 v[48:51], v[232:235], v[32:35], v[196:199]
	ds_read_b128 v[32:35], v207 offset:12288
	ds_read_b128 v[116:119], v207 offset:14336
	s_waitcnt lgkmcnt(2)
	v_mfma_f32_16x16x32_bf16 v[104:107], v[164:167], v[92:95], v[200:203]
	v_and_b32_e32 v213, 15, v215
	v_mfma_f32_16x16x32_bf16 v[100:103], v[168:171], v[92:95], v[44:47]
	v_mfma_f32_16x16x32_bf16 v[44:47], v[228:231], v[92:95], v[40:43]
	v_mfma_f32_16x16x32_bf16 v[40:43], v[232:235], v[92:95], v[36:39]
	s_waitcnt lgkmcnt(1)
	v_mfma_f32_16x16x32_bf16 v[96:99], v[164:167], v[32:35], v[28:31]
	v_mfma_f32_16x16x32_bf16 v[92:95], v[168:171], v[32:35], v[24:27]
	v_mfma_f32_16x16x32_bf16 v[36:39], v[228:231], v[32:35], v[76:79]
	v_mfma_f32_16x16x32_bf16 v[32:35], v[232:235], v[32:35], v[216:219]
	s_waitcnt lgkmcnt(0)
	v_mfma_f32_16x16x32_bf16 v[76:79], v[164:167], v[116:119], v[220:223]
	s_nop 0
	v_bfe_u32 v218, v215, 6, 1
	v_bfe_u32 v219, v215, 4, 2
	v_mfma_f32_16x16x32_bf16 v[28:31], v[168:171], v[116:119], v[224:227]
	v_mfma_f32_16x16x32_bf16 v[24:27], v[228:231], v[116:119], v[20:23]
	v_mfma_f32_16x16x32_bf16 v[20:23], v[232:235], v[116:119], v[160:163]
	s_cbranch_vccnz .LBB0_315
	v_and_b32_e32 v0, 0x3ffff80, v215
	v_add_u32_e32 v0, s41, v0
	s_add_u32 s34, s45, 0x4000
	v_or_b32_e32 v0, v0, v213
	s_addc_u32 s35, s48, 0
	v_lshlrev_b32_e32 v2, 6, v0
	s_add_u32 s36, s45, 0x104000
	v_ashrrev_i32_e32 v3, 31, v2
	s_addc_u32 s37, s48, 0
	v_lshlrev_b64 v[116:117], 2, v[2:3]
	v_lshlrev_b32_e32 v0, 4, v219
	v_lshl_add_u64 v[118:119], s[34:35], 0, v[116:117]
	v_lshl_add_u64 v[116:117], s[36:37], 0, v[116:117]
	v_lshl_or_b32 v0, v218, 7, v0
	v_lshl_add_u64 v[132:133], v[118:119], 0, v[0:1]
	v_lshl_add_u64 v[162:163], v[116:117], 0, v[0:1]
	global_load_dwordx4 v[154:157], v[132:133], off
	global_load_dwordx4 v[158:161], v[162:163], off
	s_waitcnt vmcnt(0)
	v_pk_mul_f32 v[116:117], v[88:89], v[158:159]
	v_pk_mul_f32 v[118:119], v[124:125], v[158:159]
	v_pk_fma_f32 v[116:117], v[124:125], v[154:155], v[116:117] neg_lo:[0,0,1] neg_hi:[0,0,1]
	v_pk_fma_f32 v[88:89], v[88:89], v[154:155], v[118:119]
	v_mul_f32_e32 v118, v126, v156
	v_mul_f32_e32 v124, v90, v160
	v_mul_f32_e32 v154, v90, v156
	v_mul_f32_e32 v156, v126, v160
	v_mov_b32_e32 v90, v127
	v_mov_b32_e32 v160, v157
	v_mov_b32_e32 v126, v91
	v_pk_mul_f32 v[158:159], v[90:91], v[160:161]
	v_pk_mul_f32 v[90:91], v[126:127], v[160:161]
	v_mov_b32_e32 v119, v158
	v_mov_b32_e32 v155, v90
	v_mov_b32_e32 v157, v91
	v_mov_b32_e32 v125, v159
	v_pk_add_f32 v[90:91], v[154:155], v[156:157]
	global_load_dwordx4 v[154:157], v[132:133], off offset:64
	global_load_dwordx4 v[158:161], v[162:163], off offset:64
	v_pk_add_f32 v[118:119], v[118:119], v[124:125] neg_lo:[0,1] neg_hi:[0,1]
	s_waitcnt vmcnt(0)
; __device__ void even_in_tile(const P& p, int li_even, int tm, int tn, char* smem) {
;     ...
; #pragma unroll
;     for (int i = 0; i < MI; ++i) {
;       const int s = s0 + MROW(i);
; #pragma unroll
;       for (int jj = 0; jj < 2; ++jj) {
;         const int d = wn * 32 + jj * 16 + g * 4;
;         const f32x4 c = *(const f32x4*)(ctab + s * 64 + d);
;         const f32x4 sn = *(const f32x4*)(stab + s * 64 + d);
; #pragma unroll
;         for (int r = 0; r < 4; ++r) {
;           const float a = acc[i][jj][r], bb = acc[i][jj + 2][r];
;           acc[i][jj][r] = a * c[r] - bb * sn[r];
;           acc[i][jj + 2][r] = bb * c[r] + a * sn[r];
;         }
;       }
;     }
;   }
	v_pk_mul_f32 v[124:125], v[84:85], v[158:159]
	v_pk_mul_f32 v[126:127], v[150:151], v[158:159]
	v_pk_fma_f32 v[124:125], v[150:151], v[154:155], v[124:125] neg_lo:[0,0,1] neg_hi:[0,0,1]
	v_pk_fma_f32 v[84:85], v[84:85], v[154:155], v[126:127]
	v_mul_f32_e32 v132, v86, v160
	v_mul_f32_e32 v150, v86, v156
	v_mul_f32_e32 v154, v152, v160
	v_mov_b32_e32 v86, v153
	v_mov_b32_e32 v160, v157
	v_mul_f32_e32 v126, v152, v156
	v_pk_mul_f32 v[156:157], v[86:87], v[160:161]
	v_mov_b32_e32 v152, v87
	v_mov_b32_e32 v127, v156
	v_mov_b32_e32 v133, v157
	v_pk_add_f32 v[126:127], v[126:127], v[132:133] neg_lo:[0,1] neg_hi:[0,1]
	v_or_b32_e32 v132, 0x400, v2
	v_pk_mul_f32 v[86:87], v[152:153], v[160:161]
	v_ashrrev_i32_e32 v133, 31, v132
	v_mov_b32_e32 v151, v86
	v_mov_b32_e32 v155, v87
	v_lshlrev_b64 v[132:133], 2, v[132:133]
	v_pk_add_f32 v[86:87], v[150:151], v[154:155]
	v_lshl_add_u64 v[150:151], s[34:35], 0, v[132:133]
	v_lshl_add_u64 v[132:133], s[36:37], 0, v[132:133]
	v_lshl_add_u64 v[158:159], v[150:151], 0, v[0:1]
	v_lshl_add_u64 v[160:161], v[132:133], 0, v[0:1]
	global_load_dwordx4 v[150:153], v[158:159], off
	global_load_dwordx4 v[154:157], v[160:161], off
	s_waitcnt vmcnt(0)
	v_pk_mul_f32 v[132:133], v[80:81], v[154:155]
	s_nop 0
	v_pk_fma_f32 v[132:133], v[134:135], v[150:151], v[132:133] neg_lo:[0,0,1] neg_hi:[0,0,1]
	v_pk_mul_f32 v[134:135], v[134:135], v[154:155]
	v_mul_f32_e32 v154, v136, v156
	v_pk_fma_f32 v[80:81], v[80:81], v[150:151], v[134:135]
	v_mul_f32_e32 v134, v136, v152
	v_mul_f32_e32 v150, v82, v156
	v_mul_f32_e32 v152, v82, v152
	v_mov_b32_e32 v82, v137
	v_mov_b32_e32 v156, v153
	v_mov_b32_e32 v136, v83
	v_pk_mul_f32 v[162:163], v[82:83], v[156:157]
	v_pk_mul_f32 v[82:83], v[136:137], v[156:157]
	v_mov_b32_e32 v135, v162
	v_mov_b32_e32 v151, v163
	v_mov_b32_e32 v153, v82
	v_mov_b32_e32 v155, v83
	v_pk_add_f32 v[134:135], v[134:135], v[150:151] neg_lo:[0,1] neg_hi:[0,1]
	v_pk_add_f32 v[82:83], v[152:153], v[154:155]
	global_load_dwordx4 v[150:153], v[158:159], off offset:64
	global_load_dwordx4 v[154:157], v[160:161], off offset:64
	s_waitcnt vmcnt(0)
	v_pk_mul_f32 v[136:137], v[72:73], v[154:155]
	s_nop 0
	v_pk_fma_f32 v[136:137], v[138:139], v[150:151], v[136:137] neg_lo:[0,0,1] neg_hi:[0,0,1]
	v_pk_mul_f32 v[138:139], v[138:139], v[154:155]
	v_mul_f32_e32 v154, v140, v156
	v_pk_fma_f32 v[72:73], v[72:73], v[150:151], v[138:139]
	v_mul_f32_e32 v138, v140, v152
	v_mul_f32_e32 v150, v74, v156
	v_mul_f32_e32 v152, v74, v152
	v_mov_b32_e32 v74, v141
	v_mov_b32_e32 v156, v153
	v_mov_b32_e32 v140, v75
	v_pk_mul_f32 v[158:159], v[74:75], v[156:157]
	v_pk_mul_f32 v[74:75], v[140:141], v[156:157]
	v_or_b32_e32 v140, 0x800, v2
	v_ashrrev_i32_e32 v141, 31, v140
	v_mov_b32_e32 v139, v158
	v_mov_b32_e32 v151, v159
	v_lshlrev_b64 v[140:141], 2, v[140:141]
	v_pk_add_f32 v[138:139], v[138:139], v[150:151] neg_lo:[0,1] neg_hi:[0,1]
	v_lshl_add_u64 v[150:151], s[34:35], 0, v[140:141]
	v_lshl_add_u64 v[140:141], s[36:37], 0, v[140:141]
	v_mov_b32_e32 v153, v74
	v_mov_b32_e32 v155, v75
	v_lshl_add_u64 v[158:159], v[150:151], 0, v[0:1]
	v_lshl_add_u64 v[160:161], v[140:141], 0, v[0:1]
	v_pk_add_f32 v[74:75], v[152:153], v[154:155]
	global_load_dwordx4 v[150:153], v[158:159], off
	global_load_dwordx4 v[154:157], v[160:161], off
	s_waitcnt vmcnt(0)
	v_pk_mul_f32 v[140:141], v[68:69], v[154:155]
	s_nop 0
	v_pk_fma_f32 v[140:141], v[142:143], v[150:151], v[140:141] neg_lo:[0,0,1] neg_hi:[0,0,1]
	v_pk_mul_f32 v[142:143], v[142:143], v[154:155]
	v_mul_f32_e32 v154, v144, v156
	v_pk_fma_f32 v[68:69], v[68:69], v[150:151], v[142:143]
	v_mul_f32_e32 v142, v144, v152
	v_mul_f32_e32 v150, v70, v156
	v_mul_f32_e32 v152, v70, v152
	v_mov_b32_e32 v70, v145
	v_mov_b32_e32 v156, v153
	v_mov_b32_e32 v144, v71
	v_pk_mul_f32 v[162:163], v[70:71], v[156:157]
	v_pk_mul_f32 v[70:71], v[144:145], v[156:157]
	v_mov_b32_e32 v143, v162
	v_mov_b32_e32 v151, v163
	v_mov_b32_e32 v153, v70
	v_mov_b32_e32 v155, v71
	v_pk_add_f32 v[142:143], v[142:143], v[150:151] neg_lo:[0,1] neg_hi:[0,1]
	v_pk_add_f32 v[70:71], v[152:153], v[154:155]
	global_load_dwordx4 v[150:153], v[158:159], off offset:64
	global_load_dwordx4 v[154:157], v[160:161], off offset:64
	s_waitcnt vmcnt(0)
	v_pk_mul_f32 v[144:145], v[64:65], v[154:155]
	s_nop 0
	v_pk_fma_f32 v[144:145], v[146:147], v[150:151], v[144:145] neg_lo:[0,0,1] neg_hi:[0,0,1]
	v_pk_mul_f32 v[146:147], v[146:147], v[154:155]
	v_mul_f32_e32 v154, v148, v156
	v_pk_fma_f32 v[64:65], v[64:65], v[150:151], v[146:147]
	v_mul_f32_e32 v146, v148, v152
	v_mul_f32_e32 v150, v66, v156
	v_mul_f32_e32 v152, v66, v152
	v_mov_b32_e32 v66, v149
	v_mov_b32_e32 v156, v153
	v_mov_b32_e32 v148, v67
	v_pk_mul_f32 v[158:159], v[66:67], v[156:157]
	v_pk_mul_f32 v[66:67], v[148:149], v[156:157]
	v_or_b32_e32 v148, 0xc00, v2
	v_ashrrev_i32_e32 v149, 31, v148
	v_mov_b32_e32 v147, v158
	v_mov_b32_e32 v151, v159
	v_lshlrev_b64 v[148:149], 2, v[148:149]
	v_pk_add_f32 v[146:147], v[146:147], v[150:151] neg_lo:[0,1] neg_hi:[0,1]
	v_lshl_add_u64 v[150:151], s[34:35], 0, v[148:149]
	v_lshl_add_u64 v[148:149], s[36:37], 0, v[148:149]
	v_mov_b32_e32 v153, v66
	v_mov_b32_e32 v155, v67
	v_lshl_add_u64 v[158:159], v[150:151], 0, v[0:1]
	v_lshl_add_u64 v[160:161], v[148:149], 0, v[0:1]
	v_pk_add_f32 v[66:67], v[152:153], v[154:155]
	global_load_dwordx4 v[150:153], v[158:159], off
	global_load_dwordx4 v[154:157], v[160:161], off
	s_waitcnt vmcnt(0)
; __device__ void even_in_tile(const P& p, int li_even, int tm, int tn, char* smem) {
;     ...
; #pragma unroll
;     for (int i = 0; i < MI; ++i) {
;       const int s = s0 + MROW(i);
; #pragma unroll
;       for (int jj = 0; jj < 2; ++jj) {
;         const int d = wn * 32 + jj * 16 + g * 4;
;         const f32x4 c = *(const f32x4*)(ctab + s * 64 + d);
;         const f32x4 sn = *(const f32x4*)(stab + s * 64 + d);
; #pragma unroll
;         for (int r = 0; r < 4; ++r) {
;           const float a = acc[i][jj][r], bb = acc[i][jj + 2][r];
;           acc[i][jj][r] = a * c[r] - bb * sn[r];
;           acc[i][jj + 2][r] = bb * c[r] + a * sn[r];
;         }
;       }
;     }
;   }
	v_pk_mul_f32 v[148:149], v[60:61], v[154:155]
	s_nop 0
	v_pk_fma_f32 v[148:149], v[128:129], v[150:151], v[148:149] neg_lo:[0,0,1] neg_hi:[0,0,1]
	v_pk_mul_f32 v[128:129], v[128:129], v[154:155]
	v_mul_f32_e32 v154, v130, v156
	v_pk_fma_f32 v[60:61], v[60:61], v[150:151], v[128:129]
	v_mul_f32_e32 v128, v130, v152
	v_mul_f32_e32 v150, v62, v156
	v_mul_f32_e32 v152, v62, v152
	v_mov_b32_e32 v62, v131
	v_mov_b32_e32 v156, v153
	v_mov_b32_e32 v130, v63
	v_pk_mul_f32 v[162:163], v[62:63], v[156:157]
	v_pk_mul_f32 v[62:63], v[130:131], v[156:157]
	v_mov_b32_e32 v129, v162
	v_mov_b32_e32 v153, v62
	v_mov_b32_e32 v155, v63
	v_pk_add_f32 v[62:63], v[152:153], v[154:155]
	global_load_dwordx4 v[152:155], v[158:159], off offset:64
	s_nop 0
	global_load_dwordx4 v[156:159], v[160:161], off offset:64
	v_mov_b32_e32 v151, v163
	v_pk_add_f32 v[150:151], v[128:129], v[150:151] neg_lo:[0,1] neg_hi:[0,1]
	s_waitcnt vmcnt(0)
	v_pk_mul_f32 v[128:129], v[56:57], v[156:157]
	s_nop 0
	v_pk_fma_f32 v[128:129], v[120:121], v[152:153], v[128:129] neg_lo:[0,0,1] neg_hi:[0,0,1]
	v_pk_mul_f32 v[120:121], v[120:121], v[156:157]
	v_mul_f32_e32 v130, v58, v158
	v_pk_fma_f32 v[56:57], v[56:57], v[152:153], v[120:121]
	v_mul_f32_e32 v120, v122, v154
	v_mul_f32_e32 v152, v58, v154
	v_mul_f32_e32 v154, v122, v158
	v_mov_b32_e32 v58, v123
	v_mov_b32_e32 v158, v155
	v_pk_mul_f32 v[156:157], v[58:59], v[158:159]
	v_mov_b32_e32 v122, v59
	v_mov_b32_e32 v121, v156
	v_mov_b32_e32 v131, v157
	v_pk_add_f32 v[130:131], v[120:121], v[130:131] neg_lo:[0,1] neg_hi:[0,1]
	v_or_b32_e32 v120, 0x1000, v2
	v_ashrrev_i32_e32 v121, 31, v120
	v_lshlrev_b64 v[120:121], 2, v[120:121]
	v_pk_mul_f32 v[58:59], v[122:123], v[158:159]
	v_lshl_add_u64 v[122:123], s[34:35], 0, v[120:121]
	v_lshl_add_u64 v[120:121], s[36:37], 0, v[120:121]
	v_mov_b32_e32 v153, v58
	v_mov_b32_e32 v155, v59
	v_lshl_add_u64 v[160:161], v[122:123], 0, v[0:1]
	v_lshl_add_u64 v[162:163], v[120:121], 0, v[0:1]
	v_pk_add_f32 v[58:59], v[152:153], v[154:155]
	global_load_dwordx4 v[152:155], v[160:161], off
	global_load_dwordx4 v[156:159], v[162:163], off
	s_waitcnt vmcnt(0)
	v_pk_mul_f32 v[120:121], v[52:53], v[156:157]
	s_nop 0
	v_pk_fma_f32 v[120:121], v[112:113], v[152:153], v[120:121] neg_lo:[0,0,1] neg_hi:[0,0,1]
	v_pk_mul_f32 v[112:113], v[112:113], v[156:157]
	v_mul_f32_e32 v122, v54, v158
	v_pk_fma_f32 v[52:53], v[52:53], v[152:153], v[112:113]
	v_mul_f32_e32 v112, v114, v154
	v_mul_f32_e32 v152, v54, v154
	v_mul_f32_e32 v154, v114, v158
	v_mov_b32_e32 v54, v115
	v_mov_b32_e32 v158, v155
	v_mov_b32_e32 v114, v55
	v_pk_mul_f32 v[156:157], v[54:55], v[158:159]
	v_pk_mul_f32 v[54:55], v[114:115], v[158:159]
	v_mov_b32_e32 v113, v156
	v_mov_b32_e32 v153, v54
	v_mov_b32_e32 v155, v55
	v_mov_b32_e32 v123, v157
	v_pk_add_f32 v[54:55], v[152:153], v[154:155]
	global_load_dwordx4 v[152:155], v[160:161], off offset:64
	global_load_dwordx4 v[156:159], v[162:163], off offset:64
	v_pk_add_f32 v[122:123], v[112:113], v[122:123] neg_lo:[0,1] neg_hi:[0,1]
	s_waitcnt vmcnt(0)
	v_pk_mul_f32 v[112:113], v[48:49], v[156:157]
	s_nop 0
	v_pk_fma_f32 v[112:113], v[108:109], v[152:153], v[112:113] neg_lo:[0,0,1] neg_hi:[0,0,1]
	v_pk_mul_f32 v[108:109], v[108:109], v[156:157]
	v_mul_f32_e32 v114, v50, v158
	v_pk_fma_f32 v[48:49], v[48:49], v[152:153], v[108:109]
	v_mul_f32_e32 v108, v110, v154
	v_mul_f32_e32 v152, v50, v154
	v_mul_f32_e32 v154, v110, v158
	v_mov_b32_e32 v50, v111
	v_mov_b32_e32 v158, v155
	v_pk_mul_f32 v[156:157], v[50:51], v[158:159]
	v_mov_b32_e32 v110, v51
	v_mov_b32_e32 v109, v156
	v_mov_b32_e32 v115, v157
	v_pk_add_f32 v[114:115], v[108:109], v[114:115] neg_lo:[0,1] neg_hi:[0,1]
	v_or_b32_e32 v108, 0x1400, v2
	v_ashrrev_i32_e32 v109, 31, v108
	v_lshlrev_b64 v[108:109], 2, v[108:109]
	v_pk_mul_f32 v[50:51], v[110:111], v[158:159]
	v_lshl_add_u64 v[110:111], s[34:35], 0, v[108:109]
	v_lshl_add_u64 v[108:109], s[36:37], 0, v[108:109]
	v_mov_b32_e32 v153, v50
	v_mov_b32_e32 v155, v51
	v_lshl_add_u64 v[160:161], v[110:111], 0, v[0:1]
	v_lshl_add_u64 v[162:163], v[108:109], 0, v[0:1]
	v_pk_add_f32 v[50:51], v[152:153], v[154:155]
	global_load_dwordx4 v[152:155], v[160:161], off
	global_load_dwordx4 v[156:159], v[162:163], off
	s_waitcnt vmcnt(0)
	v_pk_mul_f32 v[108:109], v[44:45], v[156:157]
	s_nop 0
	v_pk_fma_f32 v[108:109], v[104:105], v[152:153], v[108:109] neg_lo:[0,0,1] neg_hi:[0,0,1]
	v_pk_mul_f32 v[104:105], v[104:105], v[156:157]
	v_mul_f32_e32 v110, v46, v158
	v_pk_fma_f32 v[44:45], v[44:45], v[152:153], v[104:105]
	v_mul_f32_e32 v104, v106, v154
	v_mul_f32_e32 v152, v46, v154
	v_mul_f32_e32 v154, v106, v158
	v_mov_b32_e32 v46, v107
	v_mov_b32_e32 v158, v155
	v_mov_b32_e32 v106, v47
	v_pk_mul_f32 v[156:157], v[46:47], v[158:159]
	v_pk_mul_f32 v[46:47], v[106:107], v[158:159]
	v_mov_b32_e32 v105, v156
	v_mov_b32_e32 v153, v46
	v_mov_b32_e32 v155, v47
	v_mov_b32_e32 v111, v157
	v_pk_add_f32 v[46:47], v[152:153], v[154:155]
	global_load_dwordx4 v[152:155], v[160:161], off offset:64
	global_load_dwordx4 v[156:159], v[162:163], off offset:64
	v_pk_add_f32 v[110:111], v[104:105], v[110:111] neg_lo:[0,1] neg_hi:[0,1]
	s_waitcnt vmcnt(0)
; __device__ void even_in_tile(const P& p, int li_even, int tm, int tn, char* smem) {
;     ...
; #pragma unroll
;     for (int i = 0; i < MI; ++i) {
;       const int s = s0 + MROW(i);
; #pragma unroll
;       for (int jj = 0; jj < 2; ++jj) {
;         const int d = wn * 32 + jj * 16 + g * 4;
;         const f32x4 c = *(const f32x4*)(ctab + s * 64 + d);
;         const f32x4 sn = *(const f32x4*)(stab + s * 64 + d);
; #pragma unroll
;         for (int r = 0; r < 4; ++r) {
;           const float a = acc[i][jj][r], bb = acc[i][jj + 2][r];
;           acc[i][jj][r] = a * c[r] - bb * sn[r];
;           acc[i][jj + 2][r] = bb * c[r] + a * sn[r];
;         }
;       }
;     }
;   }
;   if (seg == 1) {
	v_pk_mul_f32 v[104:105], v[40:41], v[156:157]
	s_nop 0
	v_pk_fma_f32 v[104:105], v[100:101], v[152:153], v[104:105] neg_lo:[0,0,1] neg_hi:[0,0,1]
	v_pk_mul_f32 v[100:101], v[100:101], v[156:157]
	v_mul_f32_e32 v106, v42, v158
	v_pk_fma_f32 v[40:41], v[40:41], v[152:153], v[100:101]
	v_mul_f32_e32 v100, v102, v154
	v_mul_f32_e32 v152, v42, v154
	v_mul_f32_e32 v154, v102, v158
	v_mov_b32_e32 v42, v103
	v_mov_b32_e32 v158, v155
	v_pk_mul_f32 v[156:157], v[42:43], v[158:159]
	v_mov_b32_e32 v102, v43
	v_mov_b32_e32 v101, v156
	v_mov_b32_e32 v107, v157
	v_pk_add_f32 v[106:107], v[100:101], v[106:107] neg_lo:[0,1] neg_hi:[0,1]
	v_or_b32_e32 v100, 0x1800, v2
	v_ashrrev_i32_e32 v101, 31, v100
	v_lshlrev_b64 v[100:101], 2, v[100:101]
	v_pk_mul_f32 v[42:43], v[102:103], v[158:159]
	v_lshl_add_u64 v[102:103], s[34:35], 0, v[100:101]
	v_lshl_add_u64 v[100:101], s[36:37], 0, v[100:101]
	v_mov_b32_e32 v153, v42
	v_mov_b32_e32 v155, v43
	v_lshl_add_u64 v[160:161], v[102:103], 0, v[0:1]
	v_lshl_add_u64 v[162:163], v[100:101], 0, v[0:1]
	v_pk_add_f32 v[42:43], v[152:153], v[154:155]
	global_load_dwordx4 v[152:155], v[160:161], off
	global_load_dwordx4 v[156:159], v[162:163], off
	v_or_b32_e32 v2, 0x1c00, v2
	v_ashrrev_i32_e32 v3, 31, v2
	v_lshlrev_b64 v[2:3], 2, v[2:3]
	s_waitcnt vmcnt(0)
	v_pk_mul_f32 v[100:101], v[36:37], v[156:157]
	s_nop 0
	v_pk_fma_f32 v[100:101], v[96:97], v[152:153], v[100:101] neg_lo:[0,0,1] neg_hi:[0,0,1]
	v_pk_mul_f32 v[96:97], v[96:97], v[156:157]
	v_mul_f32_e32 v102, v38, v158
	v_pk_fma_f32 v[36:37], v[36:37], v[152:153], v[96:97]
	v_mul_f32_e32 v96, v98, v154
	v_mul_f32_e32 v152, v38, v154
	v_mul_f32_e32 v154, v98, v158
	v_mov_b32_e32 v38, v99
	v_mov_b32_e32 v158, v155
	v_mov_b32_e32 v98, v39
	v_pk_mul_f32 v[156:157], v[38:39], v[158:159]
	v_pk_mul_f32 v[38:39], v[98:99], v[158:159]
	v_mov_b32_e32 v97, v156
	v_mov_b32_e32 v153, v38
	v_mov_b32_e32 v155, v39
	v_mov_b32_e32 v103, v157
	v_pk_add_f32 v[38:39], v[152:153], v[154:155]
	global_load_dwordx4 v[152:155], v[160:161], off offset:64
	global_load_dwordx4 v[156:159], v[162:163], off offset:64
	v_pk_add_f32 v[102:103], v[96:97], v[102:103] neg_lo:[0,1] neg_hi:[0,1]
	s_waitcnt vmcnt(0)
	v_pk_mul_f32 v[96:97], v[32:33], v[156:157]
	s_nop 0
	v_pk_fma_f32 v[96:97], v[92:93], v[152:153], v[96:97] neg_lo:[0,0,1] neg_hi:[0,0,1]
	v_pk_mul_f32 v[92:93], v[92:93], v[156:157]
	v_mul_f32_e32 v98, v34, v158
	v_pk_fma_f32 v[32:33], v[32:33], v[152:153], v[92:93]
	v_mul_f32_e32 v92, v94, v154
	v_mul_f32_e32 v152, v34, v154
	v_mul_f32_e32 v154, v94, v158
	v_mov_b32_e32 v34, v95
	v_mov_b32_e32 v158, v155
	v_pk_mul_f32 v[156:157], v[34:35], v[158:159]
	v_mov_b32_e32 v94, v35
	v_mov_b32_e32 v93, v156
	v_mov_b32_e32 v99, v157
	v_pk_add_f32 v[98:99], v[92:93], v[98:99] neg_lo:[0,1] neg_hi:[0,1]
	v_pk_mul_f32 v[34:35], v[94:95], v[158:159]
	v_lshl_add_u64 v[92:93], s[34:35], 0, v[2:3]
	v_lshl_add_u64 v[2:3], s[36:37], 0, v[2:3]
	v_mov_b32_e32 v153, v34
	v_mov_b32_e32 v155, v35
	v_lshl_add_u64 v[160:161], v[92:93], 0, v[0:1]
	v_lshl_add_u64 v[2:3], v[2:3], 0, v[0:1]
	v_pk_add_f32 v[34:35], v[152:153], v[154:155]
	global_load_dwordx4 v[152:155], v[160:161], off
	global_load_dwordx4 v[156:159], v[2:3], off
	s_waitcnt vmcnt(0)
	v_pk_mul_f32 v[92:93], v[24:25], v[156:157]
	s_nop 0
	v_pk_fma_f32 v[92:93], v[76:77], v[152:153], v[92:93] neg_lo:[0,0,1] neg_hi:[0,0,1]
	v_pk_mul_f32 v[76:77], v[76:77], v[156:157]
	v_mul_f32_e32 v94, v26, v158
	v_pk_fma_f32 v[24:25], v[24:25], v[152:153], v[76:77]
	v_mul_f32_e32 v76, v78, v154
	v_mul_f32_e32 v152, v26, v154
	v_mul_f32_e32 v154, v78, v158
	v_mov_b32_e32 v26, v79
	v_mov_b32_e32 v158, v155
	v_mov_b32_e32 v78, v27
	v_pk_mul_f32 v[156:157], v[26:27], v[158:159]
	v_pk_mul_f32 v[26:27], v[78:79], v[158:159]
	v_mov_b32_e32 v77, v156
	v_mov_b32_e32 v95, v157
	v_mov_b32_e32 v153, v26
	v_mov_b32_e32 v155, v27
	v_pk_add_f32 v[94:95], v[76:77], v[94:95] neg_lo:[0,1] neg_hi:[0,1]
	v_pk_add_f32 v[26:27], v[152:153], v[154:155]
	global_load_dwordx4 v[76:79], v[160:161], off offset:64
	global_load_dwordx4 v[152:155], v[2:3], off offset:64
	s_waitcnt vmcnt(0)
	v_pk_mul_f32 v[2:3], v[20:21], v[152:153]
	s_nop 0
	v_pk_fma_f32 v[156:157], v[28:29], v[76:77], v[2:3] neg_lo:[0,0,1] neg_hi:[0,0,1]
	v_pk_mul_f32 v[2:3], v[28:29], v[152:153]
	v_mul_f32_e32 v28, v22, v154
	v_pk_fma_f32 v[20:21], v[20:21], v[76:77], v[2:3]
	v_mul_f32_e32 v2, v30, v78
	v_mul_f32_e32 v76, v22, v78
	v_mul_f32_e32 v78, v30, v154
	v_mov_b32_e32 v22, v31
	v_mov_b32_e32 v154, v79
	v_pk_mul_f32 v[152:153], v[22:23], v[154:155]
	v_mov_b32_e32 v30, v23
	v_mov_b32_e32 v3, v152
	v_mov_b32_e32 v29, v153
	v_pk_add_f32 v[158:159], v[2:3], v[28:29] neg_lo:[0,1] neg_hi:[0,1]
	v_pk_mul_f32 v[2:3], v[30:31], v[154:155]
	v_mov_b64_e32 v[28:29], v[156:157]
	v_mov_b32_e32 v77, v2
	v_mov_b32_e32 v79, v3
	v_pk_add_f32 v[22:23], v[76:77], v[78:79]
	v_mov_b64_e32 v[76:77], v[92:93]
	v_mov_b64_e32 v[78:79], v[94:95]
	v_mov_b64_e32 v[92:93], v[96:97]
	v_mov_b64_e32 v[94:95], v[98:99]
	v_mov_b64_e32 v[96:97], v[100:101]
	v_mov_b64_e32 v[98:99], v[102:103]
	v_mov_b64_e32 v[100:101], v[104:105]
	v_mov_b64_e32 v[102:103], v[106:107]
	v_mov_b64_e32 v[104:105], v[108:109]
	v_mov_b64_e32 v[106:107], v[110:111]
	v_mov_b64_e32 v[108:109], v[112:113]
	v_mov_b64_e32 v[110:111], v[114:115]
	v_mov_b64_e32 v[112:113], v[120:121]
	v_mov_b64_e32 v[114:115], v[122:123]
	v_mov_b64_e32 v[120:121], v[128:129]
	v_mov_b64_e32 v[122:123], v[130:131]
	v_mov_b64_e32 v[128:129], v[148:149]
	v_mov_b64_e32 v[130:131], v[150:151]
	v_mov_b64_e32 v[148:149], v[146:147]
	v_mov_b64_e32 v[146:147], v[144:145]
	v_mov_b64_e32 v[144:145], v[142:143]
	v_mov_b64_e32 v[142:143], v[140:141]
	v_mov_b64_e32 v[140:141], v[138:139]
	v_mov_b64_e32 v[152:153], v[126:127]
	v_mov_b64_e32 v[138:139], v[136:137]
	v_mov_b64_e32 v[136:137], v[134:135]
	v_mov_b64_e32 v[150:151], v[124:125]
	v_mov_b64_e32 v[126:127], v[118:119]
	v_mov_b64_e32 v[30:31], v[158:159]
	v_mov_b64_e32 v[134:135], v[132:133]
	v_mov_b64_e32 v[124:125], v[116:117]
	s_cmp_eq_u32 s42, 1
	s_cselect_b64 s[34:35], -1, 0
	s_cmp_lg_u32 s42, 1
	s_cbranch_scc0 .LBB0_316

; __device__ void even_in_tile(const P& p, int li_even, int tm, int tn, char* smem) {
;     ...
;   if (seg != 6) {
;     bf16_t* dst = R + (seg == 0 ? R_MQ : seg == 1 ? R_MK : seg == 3 ? R_RQ : R_RK) + (size_t)bh * 4096 * 128;
; #pragma unroll
;     for (int i = 0; i < MI; ++i)
; #pragma unroll
;       for (int j = 0; j < 4; ++j) {
;         u32x2 v;
;         v.x = pk_bf16(acc[i][j][0], acc[i][j][1]);
;         v.y = pk_bf16(acc[i][j][2], acc[i][j][3]);
;         *(u32x2*)(dst + (size_t)(s0 + MROW(i)) * 128 + NCOL(j)) = v;
;       }
.LBB0_306:
	v_lshlrev_b32_e32 v0, 3, v219
	s_andn2_b64 vcc, exec, s[30:31]
	v_and_b32_e32 v249, 0xffffff80, v215
	v_cvt_pk_bf16_f32 v216, v124, v125
	v_cvt_pk_bf16_f32 v217, v126, v127
	v_lshl_or_b32 v0, v218, 6, v0
	v_cvt_pk_bf16_f32 v206, v150, v151
	v_cvt_pk_bf16_f32 v207, v152, v153
	v_cvt_pk_bf16_f32 v204, v88, v89
	v_cvt_pk_bf16_f32 v205, v90, v91
	v_cvt_pk_bf16_f32 v202, v84, v85
	v_cvt_pk_bf16_f32 v203, v86, v87
	v_cvt_pk_bf16_f32 v200, v134, v135
	v_cvt_pk_bf16_f32 v201, v136, v137
	v_cvt_pk_bf16_f32 v198, v138, v139
	v_cvt_pk_bf16_f32 v199, v140, v141
	v_cvt_pk_bf16_f32 v196, v80, v81
	v_cvt_pk_bf16_f32 v197, v82, v83
	v_cvt_pk_bf16_f32 v194, v72, v73
	v_cvt_pk_bf16_f32 v195, v74, v75
	v_cvt_pk_bf16_f32 v192, v142, v143
	v_cvt_pk_bf16_f32 v193, v144, v145
	v_cvt_pk_bf16_f32 v190, v146, v147
	v_cvt_pk_bf16_f32 v191, v148, v149
	v_cvt_pk_bf16_f32 v188, v68, v69
	v_cvt_pk_bf16_f32 v189, v70, v71
	v_cvt_pk_bf16_f32 v186, v64, v65
	v_cvt_pk_bf16_f32 v187, v66, v67
	v_cvt_pk_bf16_f32 v184, v128, v129
	v_cvt_pk_bf16_f32 v185, v130, v131
	v_cvt_pk_bf16_f32 v182, v120, v121
	v_cvt_pk_bf16_f32 v183, v122, v123
	v_cvt_pk_bf16_f32 v180, v60, v61
	v_cvt_pk_bf16_f32 v181, v62, v63
	v_cvt_pk_bf16_f32 v178, v56, v57
	v_cvt_pk_bf16_f32 v179, v58, v59
	v_cvt_pk_bf16_f32 v176, v112, v113
	v_cvt_pk_bf16_f32 v177, v114, v115
	v_cvt_pk_bf16_f32 v174, v108, v109
	v_cvt_pk_bf16_f32 v175, v110, v111
	v_cvt_pk_bf16_f32 v172, v52, v53
	v_cvt_pk_bf16_f32 v173, v54, v55
	v_cvt_pk_bf16_f32 v170, v48, v49
	v_cvt_pk_bf16_f32 v171, v50, v51
	v_cvt_pk_bf16_f32 v168, v104, v105
	v_cvt_pk_bf16_f32 v169, v106, v107
	v_cvt_pk_bf16_f32 v166, v100, v101
	v_cvt_pk_bf16_f32 v167, v102, v103
	v_cvt_pk_bf16_f32 v164, v44, v45
	v_cvt_pk_bf16_f32 v165, v46, v47
	v_cvt_pk_bf16_f32 v162, v40, v41
	v_cvt_pk_bf16_f32 v163, v42, v43
	v_cvt_pk_bf16_f32 v160, v96, v97
	v_cvt_pk_bf16_f32 v161, v98, v99
	v_cvt_pk_bf16_f32 v158, v92, v93
	v_cvt_pk_bf16_f32 v159, v94, v95
	v_cvt_pk_bf16_f32 v156, v36, v37
	v_cvt_pk_bf16_f32 v157, v38, v39
	v_cvt_pk_bf16_f32 v154, v32, v33
	v_cvt_pk_bf16_f32 v155, v34, v35
	v_cvt_pk_bf16_f32 v132, v76, v77
	v_cvt_pk_bf16_f32 v133, v78, v79
	v_cvt_pk_bf16_f32 v118, v28, v29
	v_cvt_pk_bf16_f32 v119, v30, v31
	v_cvt_pk_bf16_f32 v116, v24, v25
	v_cvt_pk_bf16_f32 v117, v26, v27
	v_cvt_pk_bf16_f32 v2, v20, v21
	v_cvt_pk_bf16_f32 v3, v22, v23
	s_cbranch_vccnz .LBB0_381
; __device__ void even_in_tile(const P& p, int li_even, int tm, int tn, char* smem) {
;     ...
;   if (seg != 6) {
;     bf16_t* dst = R + (seg == 0 ? R_MQ : seg == 1 ? R_MK : seg == 3 ? R_RQ : R_RK) + (size_t)bh * 4096 * 128;
; #pragma unroll
;     for (int i = 0; i < MI; ++i)
; #pragma unroll
;       for (int j = 0; j < 4; ++j) {
;         u32x2 v;
;         v.x = pk_bf16(acc[i][j][0], acc[i][j][1]);
;         v.y = pk_bf16(acc[i][j][2], acc[i][j][3]);
;         *(u32x2*)(dst + (size_t)(s0 + MROW(i)) * 128 + NCOL(j)) = v;
;       }
	s_cmp_eq_u32 s42, 3
	s_mov_b32 s7, 0x1800000
	s_cselect_b32 s7, s7, 0x2000000
	s_and_b64 s[30:31], s[34:35], exec
	s_cselect_b32 s7, 0x800000, s7
	s_cmp_gt_u32 s24, 3
	s_cselect_b32 s7, s7, 0
	s_lshl_b32 s7, s7, 1
	s_add_u32 s30, s40, s7
	s_addc_u32 s31, s39, 0
	s_ashr_i32 s7, s6, 31
	v_add_u32_e32 v220, s41, v249
	s_lshl_b64 s[24:25], s[6:7], 20
	v_or_b32_e32 v220, v220, v213
	s_add_u32 s24, s30, s24
	v_ashrrev_i32_e32 v221, 31, v220
	s_addc_u32 s25, s31, s25
	v_lshlrev_b64 v[222:223], 8, v[220:221]
	v_lshl_add_u64 v[222:223], s[24:25], 0, v[222:223]
	v_lshl_add_u64 v[222:223], v[222:223], 0, v[0:1]
	v_mov_b64_e32 v[4:5], v[216:217]
	v_mov_b64_e32 v[6:7], v[206:207]
	s_nop 1
	v_permlane16_swap_b32_e32 v4, v6
	v_permlane16_swap_b32_e32 v5, v7
	v_lshl_add_u64 v[14:15], v[222:223], 0, v[12:13]
	global_store_dwordx4 v[14:15], v[4:7], off
	v_mov_b64_e32 v[8:9], v[204:205]
	v_mov_b64_e32 v[10:11], v[202:203]
	s_nop 1
	v_permlane16_swap_b32_e32 v8, v10
	v_permlane16_swap_b32_e32 v9, v11
	v_lshl_add_u64 v[14:15], v[222:223], 0, v[12:13]
	global_store_dwordx4 v[14:15], v[8:11], off offset:128
	v_or_b32_e32 v222, 16, v220
	v_ashrrev_i32_e32 v223, 31, v222
	v_lshlrev_b64 v[222:223], 8, v[222:223]
	v_lshl_add_u64 v[222:223], s[24:25], 0, v[222:223]
	v_lshl_add_u64 v[222:223], v[222:223], 0, v[0:1]
	v_mov_b64_e32 v[4:5], v[200:201]
	v_mov_b64_e32 v[6:7], v[198:199]
	s_nop 1
	v_permlane16_swap_b32_e32 v4, v6
	v_permlane16_swap_b32_e32 v5, v7
	v_lshl_add_u64 v[14:15], v[222:223], 0, v[12:13]
	global_store_dwordx4 v[14:15], v[4:7], off
	v_mov_b64_e32 v[8:9], v[196:197]
	v_mov_b64_e32 v[10:11], v[194:195]
	s_nop 1
	v_permlane16_swap_b32_e32 v8, v10
	v_permlane16_swap_b32_e32 v9, v11
	v_lshl_add_u64 v[14:15], v[222:223], 0, v[12:13]
	global_store_dwordx4 v[14:15], v[8:11], off offset:128
	v_or_b32_e32 v222, 32, v220
	v_ashrrev_i32_e32 v223, 31, v222
	v_lshlrev_b64 v[222:223], 8, v[222:223]
	v_lshl_add_u64 v[222:223], s[24:25], 0, v[222:223]
	v_lshl_add_u64 v[222:223], v[222:223], 0, v[0:1]
	v_mov_b64_e32 v[4:5], v[192:193]
	v_mov_b64_e32 v[6:7], v[190:191]
	s_nop 1
	v_permlane16_swap_b32_e32 v4, v6
	v_permlane16_swap_b32_e32 v5, v7
	v_lshl_add_u64 v[14:15], v[222:223], 0, v[12:13]
	global_store_dwordx4 v[14:15], v[4:7], off
	v_mov_b64_e32 v[8:9], v[188:189]
	v_mov_b64_e32 v[10:11], v[186:187]
	s_nop 1
	v_permlane16_swap_b32_e32 v8, v10
	v_permlane16_swap_b32_e32 v9, v11
	v_lshl_add_u64 v[14:15], v[222:223], 0, v[12:13]
	global_store_dwordx4 v[14:15], v[8:11], off offset:128
	v_or_b32_e32 v222, 48, v220
	v_ashrrev_i32_e32 v223, 31, v222
	v_lshlrev_b64 v[222:223], 8, v[222:223]
	v_lshl_add_u64 v[222:223], s[24:25], 0, v[222:223]
	v_lshl_add_u64 v[222:223], v[222:223], 0, v[0:1]
	v_mov_b64_e32 v[4:5], v[184:185]
	v_mov_b64_e32 v[6:7], v[182:183]
	s_nop 1
	v_permlane16_swap_b32_e32 v4, v6
	v_permlane16_swap_b32_e32 v5, v7
	v_lshl_add_u64 v[14:15], v[222:223], 0, v[12:13]
	global_store_dwordx4 v[14:15], v[4:7], off
	v_mov_b64_e32 v[8:9], v[180:181]
	v_mov_b64_e32 v[10:11], v[178:179]
	s_nop 1
	v_permlane16_swap_b32_e32 v8, v10
	v_permlane16_swap_b32_e32 v9, v11
	v_lshl_add_u64 v[14:15], v[222:223], 0, v[12:13]
	global_store_dwordx4 v[14:15], v[8:11], off offset:128
	v_or_b32_e32 v222, 64, v220
	v_ashrrev_i32_e32 v223, 31, v222
	v_lshlrev_b64 v[222:223], 8, v[222:223]
	v_lshl_add_u64 v[222:223], s[24:25], 0, v[222:223]
	v_lshl_add_u64 v[222:223], v[222:223], 0, v[0:1]
	v_mov_b64_e32 v[4:5], v[176:177]
	v_mov_b64_e32 v[6:7], v[174:175]
	s_nop 1
	v_permlane16_swap_b32_e32 v4, v6
	v_permlane16_swap_b32_e32 v5, v7
	v_lshl_add_u64 v[14:15], v[222:223], 0, v[12:13]
	global_store_dwordx4 v[14:15], v[4:7], off
	v_mov_b64_e32 v[8:9], v[172:173]
	v_mov_b64_e32 v[10:11], v[170:171]
	s_nop 1
	v_permlane16_swap_b32_e32 v8, v10
	v_permlane16_swap_b32_e32 v9, v11
	v_lshl_add_u64 v[14:15], v[222:223], 0, v[12:13]
	global_store_dwordx4 v[14:15], v[8:11], off offset:128
	v_or_b32_e32 v222, 0x50, v220
	v_ashrrev_i32_e32 v223, 31, v222
	v_lshlrev_b64 v[222:223], 8, v[222:223]
	v_lshl_add_u64 v[222:223], s[24:25], 0, v[222:223]
	v_lshl_add_u64 v[222:223], v[222:223], 0, v[0:1]
	v_mov_b64_e32 v[4:5], v[168:169]
	v_mov_b64_e32 v[6:7], v[166:167]
	s_nop 1
	v_permlane16_swap_b32_e32 v4, v6
	v_permlane16_swap_b32_e32 v5, v7
	v_lshl_add_u64 v[14:15], v[222:223], 0, v[12:13]
	global_store_dwordx4 v[14:15], v[4:7], off
	v_mov_b64_e32 v[8:9], v[164:165]
	v_mov_b64_e32 v[10:11], v[162:163]
	s_nop 1
	v_permlane16_swap_b32_e32 v8, v10
	v_permlane16_swap_b32_e32 v9, v11
	v_lshl_add_u64 v[14:15], v[222:223], 0, v[12:13]
	global_store_dwordx4 v[14:15], v[8:11], off offset:128
	v_or_b32_e32 v222, 0x60, v220
	v_or_b32_e32 v220, 0x70, v220
	v_ashrrev_i32_e32 v223, 31, v222
	v_ashrrev_i32_e32 v221, 31, v220
	v_lshlrev_b64 v[222:223], 8, v[222:223]
	v_lshlrev_b64 v[220:221], 8, v[220:221]
	v_lshl_add_u64 v[222:223], s[24:25], 0, v[222:223]
	v_lshl_add_u64 v[220:221], s[24:25], 0, v[220:221]
	v_lshl_add_u64 v[222:223], v[222:223], 0, v[0:1]
	v_lshl_add_u64 v[220:221], v[220:221], 0, v[0:1]
	v_mov_b64_e32 v[4:5], v[160:161]
	v_mov_b64_e32 v[6:7], v[158:159]
	s_nop 1
	v_permlane16_swap_b32_e32 v4, v6
	v_permlane16_swap_b32_e32 v5, v7
	v_lshl_add_u64 v[14:15], v[222:223], 0, v[12:13]
	global_store_dwordx4 v[14:15], v[4:7], off
	v_mov_b64_e32 v[8:9], v[156:157]
	v_mov_b64_e32 v[10:11], v[154:155]
	s_nop 1
	v_permlane16_swap_b32_e32 v8, v10
	v_permlane16_swap_b32_e32 v9, v11
	v_lshl_add_u64 v[14:15], v[222:223], 0, v[12:13]
	global_store_dwordx4 v[14:15], v[8:11], off offset:128
	v_mov_b64_e32 v[4:5], v[132:133]
	v_mov_b64_e32 v[6:7], v[118:119]
	s_nop 1
	v_permlane16_swap_b32_e32 v4, v6
	v_permlane16_swap_b32_e32 v5, v7
	v_lshl_add_u64 v[14:15], v[220:221], 0, v[12:13]
	global_store_dwordx4 v[14:15], v[4:7], off
	v_mov_b64_e32 v[8:9], v[116:117]
	v_mov_b64_e32 v[10:11], v[2:3]
	s_nop 1
	v_permlane16_swap_b32_e32 v8, v10
	v_permlane16_swap_b32_e32 v9, v11
	v_lshl_add_u64 v[14:15], v[220:221], 0, v[12:13]
	global_store_dwordx4 v[14:15], v[8:11], off offset:128
	s_andn2_b64 vcc, exec, s[28:29]
	s_cbranch_vccz .LBB0_382

; __device__ void even_in_tile(const P& p, int li_even, int tm, int tn, char* smem) {
;     ...
;   if (seg == 6) {
;     bf16_t* dst = R + R_RG;
; #pragma unroll
;     for (int i = 0; i < MI; ++i)
; #pragma unroll
;       for (int j = 0; j < 4; ++j) {
;         u32x2 v;
;         v.x = pk_bf16(acc[i][j][0], acc[i][j][1]);
;         v.y = pk_bf16(acc[i][j][2], acc[i][j][3]);
;         *(u32x2*)(dst + (size_t)(t0 + MROW(i)) * 512 + hd * 128 + NCOL(j)) = v;
;       }
;   }
.LBB0_309:
	s_lshl_b32 s7, s49, 8
	v_add_u32_e32 v20, s54, v249
	s_add_u32 s7, s45, s7
	v_or_b32_e32 v20, v20, v213
	s_addc_u32 s25, s48, 0
	s_add_u32 s24, s7, 0x20a84000
	v_ashrrev_i32_e32 v21, 31, v20
	s_addc_u32 s25, s25, 0
	v_lshlrev_b64 v[22:23], 10, v[20:21]
	v_lshl_add_u64 v[22:23], s[24:25], 0, v[22:23]
	v_lshl_add_u64 v[22:23], v[22:23], 0, v[0:1]
	v_mov_b64_e32 v[4:5], v[216:217]
	v_mov_b64_e32 v[6:7], v[206:207]
	s_nop 1
	v_permlane16_swap_b32_e32 v4, v6
	v_permlane16_swap_b32_e32 v5, v7
	v_lshl_add_u64 v[14:15], v[22:23], 0, v[12:13]
	global_store_dwordx4 v[14:15], v[4:7], off
	v_mov_b64_e32 v[8:9], v[204:205]
	v_mov_b64_e32 v[10:11], v[202:203]
	s_nop 1
	v_permlane16_swap_b32_e32 v8, v10
	v_permlane16_swap_b32_e32 v9, v11
	v_lshl_add_u64 v[14:15], v[22:23], 0, v[12:13]
	global_store_dwordx4 v[14:15], v[8:11], off offset:128
	v_or_b32_e32 v22, 16, v20
	v_ashrrev_i32_e32 v23, 31, v22
	v_lshlrev_b64 v[22:23], 10, v[22:23]
	v_lshl_add_u64 v[22:23], s[24:25], 0, v[22:23]
	v_lshl_add_u64 v[22:23], v[22:23], 0, v[0:1]
	v_mov_b64_e32 v[4:5], v[200:201]
	v_mov_b64_e32 v[6:7], v[198:199]
	s_nop 1
	v_permlane16_swap_b32_e32 v4, v6
	v_permlane16_swap_b32_e32 v5, v7
	v_lshl_add_u64 v[14:15], v[22:23], 0, v[12:13]
	global_store_dwordx4 v[14:15], v[4:7], off
	v_mov_b64_e32 v[8:9], v[196:197]
	v_mov_b64_e32 v[10:11], v[194:195]
	s_nop 1
	v_permlane16_swap_b32_e32 v8, v10
	v_permlane16_swap_b32_e32 v9, v11
	v_lshl_add_u64 v[14:15], v[22:23], 0, v[12:13]
	global_store_dwordx4 v[14:15], v[8:11], off offset:128
	v_or_b32_e32 v22, 32, v20
	v_ashrrev_i32_e32 v23, 31, v22
	v_lshlrev_b64 v[22:23], 10, v[22:23]
	v_lshl_add_u64 v[22:23], s[24:25], 0, v[22:23]
	v_lshl_add_u64 v[22:23], v[22:23], 0, v[0:1]
	v_mov_b64_e32 v[4:5], v[192:193]
	v_mov_b64_e32 v[6:7], v[190:191]
	s_nop 1
	v_permlane16_swap_b32_e32 v4, v6
	v_permlane16_swap_b32_e32 v5, v7
	v_lshl_add_u64 v[14:15], v[22:23], 0, v[12:13]
	global_store_dwordx4 v[14:15], v[4:7], off
	v_mov_b64_e32 v[8:9], v[188:189]
	v_mov_b64_e32 v[10:11], v[186:187]
	s_nop 1
	v_permlane16_swap_b32_e32 v8, v10
	v_permlane16_swap_b32_e32 v9, v11
	v_lshl_add_u64 v[14:15], v[22:23], 0, v[12:13]
	global_store_dwordx4 v[14:15], v[8:11], off offset:128
	v_or_b32_e32 v22, 48, v20
	v_ashrrev_i32_e32 v23, 31, v22
	v_lshlrev_b64 v[22:23], 10, v[22:23]
	v_lshl_add_u64 v[22:23], s[24:25], 0, v[22:23]
	v_lshl_add_u64 v[22:23], v[22:23], 0, v[0:1]
	v_mov_b64_e32 v[4:5], v[184:185]
	v_mov_b64_e32 v[6:7], v[182:183]
	s_nop 1
	v_permlane16_swap_b32_e32 v4, v6
	v_permlane16_swap_b32_e32 v5, v7
	v_lshl_add_u64 v[14:15], v[22:23], 0, v[12:13]
	global_store_dwordx4 v[14:15], v[4:7], off
	v_mov_b64_e32 v[8:9], v[180:181]
	v_mov_b64_e32 v[10:11], v[178:179]
	s_nop 1
	v_permlane16_swap_b32_e32 v8, v10
	v_permlane16_swap_b32_e32 v9, v11
	v_lshl_add_u64 v[14:15], v[22:23], 0, v[12:13]
	global_store_dwordx4 v[14:15], v[8:11], off offset:128
	v_or_b32_e32 v22, 64, v20
	v_ashrrev_i32_e32 v23, 31, v22
	v_lshlrev_b64 v[22:23], 10, v[22:23]
	v_lshl_add_u64 v[22:23], s[24:25], 0, v[22:23]
	v_lshl_add_u64 v[22:23], v[22:23], 0, v[0:1]
	v_mov_b64_e32 v[4:5], v[176:177]
	v_mov_b64_e32 v[6:7], v[174:175]
	s_nop 1
	v_permlane16_swap_b32_e32 v4, v6
	v_permlane16_swap_b32_e32 v5, v7
	v_lshl_add_u64 v[14:15], v[22:23], 0, v[12:13]
	global_store_dwordx4 v[14:15], v[4:7], off
	v_mov_b64_e32 v[8:9], v[172:173]
	v_mov_b64_e32 v[10:11], v[170:171]
	s_nop 1
	v_permlane16_swap_b32_e32 v8, v10
	v_permlane16_swap_b32_e32 v9, v11
	v_lshl_add_u64 v[14:15], v[22:23], 0, v[12:13]
	global_store_dwordx4 v[14:15], v[8:11], off offset:128
	v_or_b32_e32 v22, 0x50, v20
	v_ashrrev_i32_e32 v23, 31, v22
	v_lshlrev_b64 v[22:23], 10, v[22:23]
	v_lshl_add_u64 v[22:23], s[24:25], 0, v[22:23]
	v_lshl_add_u64 v[22:23], v[22:23], 0, v[0:1]
	v_mov_b64_e32 v[4:5], v[168:169]
	v_mov_b64_e32 v[6:7], v[166:167]
	s_nop 1
	v_permlane16_swap_b32_e32 v4, v6
	v_permlane16_swap_b32_e32 v5, v7
	v_lshl_add_u64 v[14:15], v[22:23], 0, v[12:13]
	global_store_dwordx4 v[14:15], v[4:7], off
	v_mov_b64_e32 v[8:9], v[164:165]
	v_mov_b64_e32 v[10:11], v[162:163]
	s_nop 1
	v_permlane16_swap_b32_e32 v8, v10
	v_permlane16_swap_b32_e32 v9, v11
	v_lshl_add_u64 v[14:15], v[22:23], 0, v[12:13]
	global_store_dwordx4 v[14:15], v[8:11], off offset:128
	v_or_b32_e32 v22, 0x60, v20
	v_or_b32_e32 v20, 0x70, v20
	v_ashrrev_i32_e32 v23, 31, v22
	v_ashrrev_i32_e32 v21, 31, v20
	v_lshlrev_b64 v[22:23], 10, v[22:23]
	v_lshlrev_b64 v[20:21], 10, v[20:21]
	v_lshl_add_u64 v[22:23], s[24:25], 0, v[22:23]
	v_lshl_add_u64 v[20:21], s[24:25], 0, v[20:21]
	v_lshl_add_u64 v[22:23], v[22:23], 0, v[0:1]
	v_lshl_add_u64 v[20:21], v[20:21], 0, v[0:1]
	v_mov_b64_e32 v[4:5], v[160:161]
	v_mov_b64_e32 v[6:7], v[158:159]
	s_nop 1
	v_permlane16_swap_b32_e32 v4, v6
	v_permlane16_swap_b32_e32 v5, v7
	v_lshl_add_u64 v[14:15], v[22:23], 0, v[12:13]
	global_store_dwordx4 v[14:15], v[4:7], off
	v_mov_b64_e32 v[8:9], v[156:157]
	v_mov_b64_e32 v[10:11], v[154:155]
	s_nop 1
	v_permlane16_swap_b32_e32 v8, v10
	v_permlane16_swap_b32_e32 v9, v11
	v_lshl_add_u64 v[14:15], v[22:23], 0, v[12:13]
	global_store_dwordx4 v[14:15], v[8:11], off offset:128
	v_mov_b64_e32 v[4:5], v[132:133]
	v_mov_b64_e32 v[6:7], v[118:119]
	s_nop 1
	v_permlane16_swap_b32_e32 v4, v6
	v_permlane16_swap_b32_e32 v5, v7
	v_lshl_add_u64 v[14:15], v[20:21], 0, v[12:13]
	global_store_dwordx4 v[14:15], v[4:7], off
	v_mov_b64_e32 v[8:9], v[116:117]
	v_mov_b64_e32 v[10:11], v[2:3]
	s_nop 1
	v_permlane16_swap_b32_e32 v8, v10
	v_permlane16_swap_b32_e32 v9, v11
	v_lshl_add_u64 v[14:15], v[20:21], 0, v[12:13]
	global_store_dwordx4 v[14:15], v[8:11], off offset:128

; template <int MI, bool SWAP, bool F8 = false>
; __device__ __forceinline__ void gemm_core(const bf16_t* __restrict__ A, int lda, const bf16_t* __restrict__ B, int ldb,
;                                           int K, char* smem, f32x4 (&acc)[MI][4]) {
;     ...
;   for (int kt = 0; kt < nk; ++kt) {
;     __syncthreads();
; #pragma unroll
;     for (int i = 0; i < MI; ++i) *(u32x4*)(smem + woff + i * 4096) = ra[i];
; #pragma unroll
;     for (int i = 0; i < 4; ++i) *(u32x4*)(smem + 32768 + woff + i * 4096) = rb[i];
;     __syncthreads();
;     if (kt + 1 < nk) {
; #pragma unroll
;       for (int i = 0; i < MI; ++i) ra[i] = *(const u32x4*)(ap + (size_t)(32 * i) * lda + (kt + 1) * 64);
; #pragma unroll
;       for (int i = 0; i < 4; ++i) rb[i] = *(const u32x4*)(bp + (size_t)(32 * i) * ldb + (kt + 1) * 64);
;     }
;     if (F8) {
;       const int c0 = (g ^ (li & 7)) << 4, c1 = ((4 + g) ^ (li & 7)) << 4;
;       i32x8 wf8[4];
; #pragma unroll
;       for (int j = 0; j < 4; ++j) {
;         const char* rp = smem + wrow + ((j & 1) * 16 + (j >> 1) * 64) * 128;
;         const u32x4 lo = *(const u32x4*)(rp + c0), hi = *(const u32x4*)(rp + c1);
;         wf8[j] = (i32x8){(int)lo.x, (int)lo.y, (int)lo.z, (int)lo.w, (int)hi.x, (int)hi.y, (int)hi.z, (int)hi.w};
;       }
; #pragma unroll
;       for (int i = 0; i < MI; ++i) {
;         const char* rp = smem + xrow + i * 2048;
;         const u32x4 lo = *(const u32x4*)(rp + c0), hi = *(const u32x4*)(rp + c1);
;         const i32x8 xf8 = {(int)lo.x, (int)lo.y, (int)lo.z, (int)lo.w, (int)hi.x, (int)hi.y, (int)hi.z, (int)hi.w};
; #pragma unroll
;         for (int j = 0; j < 4; ++j)
;           acc[i][j] = __builtin_amdgcn_mfma_scale_f32_16x16x128_f8f6f4(wf8[j], xf8, acc[i][j], 0, 0, 0, 0x77777777, 0, 0x7f7f7f7f);
;       }
;     } else {
; #pragma unroll
;     for (int kk = 0; kk < 2; ++kk) {
;       const int ch = ((kk * 4 + g) ^ (li & 7)) << 4;
;       bf16x8 xf[MI], wf[4];
; #pragma unroll
;       for (int j = 0; j < 4; ++j) wf[j] = *(const bf16x8*)(smem + wrow + ((j & 1) * 16 + (j >> 1) * 64) * 128 + ch);
; #pragma unroll
;       for (int i = 0; i < MI; ++i) xf[i] = *(const bf16x8*)(smem + xrow + i * 2048 + ch);
; #pragma unroll
;       for (int i = 0; i < MI; ++i)
; #pragma unroll
;         for (int j = 0; j < 4; ++j) {
.LBB0_313:
	v_add_u32_e32 v215, v204, v205
	v_add_u32_e32 v213, v203, v205
	s_waitcnt vmcnt(63) expcnt(7) lgkmcnt(15)
	s_barrier
	s_mov_b32 m0, s62
	s_nop 0
	global_load_lds_dwordx4 v252, s[56:57]
	s_add_u32 m0, s62, 0x1000
	s_nop 0
	global_load_lds_dwordx4 v253, s[56:57]
	s_add_u32 s56, s56, 0x20000
	s_addc_u32 s57, s57, 0
	s_add_u32 m0, s62, 0x2000
	s_nop 0
	global_load_lds_dwordx4 v252, s[56:57]
	s_add_u32 m0, s62, 0x3000
	s_nop 0
	global_load_lds_dwordx4 v253, s[56:57]
	s_add_u32 s56, s56, 0x20000
	s_addc_u32 s57, s57, 0
	s_add_u32 m0, s62, 0x4000
	s_nop 0
	global_load_lds_dwordx4 v252, s[56:57]
	s_add_u32 m0, s62, 0x5000
	s_nop 0
	global_load_lds_dwordx4 v253, s[56:57]
	s_add_u32 s56, s56, 0x20000
	s_addc_u32 s57, s57, 0
	s_add_u32 m0, s62, 0x6000
	s_nop 0
	global_load_lds_dwordx4 v252, s[56:57]
	s_add_u32 m0, s62, 0x7000
	s_nop 0
	global_load_lds_dwordx4 v253, s[56:57]
	s_sub_u32 s56, s56, 0x60000
	s_subb_u32 s57, s57, 0
	s_add_u32 m0, s62, 0x8000
	s_nop 0
	global_load_lds_dwordx4 v252, s[58:59]
	s_add_u32 m0, s62, 0x9000
	s_nop 0
	global_load_lds_dwordx4 v253, s[58:59]
	s_add_u32 s58, s58, 0x20000
	s_addc_u32 s59, s59, 0
	s_add_u32 m0, s62, 0xa000
	s_nop 0
	global_load_lds_dwordx4 v252, s[58:59]
	s_add_u32 m0, s62, 0xb000
	s_nop 0
	global_load_lds_dwordx4 v253, s[58:59]
	s_sub_u32 s58, s58, 0x20000
	s_subb_u32 s59, s59, 0
	v_add_u32_e32 v252, 0x80, v252
	v_add_u32_e32 v253, 0x80, v253
	s_waitcnt vmcnt(0)
	s_barrier
	ds_read_b128 v[148:151], v213
	ds_read_b128 v[152:155], v215 offset:32768
	ds_read_b128 v[156:159], v215 offset:34816
	ds_read_b128 v[160:163], v213 offset:2048
	ds_read_b128 v[164:167], v215 offset:40960
	ds_read_b128 v[168:171], v215 offset:43008
	s_waitcnt lgkmcnt(4)
	v_mfma_f32_16x16x32_bf16 v[140:143], v[148:151], v[152:155], v[140:143]
	v_add_u32_e32 v0, v203, v206
	v_add_u32_e32 v207, v204, v206
	s_waitcnt lgkmcnt(3)
	v_mfma_f32_16x16x32_bf16 v[136:139], v[148:151], v[156:159], v[136:139]
	s_waitcnt lgkmcnt(1)
	v_mfma_f32_16x16x32_bf16 v[132:135], v[148:151], v[164:167], v[132:135]
	s_waitcnt lgkmcnt(0)
	v_mfma_f32_16x16x32_bf16 v[128:131], v[148:151], v[168:171], v[128:131]
	v_mfma_f32_16x16x32_bf16 v[124:127], v[160:163], v[152:155], v[124:127]
	v_mfma_f32_16x16x32_bf16 v[120:123], v[160:163], v[156:159], v[120:123]
	v_mfma_f32_16x16x32_bf16 v[116:119], v[160:163], v[164:167], v[116:119]
	v_mfma_f32_16x16x32_bf16 v[112:115], v[160:163], v[168:171], v[112:115]
	ds_read_b128 v[148:151], v213 offset:4096
	ds_read_b128 v[160:163], v213 offset:6144
	s_waitcnt lgkmcnt(1)
	v_mfma_f32_16x16x32_bf16 v[108:111], v[148:151], v[152:155], v[108:111]
	v_mfma_f32_16x16x32_bf16 v[104:107], v[148:151], v[156:159], v[104:107]
	v_mfma_f32_16x16x32_bf16 v[100:103], v[148:151], v[164:167], v[100:103]
	v_mfma_f32_16x16x32_bf16 v[96:99], v[148:151], v[168:171], v[96:99]
	s_waitcnt lgkmcnt(0)
	v_mfma_f32_16x16x32_bf16 v[92:95], v[160:163], v[152:155], v[92:95]
	v_mfma_f32_16x16x32_bf16 v[88:91], v[160:163], v[156:159], v[88:91]
	v_mfma_f32_16x16x32_bf16 v[80:83], v[160:163], v[164:167], v[80:83]
	v_mfma_f32_16x16x32_bf16 v[72:75], v[160:163], v[168:171], v[72:75]
	ds_read_b128 v[148:151], v213 offset:8192
	ds_read_b128 v[160:163], v213 offset:10240
	s_waitcnt lgkmcnt(1)
	v_mfma_f32_16x16x32_bf16 v[64:67], v[148:151], v[152:155], v[64:67]
	v_mfma_f32_16x16x32_bf16 v[60:63], v[148:151], v[156:159], v[60:63]
	v_mfma_f32_16x16x32_bf16 v[52:55], v[148:151], v[164:167], v[52:55]
	v_mfma_f32_16x16x32_bf16 v[48:51], v[148:151], v[168:171], v[48:51]
	s_waitcnt lgkmcnt(0)
	v_mfma_f32_16x16x32_bf16 v[44:47], v[160:163], v[152:155], v[44:47]
	v_mfma_f32_16x16x32_bf16 v[40:43], v[160:163], v[156:159], v[40:43]
	v_mfma_f32_16x16x32_bf16 v[36:39], v[160:163], v[164:167], v[36:39]
	v_mfma_f32_16x16x32_bf16 v[32:35], v[160:163], v[168:171], v[32:35]
	ds_read_b128 v[148:151], v213 offset:12288
	ds_read_b128 v[160:163], v213 offset:14336
	s_waitcnt lgkmcnt(1)
	v_mfma_f32_16x16x32_bf16 v[24:27], v[148:151], v[156:159], v[24:27]
	s_waitcnt lgkmcnt(0)
	v_mfma_f32_16x16x32_bf16 v[56:59], v[160:163], v[156:159], v[56:59]
	v_mfma_f32_16x16x32_bf16 v[68:71], v[160:163], v[152:155], v[68:71]
	v_mfma_f32_16x16x32_bf16 v[20:23], v[160:163], v[164:167], v[20:23]
	v_mfma_f32_16x16x32_bf16 v[144:147], v[160:163], v[168:171], v[144:147]
	v_mfma_f32_16x16x32_bf16 v[28:31], v[148:151], v[152:155], v[28:31]
	v_mfma_f32_16x16x32_bf16 v[84:87], v[148:151], v[164:167], v[84:87]
	v_mfma_f32_16x16x32_bf16 v[76:79], v[148:151], v[168:171], v[76:79]
	ds_read_b128 v[148:151], v0
	ds_read_b128 v[168:171], v207 offset:32768
	ds_read_b128 v[180:183], v207 offset:34816
	ds_read_b128 v[152:155], v0 offset:2048
	ds_read_b128 v[192:195], v207 offset:40960
	ds_read_b128 v[196:199], v207 offset:43008
	s_waitcnt lgkmcnt(4)
	v_mfma_f32_16x16x32_bf16 v[140:143], v[148:151], v[168:171], v[140:143]
	s_waitcnt lgkmcnt(3)
	v_mfma_f32_16x16x32_bf16 v[136:139], v[148:151], v[180:183], v[136:139]
	s_waitcnt lgkmcnt(1)
	v_mfma_f32_16x16x32_bf16 v[132:135], v[148:151], v[192:195], v[132:135]
	s_waitcnt lgkmcnt(0)
	v_mfma_f32_16x16x32_bf16 v[128:131], v[148:151], v[196:199], v[128:131]
	v_mfma_f32_16x16x32_bf16 v[124:127], v[152:155], v[168:171], v[124:127]
	v_mfma_f32_16x16x32_bf16 v[120:123], v[152:155], v[180:183], v[120:123]
	v_mfma_f32_16x16x32_bf16 v[116:119], v[152:155], v[192:195], v[116:119]
	v_mfma_f32_16x16x32_bf16 v[112:115], v[152:155], v[196:199], v[112:115]
	ds_read_b128 v[148:151], v0 offset:4096
	ds_read_b128 v[152:155], v0 offset:6144
	ds_read_b128 v[156:159], v0 offset:12288
	ds_read_b128 v[216:219], v0 offset:14336
	s_waitcnt lgkmcnt(3)
; template <int MI, bool SWAP, bool F8 = false>
; __device__ __forceinline__ void gemm_core(const bf16_t* __restrict__ A, int lda, const bf16_t* __restrict__ B, int ldb,
;                                           int K, char* smem, f32x4 (&acc)[MI][4]) {
;     ...
;   for (int kt = 0; kt < nk; ++kt) {
;     __syncthreads();
; #pragma unroll
;     for (int i = 0; i < MI; ++i) *(u32x4*)(smem + woff + i * 4096) = ra[i];
; #pragma unroll
;     for (int i = 0; i < 4; ++i) *(u32x4*)(smem + 32768 + woff + i * 4096) = rb[i];
;     __syncthreads();
;     if (kt + 1 < nk) {
; #pragma unroll
;       for (int i = 0; i < MI; ++i) ra[i] = *(const u32x4*)(ap + (size_t)(32 * i) * lda + (kt + 1) * 64);
; #pragma unroll
;       for (int i = 0; i < 4; ++i) rb[i] = *(const u32x4*)(bp + (size_t)(32 * i) * ldb + (kt + 1) * 64);
;     }
;     if (F8) {
;       const int c0 = (g ^ (li & 7)) << 4, c1 = ((4 + g) ^ (li & 7)) << 4;
;       i32x8 wf8[4];
; #pragma unroll
;       for (int j = 0; j < 4; ++j) {
;         const char* rp = smem + wrow + ((j & 1) * 16 + (j >> 1) * 64) * 128;
;         const u32x4 lo = *(const u32x4*)(rp + c0), hi = *(const u32x4*)(rp + c1);
;         wf8[j] = (i32x8){(int)lo.x, (int)lo.y, (int)lo.z, (int)lo.w, (int)hi.x, (int)hi.y, (int)hi.z, (int)hi.w};
;       }
; #pragma unroll
;       for (int i = 0; i < MI; ++i) {
;         const char* rp = smem + xrow + i * 2048;
;         const u32x4 lo = *(const u32x4*)(rp + c0), hi = *(const u32x4*)(rp + c1);
;         const i32x8 xf8 = {(int)lo.x, (int)lo.y, (int)lo.z, (int)lo.w, (int)hi.x, (int)hi.y, (int)hi.z, (int)hi.w};
; #pragma unroll
;         for (int j = 0; j < 4; ++j)
;           acc[i][j] = __builtin_amdgcn_mfma_scale_f32_16x16x128_f8f6f4(wf8[j], xf8, acc[i][j], 0, 0, 0, 0x77777777, 0, 0x7f7f7f7f);
;       }
;     } else {
; #pragma unroll
;     for (int kk = 0; kk < 2; ++kk) {
;       const int ch = ((kk * 4 + g) ^ (li & 7)) << 4;
;       bf16x8 xf[MI], wf[4];
; #pragma unroll
;       for (int j = 0; j < 4; ++j) wf[j] = *(const bf16x8*)(smem + wrow + ((j & 1) * 16 + (j >> 1) * 64) * 128 + ch);
; #pragma unroll
;       for (int i = 0; i < MI; ++i) xf[i] = *(const bf16x8*)(smem + xrow + i * 2048 + ch);
; #pragma unroll
;       for (int i = 0; i < MI; ++i)
; #pragma unroll
;         for (int j = 0; j < 4; ++j) {
	v_mfma_f32_16x16x32_bf16 v[108:111], v[148:151], v[168:171], v[108:111]
	v_mfma_f32_16x16x32_bf16 v[104:107], v[148:151], v[180:183], v[104:107]
	v_mfma_f32_16x16x32_bf16 v[100:103], v[148:151], v[192:195], v[100:103]
	v_mfma_f32_16x16x32_bf16 v[96:99], v[148:151], v[196:199], v[96:99]
	ds_read_b128 v[148:151], v0 offset:8192
	s_waitcnt lgkmcnt(3)
	v_mfma_f32_16x16x32_bf16 v[92:95], v[152:155], v[168:171], v[92:95]
	v_mfma_f32_16x16x32_bf16 v[88:91], v[152:155], v[180:183], v[88:91]
	v_mfma_f32_16x16x32_bf16 v[80:83], v[152:155], v[192:195], v[80:83]
	v_mfma_f32_16x16x32_bf16 v[72:75], v[152:155], v[196:199], v[72:75]
	ds_read_b128 v[152:155], v0 offset:10240
	s_waitcnt lgkmcnt(1)
	v_mfma_f32_16x16x32_bf16 v[64:67], v[148:151], v[168:171], v[64:67]
	v_mfma_f32_16x16x32_bf16 v[60:63], v[148:151], v[180:183], v[60:63]
	v_mfma_f32_16x16x32_bf16 v[52:55], v[148:151], v[192:195], v[52:55]
	v_mfma_f32_16x16x32_bf16 v[48:51], v[148:151], v[196:199], v[48:51]
	s_waitcnt lgkmcnt(0)
	v_mfma_f32_16x16x32_bf16 v[44:47], v[152:155], v[168:171], v[44:47]
	v_mfma_f32_16x16x32_bf16 v[40:43], v[152:155], v[180:183], v[40:43]
	v_mfma_f32_16x16x32_bf16 v[36:39], v[152:155], v[192:195], v[36:39]
	v_mfma_f32_16x16x32_bf16 v[32:35], v[152:155], v[196:199], v[32:35]
	v_mfma_f32_16x16x32_bf16 v[28:31], v[156:159], v[168:171], v[28:31]
	v_mfma_f32_16x16x32_bf16 v[24:27], v[156:159], v[180:183], v[24:27]
	v_mfma_f32_16x16x32_bf16 v[84:87], v[156:159], v[192:195], v[84:87]
	v_mfma_f32_16x16x32_bf16 v[76:79], v[156:159], v[196:199], v[76:79]
	v_mfma_f32_16x16x32_bf16 v[68:71], v[216:219], v[168:171], v[68:71]
	v_mfma_f32_16x16x32_bf16 v[56:59], v[216:219], v[180:183], v[56:59]
	v_mfma_f32_16x16x32_bf16 v[20:23], v[216:219], v[192:195], v[20:23]
	v_mfma_f32_16x16x32_bf16 v[144:147], v[216:219], v[196:199], v[144:147]
	s_add_u32 s8, s8, 0x80
	s_addc_u32 s9, s9, 0
	s_cmpk_lg_i32 s8, 0x780
	s_cbranch_scc1 .LBB0_313
	s_barrier
	s_mov_b32 m0, s62
	s_nop 0
	global_load_lds_dwordx4 v252, s[56:57]
	s_add_u32 m0, s62, 0x1000
	s_nop 0
	global_load_lds_dwordx4 v253, s[56:57]
	s_add_u32 s56, s56, 0x20000
	s_addc_u32 s57, s57, 0
	s_add_u32 m0, s62, 0x2000
	s_nop 0
	global_load_lds_dwordx4 v252, s[56:57]
	s_add_u32 m0, s62, 0x3000
	s_nop 0
	global_load_lds_dwordx4 v253, s[56:57]
	s_add_u32 s56, s56, 0x20000
	s_addc_u32 s57, s57, 0
	s_add_u32 m0, s62, 0x4000
	s_nop 0
	global_load_lds_dwordx4 v252, s[56:57]
	s_add_u32 m0, s62, 0x5000
	s_nop 0
	global_load_lds_dwordx4 v253, s[56:57]
	s_add_u32 s56, s56, 0x20000
	s_addc_u32 s57, s57, 0
	s_add_u32 m0, s62, 0x6000
	s_nop 0
	global_load_lds_dwordx4 v252, s[56:57]
	s_add_u32 m0, s62, 0x7000
	s_nop 0
	global_load_lds_dwordx4 v253, s[56:57]
	s_sub_u32 s56, s56, 0x60000
	s_subb_u32 s57, s57, 0
	s_add_u32 m0, s62, 0x8000
	s_nop 0
	global_load_lds_dwordx4 v252, s[58:59]
	s_add_u32 m0, s62, 0x9000
	s_nop 0
	global_load_lds_dwordx4 v253, s[58:59]
	s_add_u32 s58, s58, 0x20000
	s_addc_u32 s59, s59, 0
	s_add_u32 m0, s62, 0xa000
	s_nop 0
	global_load_lds_dwordx4 v252, s[58:59]
	s_add_u32 m0, s62, 0xb000
	s_nop 0
	global_load_lds_dwordx4 v253, s[58:59]
	s_sub_u32 s58, s58, 0x20000
	s_subb_u32 s59, s59, 0
	s_waitcnt vmcnt(0)
	s_barrier
	v_bfe_u32 v12, v208, 4, 1
	v_mul_u32_u24_e32 v12, 24, v12
	v_mov_b32_e32 v13, 0
	ds_read_b128 v[148:151], v215 offset:32768
	ds_read_b128 v[152:155], v215 offset:34816
	ds_read_b128 v[156:159], v215 offset:40960
	ds_read_b128 v[160:163], v215 offset:43008
	ds_read_b128 v[164:167], v213
	ds_read_b128 v[168:171], v213 offset:2048
	ds_read_b128 v[172:175], v213 offset:4096
	ds_read_b128 v[176:179], v213 offset:6144
	ds_read_b128 v[180:183], v213 offset:8192
	ds_read_b128 v[184:187], v213 offset:10240
	ds_read_b128 v[188:191], v213 offset:12288
	ds_read_b128 v[192:195], v213 offset:14336
	s_cmp_eq_u32 s42, 2
	s_mov_b32 s7, 0x6000000
	s_cselect_b32 s7, 0x2000000, s7
	s_waitcnt lgkmcnt(7)
	v_mfma_f32_16x16x32_bf16 v[140:143], v[164:167], v[148:151], v[140:143]
	s_add_u32 s8, s40, s7
	s_addc_u32 s9, s39, 0
	s_ashr_i32 s7, s6, 31
	v_mfma_f32_16x16x32_bf16 v[136:139], v[164:167], v[152:155], v[136:139]
	s_lshl_b64 s[6:7], s[6:7], 20
	s_add_u32 s6, s8, s6
	s_addc_u32 s7, s9, s7
	v_mfma_f32_16x16x32_bf16 v[132:135], v[164:167], v[156:159], v[132:135]
	s_lshl_b32 s8, s41, 1
	s_add_u32 s6, s6, s8
	s_addc_u32 s7, s7, 0
	v_mfma_f32_16x16x32_bf16 v[128:131], v[164:167], v[160:163], v[128:131]
	s_waitcnt lgkmcnt(6)
	v_mfma_f32_16x16x32_bf16 v[124:127], v[168:171], v[148:151], v[124:127]
	v_mfma_f32_16x16x32_bf16 v[120:123], v[168:171], v[152:155], v[120:123]
	v_mfma_f32_16x16x32_bf16 v[116:119], v[168:171], v[156:159], v[116:119]
	v_mfma_f32_16x16x32_bf16 v[112:115], v[168:171], v[160:163], v[112:115]
	s_waitcnt lgkmcnt(5)
	v_mfma_f32_16x16x32_bf16 v[108:111], v[172:175], v[148:151], v[108:111]
	v_mfma_f32_16x16x32_bf16 v[104:107], v[172:175], v[152:155], v[104:107]
	v_mfma_f32_16x16x32_bf16 v[100:103], v[172:175], v[156:159], v[100:103]
	v_mfma_f32_16x16x32_bf16 v[96:99], v[172:175], v[160:163], v[96:99]
	s_waitcnt lgkmcnt(4)
	v_mfma_f32_16x16x32_bf16 v[92:95], v[176:179], v[148:151], v[92:95]
	v_mfma_f32_16x16x32_bf16 v[88:91], v[176:179], v[152:155], v[88:91]
	v_mfma_f32_16x16x32_bf16 v[80:83], v[176:179], v[156:159], v[80:83]
	v_mfma_f32_16x16x32_bf16 v[72:75], v[176:179], v[160:163], v[72:75]
	s_waitcnt lgkmcnt(3)
	v_mfma_f32_16x16x32_bf16 v[64:67], v[180:183], v[148:151], v[64:67]
	v_mfma_f32_16x16x32_bf16 v[60:63], v[180:183], v[152:155], v[60:63]
	v_mfma_f32_16x16x32_bf16 v[52:55], v[180:183], v[156:159], v[52:55]
	v_mfma_f32_16x16x32_bf16 v[48:51], v[180:183], v[160:163], v[48:51]
	s_waitcnt lgkmcnt(2)
; __device__ void even_in_tile(const P& p, int li_even, int tm, int tn, char* smem) {
;     ...
;   if (seg == 2 || seg == 5) {
;     gemm_core<MI, true>(A, 1024, B, 1024, 1024, smem, acc);
;     EPI_COORDS
;     bf16_t* dst = R + (seg == 2 ? R_MVT : R_RVT) + (size_t)bh * 128 * 4096;
; #pragma unroll
;     for (int i = 0; i < MI; ++i)
; #pragma unroll
;       for (int j = 0; j < 4; ++j) {
;         u32x2 v;
;         v.x = pk_bf16(acc[i][j][0], acc[i][j][1]);
;         v.y = pk_bf16(acc[i][j][2], acc[i][j][3]);
;         *(u32x2*)(dst + (size_t)NCOLS(j) * 4096 + s0 + MROWS(i)) = v;
;       }
	v_mfma_f32_16x16x32_bf16 v[44:47], v[184:187], v[148:151], v[44:47]
	v_mfma_f32_16x16x32_bf16 v[40:43], v[184:187], v[152:155], v[40:43]
	v_mfma_f32_16x16x32_bf16 v[36:39], v[184:187], v[156:159], v[36:39]
	v_mfma_f32_16x16x32_bf16 v[32:35], v[184:187], v[160:163], v[32:35]
	s_waitcnt lgkmcnt(1)
	v_mfma_f32_16x16x32_bf16 v[28:31], v[188:191], v[148:151], v[28:31]
	v_mfma_f32_16x16x32_bf16 v[24:27], v[188:191], v[152:155], v[24:27]
	v_mfma_f32_16x16x32_bf16 v[164:167], v[188:191], v[156:159], v[84:87]
	v_mfma_f32_16x16x32_bf16 v[168:171], v[188:191], v[160:163], v[76:79]
	s_waitcnt lgkmcnt(0)
	v_mfma_f32_16x16x32_bf16 v[148:151], v[192:195], v[148:151], v[68:71]
	v_mfma_f32_16x16x32_bf16 v[152:155], v[192:195], v[152:155], v[56:59]
	v_mfma_f32_16x16x32_bf16 v[20:23], v[192:195], v[156:159], v[20:23]
	v_mfma_f32_16x16x32_bf16 v[144:147], v[192:195], v[160:163], v[144:147]
	ds_read_b128 v[156:159], v207 offset:32768
	ds_read_b128 v[160:163], v207 offset:34816
	ds_read_b128 v[172:175], v207 offset:40960
	ds_read_b128 v[176:179], v207 offset:43008
	ds_read_b128 v[56:59], v0
	ds_read_b128 v[68:71], v0 offset:2048
	ds_read_b128 v[76:79], v0 offset:4096
	ds_read_b128 v[84:87], v0 offset:6144
	ds_read_b128 v[180:183], v0 offset:8192
	ds_read_b128 v[184:187], v0 offset:10240
	ds_read_b128 v[188:191], v0 offset:12288
	ds_read_b128 v[192:195], v0 offset:14336
	v_mov_b32_e32 v0, v208
	s_waitcnt lgkmcnt(7)
	v_mfma_f32_16x16x32_bf16 v[140:143], v[56:59], v[156:159], v[140:143]
	v_and_b32_e32 v2, 15, v0
	v_lshrrev_b32_e32 v3, 1, v0
	v_mfma_f32_16x16x32_bf16 v[196:199], v[56:59], v[160:163], v[136:139]
	s_nop 2
	v_and_or_b32 v136, v3, 32, v2
	v_and_b32_e32 v2, 0xffffff80, v0
	v_lshrrev_b32_e32 v0, 2, v0
	v_and_or_b32 v2, v0, 12, v2
	v_ashrrev_i32_e32 v3, 31, v2
	v_lshl_add_u64 v[2:3], v[2:3], 1, s[6:7]
	v_lshlrev_b32_e32 v0, 13, v136
	v_mfma_f32_16x16x32_bf16 v[200:203], v[56:59], v[172:175], v[132:135]
	v_cvt_pk_bf16_f32 v138, v140, v141
	v_cvt_pk_bf16_f32 v139, v142, v143
	v_lshl_add_u64 v[136:137], v[2:3], 0, v[0:1]
	v_mfma_f32_16x16x32_bf16 v[132:135], v[56:59], v[176:179], v[128:131]
	global_store_dwordx2 v[136:137], v[138:139], off
	v_or_b32_e32 v138, 0x20000, v0
	v_mov_b32_e32 v139, v1
	s_waitcnt lgkmcnt(6)
	v_mfma_f32_16x16x32_bf16 v[128:131], v[68:71], v[156:159], v[124:127]
	v_cvt_pk_bf16_f32 v140, v196, v197
	v_cvt_pk_bf16_f32 v141, v198, v199
	v_lshl_add_u64 v[142:143], v[2:3], 0, v[138:139]
	v_mfma_f32_16x16x32_bf16 v[124:127], v[68:71], v[160:163], v[120:123]
	global_store_dwordx2 v[142:143], v[140:141], off
	v_or_b32_e32 v140, 0x80000, v0
	v_or_b32_e32 v0, 0xa0000, v0
	v_mfma_f32_16x16x32_bf16 v[120:123], v[68:71], v[172:175], v[116:119]
	v_cvt_pk_bf16_f32 v132, v132, v133
	v_cvt_pk_bf16_f32 v133, v134, v135
	v_lshl_add_u64 v[134:135], v[2:3], 0, v[0:1]
	v_mfma_f32_16x16x32_bf16 v[116:119], v[68:71], v[176:179], v[112:115]
	global_store_dwordx2 v[134:135], v[132:133], off
	v_lshl_add_u64 v[132:133], v[2:3], 0, 32
	s_mov_b64 s[6:7], 0x60
	s_waitcnt lgkmcnt(5)
	v_mfma_f32_16x16x32_bf16 v[112:115], v[76:79], v[156:159], v[108:111]
	v_mov_b32_e32 v141, v1
	s_nop 1
	v_cvt_pk_bf16_f32 v116, v116, v117
	v_cvt_pk_bf16_f32 v117, v118, v119
	v_mfma_f32_16x16x32_bf16 v[108:111], v[76:79], v[160:163], v[104:107]
	v_lshl_add_u64 v[118:119], v[132:133], 0, v[0:1]
	global_store_dwordx2 v[118:119], v[116:117], off
	v_lshl_add_u64 v[116:117], v[2:3], 0, 64
	v_mfma_f32_16x16x32_bf16 v[104:107], v[76:79], v[172:175], v[100:103]
	v_cvt_pk_bf16_f32 v142, v200, v201
	v_cvt_pk_bf16_f32 v143, v202, v203
	v_cvt_pk_bf16_f32 v128, v128, v129
	v_mfma_f32_16x16x32_bf16 v[100:103], v[76:79], v[176:179], v[96:99]
	v_cvt_pk_bf16_f32 v129, v130, v131
	v_cvt_pk_bf16_f32 v124, v124, v125
	v_cvt_pk_bf16_f32 v125, v126, v127
	s_waitcnt lgkmcnt(4)
	v_mfma_f32_16x16x32_bf16 v[96:99], v[84:87], v[156:159], v[92:95]
	v_lshl_add_u64 v[126:127], v[132:133], 0, v[138:139]
	s_nop 1
	v_cvt_pk_bf16_f32 v100, v100, v101
	v_cvt_pk_bf16_f32 v101, v102, v103
	v_mfma_f32_16x16x32_bf16 v[92:95], v[84:87], v[160:163], v[88:91]
	v_lshl_add_u64 v[102:103], v[116:117], 0, v[0:1]
	global_store_dwordx2 v[102:103], v[100:101], off
	v_lshl_add_u64 v[100:101], v[2:3], 0, s[6:7]
	v_mfma_f32_16x16x32_bf16 v[88:91], v[84:87], v[172:175], v[80:83]
	s_mov_b64 s[6:7], 0x80
	v_cvt_pk_bf16_f32 v120, v120, v121
	v_cvt_pk_bf16_f32 v121, v122, v123
	v_mfma_f32_16x16x32_bf16 v[84:87], v[84:87], v[176:179], v[72:75]
	v_lshl_add_u64 v[122:123], v[132:133], 0, v[140:141]
	v_cvt_pk_bf16_f32 v112, v112, v113
	v_cvt_pk_bf16_f32 v113, v114, v115
	s_waitcnt lgkmcnt(3)
	v_mfma_f32_16x16x32_bf16 v[68:71], v[180:183], v[176:179], v[48:51]
	v_cvt_pk_bf16_f32 v108, v108, v109
	s_nop 1
	v_cvt_pk_bf16_f32 v84, v84, v85
	v_cvt_pk_bf16_f32 v85, v86, v87
	v_mfma_f32_16x16x32_bf16 v[72:75], v[180:183], v[172:175], v[52:55]
	v_lshl_add_u64 v[86:87], v[100:101], 0, v[0:1]
	global_store_dwordx2 v[86:87], v[84:85], off
	v_lshl_add_u64 v[84:85], v[2:3], 0, s[6:7]
	s_waitcnt lgkmcnt(2)
; __device__ void even_in_tile(const P& p, int li_even, int tm, int tn, char* smem) {
;     ...
; #pragma unroll
;     for (int i = 0; i < MI; ++i)
; #pragma unroll
;       for (int j = 0; j < 4; ++j) {
;         u32x2 v;
;         v.x = pk_bf16(acc[i][j][0], acc[i][j][1]);
;         v.y = pk_bf16(acc[i][j][2], acc[i][j][3]);
;         *(u32x2*)(dst + (size_t)NCOLS(j) * 4096 + s0 + MROWS(i)) = v;
;       }
	v_mfma_f32_16x16x32_bf16 v[52:55], v[184:187], v[176:179], v[32:35]
	v_cvt_pk_bf16_f32 v68, v68, v69
	v_cvt_pk_bf16_f32 v69, v70, v71
	v_lshl_add_u64 v[70:71], v[84:85], 0, v[0:1]
	s_mov_b64 s[6:7], 0xa0
	v_mfma_f32_16x16x32_bf16 v[80:83], v[180:183], v[156:159], v[64:67]
	global_store_dwordx2 v[70:71], v[68:69], off
	v_lshl_add_u64 v[68:69], v[2:3], 0, s[6:7]
	s_nop 0
	v_cvt_pk_bf16_f32 v52, v52, v53
	v_mfma_f32_16x16x32_bf16 v[76:79], v[180:183], v[160:163], v[60:63]
	v_cvt_pk_bf16_f32 v53, v54, v55
	v_lshl_add_u64 v[54:55], v[68:69], 0, v[0:1]
	s_mov_b64 s[6:7], 0xc0
	v_mfma_f32_16x16x32_bf16 v[64:67], v[184:187], v[156:159], v[44:47]
	global_store_dwordx2 v[54:55], v[52:53], off
	v_lshl_add_u64 v[52:53], v[2:3], 0, s[6:7]
	s_mov_b64 s[6:7], 0xe0
	v_mfma_f32_16x16x32_bf16 v[60:63], v[184:187], v[160:163], v[40:43]
	v_cvt_pk_bf16_f32 v109, v110, v111
	v_lshl_add_u64 v[110:111], v[116:117], 0, v[138:139]
	v_cvt_pk_bf16_f32 v104, v104, v105
	v_mfma_f32_16x16x32_bf16 v[56:59], v[184:187], v[172:175], v[36:39]
	v_cvt_pk_bf16_f32 v105, v106, v107
	v_lshl_add_u64 v[106:107], v[116:117], 0, v[140:141]
	v_cvt_pk_bf16_f32 v96, v96, v97
	s_waitcnt lgkmcnt(1)
	v_mfma_f32_16x16x32_bf16 v[48:51], v[188:191], v[156:159], v[28:31]
	v_cvt_pk_bf16_f32 v97, v98, v99
	v_cvt_pk_bf16_f32 v92, v92, v93
	v_cvt_pk_bf16_f32 v93, v94, v95
	v_mfma_f32_16x16x32_bf16 v[44:47], v[188:191], v[160:163], v[24:27]
	v_lshl_add_u64 v[94:95], v[100:101], 0, v[138:139]
	v_cvt_pk_bf16_f32 v88, v88, v89
	v_cvt_pk_bf16_f32 v89, v90, v91
	v_mfma_f32_16x16x32_bf16 v[40:43], v[188:191], v[172:175], v[164:167]
	v_lshl_add_u64 v[90:91], v[100:101], 0, v[140:141]
	v_cvt_pk_bf16_f32 v80, v80, v81
	v_cvt_pk_bf16_f32 v81, v82, v83
	v_mfma_f32_16x16x32_bf16 v[36:39], v[188:191], v[176:179], v[168:171]
	v_cvt_pk_bf16_f32 v76, v76, v77
	v_cvt_pk_bf16_f32 v77, v78, v79
	v_lshl_add_u64 v[78:79], v[84:85], 0, v[138:139]
	s_waitcnt lgkmcnt(0)
	v_mfma_f32_16x16x32_bf16 v[32:35], v[192:195], v[156:159], v[148:151]
	v_cvt_pk_bf16_f32 v72, v72, v73
	v_cvt_pk_bf16_f32 v73, v74, v75
	v_lshl_add_u64 v[74:75], v[84:85], 0, v[140:141]
	v_mfma_f32_16x16x32_bf16 v[28:31], v[192:195], v[160:163], v[152:155]
	v_cvt_pk_bf16_f32 v64, v64, v65
	v_cvt_pk_bf16_f32 v65, v66, v67
	v_cvt_pk_bf16_f32 v60, v60, v61
	v_mfma_f32_16x16x32_bf16 v[24:27], v[192:195], v[172:175], v[20:23]
	v_cvt_pk_bf16_f32 v61, v62, v63
	v_lshl_add_u64 v[62:63], v[68:69], 0, v[138:139]
	v_cvt_pk_bf16_f32 v56, v56, v57
	v_mfma_f32_16x16x32_bf16 v[20:23], v[192:195], v[176:179], v[144:147]
	v_cvt_pk_bf16_f32 v57, v58, v59
	v_lshl_add_u64 v[58:59], v[68:69], 0, v[140:141]
	v_cvt_pk_bf16_f32 v48, v48, v49
	v_lshl_add_u64 v[144:145], v[2:3], 0, v[140:141]
	v_lshl_add_u64 v[2:3], v[2:3], 0, s[6:7]
	v_cvt_pk_bf16_f32 v49, v50, v51
	v_cvt_pk_bf16_f32 v44, v44, v45
	v_cvt_pk_bf16_f32 v45, v46, v47
	v_lshl_add_u64 v[46:47], v[52:53], 0, v[138:139]
	v_cvt_pk_bf16_f32 v40, v40, v41
	v_cvt_pk_bf16_f32 v41, v42, v43
	v_lshl_add_u64 v[42:43], v[52:53], 0, v[140:141]
	v_cvt_pk_bf16_f32 v36, v36, v37
	v_cvt_pk_bf16_f32 v37, v38, v39
	v_lshl_add_u64 v[38:39], v[52:53], 0, v[0:1]
	v_cvt_pk_bf16_f32 v32, v32, v33
	v_cvt_pk_bf16_f32 v33, v34, v35
	v_cvt_pk_bf16_f32 v28, v28, v29
	v_cvt_pk_bf16_f32 v29, v30, v31
	v_lshl_add_u64 v[30:31], v[2:3], 0, v[138:139]
	v_cvt_pk_bf16_f32 v24, v24, v25
	v_cvt_pk_bf16_f32 v25, v26, v27
	v_lshl_add_u64 v[26:27], v[2:3], 0, v[140:141]
	v_cvt_pk_bf16_f32 v20, v20, v21
	v_cvt_pk_bf16_f32 v21, v22, v23
	v_lshl_add_u64 v[2:3], v[2:3], 0, v[0:1]
	global_store_dwordx2 v[144:145], v[142:143], off
	global_store_dwordx2 v[136:137], v[128:129], off offset:32
	global_store_dwordx2 v[126:127], v[124:125], off
	global_store_dwordx2 v[122:123], v[120:121], off
	global_store_dwordx2 v[136:137], v[112:113], off offset:64
	global_store_dwordx2 v[110:111], v[108:109], off
	global_store_dwordx2 v[106:107], v[104:105], off
	global_store_dwordx2 v[136:137], v[96:97], off offset:96
	global_store_dwordx2 v[94:95], v[92:93], off
	global_store_dwordx2 v[90:91], v[88:89], off
	global_store_dwordx2 v[136:137], v[80:81], off offset:128
	global_store_dwordx2 v[78:79], v[76:77], off
	global_store_dwordx2 v[74:75], v[72:73], off
	global_store_dwordx2 v[136:137], v[64:65], off offset:160
	global_store_dwordx2 v[62:63], v[60:61], off
	global_store_dwordx2 v[58:59], v[56:57], off
	global_store_dwordx2 v[136:137], v[48:49], off offset:192
	global_store_dwordx2 v[46:47], v[44:45], off
	global_store_dwordx2 v[42:43], v[40:41], off
	global_store_dwordx2 v[38:39], v[36:37], off
	global_store_dwordx2 v[136:137], v[32:33], off offset:224
	global_store_dwordx2 v[30:31], v[28:29], off
	global_store_dwordx2 v[26:27], v[24:25], off
	global_store_dwordx2 v[2:3], v[20:21], off
	s_branch .LBB0_294

; template <int MI, bool SWAP, bool F8 = false>
; __device__ __forceinline__ void gemm_core(const bf16_t* __restrict__ A, int lda, const bf16_t* __restrict__ B, int ldb,
;                                           int K, char* smem, f32x4 (&acc)[MI][4]) {
;     ...
;   for (int kt = 0; kt < nk; ++kt) {
;     __syncthreads();
; #pragma unroll
;     for (int i = 0; i < MI; ++i) *(u32x4*)(smem + woff + i * 4096) = ra[i];
; #pragma unroll
;     for (int i = 0; i < 4; ++i) *(u32x4*)(smem + 32768 + woff + i * 4096) = rb[i];
;     __syncthreads();
;     if (kt + 1 < nk) {
; #pragma unroll
;       for (int i = 0; i < MI; ++i) ra[i] = *(const u32x4*)(ap + (size_t)(32 * i) * lda + (kt + 1) * 64);
; #pragma unroll
;       for (int i = 0; i < 4; ++i) rb[i] = *(const u32x4*)(bp + (size_t)(32 * i) * ldb + (kt + 1) * 64);
;     }
;     if (F8) {
;       const int c0 = (g ^ (li & 7)) << 4, c1 = ((4 + g) ^ (li & 7)) << 4;
;       i32x8 wf8[4];
; #pragma unroll
;       for (int j = 0; j < 4; ++j) {
;         const char* rp = smem + wrow + ((j & 1) * 16 + (j >> 1) * 64) * 128;
;         const u32x4 lo = *(const u32x4*)(rp + c0), hi = *(const u32x4*)(rp + c1);
;         wf8[j] = (i32x8){(int)lo.x, (int)lo.y, (int)lo.z, (int)lo.w, (int)hi.x, (int)hi.y, (int)hi.z, (int)hi.w};
;       }
; #pragma unroll
;       for (int i = 0; i < MI; ++i) {
;         const char* rp = smem + xrow + i * 2048;
;         const u32x4 lo = *(const u32x4*)(rp + c0), hi = *(const u32x4*)(rp + c1);
;         const i32x8 xf8 = {(int)lo.x, (int)lo.y, (int)lo.z, (int)lo.w, (int)hi.x, (int)hi.y, (int)hi.z, (int)hi.w};
; #pragma unroll
;         for (int j = 0; j < 4; ++j)
;           acc[i][j] = __builtin_amdgcn_mfma_scale_f32_16x16x128_f8f6f4(wf8[j], xf8, acc[i][j], 0, 0, 0, 0x77777777, 0, 0x7f7f7f7f);
;       }
.LBB0_944:
	v_add_u32_e32 v222, v215, v218
	v_add_u32_e32 v223, v215, v219
	s_barrier
	s_mov_b32 m0, s62
	s_nop 0
	global_load_lds_dwordx4 v252, s[56:57]
	s_add_u32 m0, s62, 0x1000
	s_nop 0
	global_load_lds_dwordx4 v253, s[56:57]
	s_add_u32 s56, s56, 0x10000
	s_addc_u32 s57, s57, 0
	s_add_u32 m0, s62, 0x2000
	s_nop 0
	global_load_lds_dwordx4 v252, s[56:57]
	s_add_u32 m0, s62, 0x3000
	s_nop 0
	global_load_lds_dwordx4 v253, s[56:57]
	s_add_u32 s56, s56, 0x10000
	s_addc_u32 s57, s57, 0
	s_add_u32 m0, s62, 0x4000
	s_nop 0
	global_load_lds_dwordx4 v252, s[56:57]
	s_add_u32 m0, s62, 0x5000
	s_nop 0
	global_load_lds_dwordx4 v253, s[56:57]
	s_add_u32 s56, s56, 0x10000
	s_addc_u32 s57, s57, 0
	s_add_u32 m0, s62, 0x6000
	s_nop 0
	global_load_lds_dwordx4 v252, s[56:57]
	s_add_u32 m0, s62, 0x7000
	s_nop 0
	global_load_lds_dwordx4 v253, s[56:57]
	s_sub_u32 s56, s56, 0x30000
	s_subb_u32 s57, s57, 0
	s_add_u32 m0, s62, 0x8000
	s_nop 0
	global_load_lds_dwordx4 v252, s[58:59]
	s_add_u32 m0, s62, 0x9000
	s_nop 0
	global_load_lds_dwordx4 v253, s[58:59]
	s_add_u32 s58, s58, 0x10000
	s_addc_u32 s59, s59, 0
	s_add_u32 m0, s62, 0xa000
	s_nop 0
	global_load_lds_dwordx4 v252, s[58:59]
	s_add_u32 m0, s62, 0xb000
	s_nop 0
	global_load_lds_dwordx4 v253, s[58:59]
	s_sub_u32 s58, s58, 0x10000
	s_subb_u32 s59, s59, 0
	v_add_u32_e32 v252, 0x80, v252
	v_add_u32_e32 v253, 0x80, v253
	s_waitcnt vmcnt(0)
	s_barrier
	v_add_u32_e32 v221, v213, v218
	v_add_u32_e32 v220, v213, v219
	ds_read_b128 v[44:47], v222 offset:32768
	ds_read_b128 v[48:51], v223 offset:32768
	ds_read_b128 v[180:183], v221
	ds_read_b128 v[184:187], v220
	ds_read_b128 v[20:23], v222 offset:34816
	ds_read_b128 v[24:27], v223 offset:34816
	ds_read_b128 v[188:191], v221 offset:2048
	ds_read_b128 v[192:195], v220 offset:2048
	ds_read_b128 v[32:35], v223 offset:40960
	ds_read_b128 v[28:31], v222 offset:40960
	ds_read_b128 v[36:39], v222 offset:43008
	ds_read_b128 v[40:43], v223 offset:43008
	s_waitcnt lgkmcnt(8)
	v_mfma_scale_f32_16x16x128_f8f6f4 v[176:179], v[44:51], v[180:187], v[176:179], v239, v238 op_sel_hi:[0,0,0]
	s_waitcnt lgkmcnt(6)
	v_mfma_scale_f32_16x16x128_f8f6f4 v[172:175], v[20:27], v[180:187], v[172:175], v239, v238 op_sel_hi:[0,0,0]
	s_waitcnt lgkmcnt(2)
	v_mfma_scale_f32_16x16x128_f8f6f4 v[168:171], v[28:35], v[180:187], v[168:171], v239, v238 op_sel_hi:[0,0,0]
	s_waitcnt lgkmcnt(0)
	v_mfma_scale_f32_16x16x128_f8f6f4 v[164:167], v[36:43], v[180:187], v[164:167], v239, v238 op_sel_hi:[0,0,0]
	v_mfma_scale_f32_16x16x128_f8f6f4 v[160:163], v[44:51], v[188:195], v[160:163], v239, v238 op_sel_hi:[0,0,0]
	v_mfma_scale_f32_16x16x128_f8f6f4 v[156:159], v[20:27], v[188:195], v[156:159], v239, v238 op_sel_hi:[0,0,0]
	v_mfma_scale_f32_16x16x128_f8f6f4 v[152:155], v[28:35], v[188:195], v[152:155], v239, v238 op_sel_hi:[0,0,0]
	v_mfma_scale_f32_16x16x128_f8f6f4 v[148:151], v[36:43], v[188:195], v[148:151], v239, v238 op_sel_hi:[0,0,0]
	ds_read_b128 v[184:187], v220 offset:4096
	ds_read_b128 v[180:183], v221 offset:4096
	ds_read_b128 v[188:191], v221 offset:6144
	ds_read_b128 v[192:195], v220 offset:6144
	s_waitcnt lgkmcnt(2)
	v_mfma_scale_f32_16x16x128_f8f6f4 v[144:147], v[44:51], v[180:187], v[144:147], v239, v238 op_sel_hi:[0,0,0]
	v_mfma_scale_f32_16x16x128_f8f6f4 v[140:143], v[20:27], v[180:187], v[140:143], v239, v238 op_sel_hi:[0,0,0]
	v_mfma_scale_f32_16x16x128_f8f6f4 v[136:139], v[28:35], v[180:187], v[136:139], v239, v238 op_sel_hi:[0,0,0]
	v_mfma_scale_f32_16x16x128_f8f6f4 v[132:135], v[36:43], v[180:187], v[132:135], v239, v238 op_sel_hi:[0,0,0]
	s_waitcnt lgkmcnt(0)
	v_mfma_scale_f32_16x16x128_f8f6f4 v[128:131], v[44:51], v[188:195], v[128:131], v239, v238 op_sel_hi:[0,0,0]
	v_mfma_scale_f32_16x16x128_f8f6f4 v[124:127], v[20:27], v[188:195], v[124:127], v239, v238 op_sel_hi:[0,0,0]
	v_mfma_scale_f32_16x16x128_f8f6f4 v[120:123], v[28:35], v[188:195], v[120:123], v239, v238 op_sel_hi:[0,0,0]
	v_mfma_scale_f32_16x16x128_f8f6f4 v[116:119], v[36:43], v[188:195], v[116:119], v239, v238 op_sel_hi:[0,0,0]
	ds_read_b128 v[184:187], v220 offset:8192
	ds_read_b128 v[180:183], v221 offset:8192
	ds_read_b128 v[188:191], v221 offset:10240
	ds_read_b128 v[192:195], v220 offset:10240
	s_waitcnt lgkmcnt(0)
	v_mfma_scale_f32_16x16x128_f8f6f4 v[96:99], v[44:51], v[188:195], v[96:99], v239, v238 op_sel_hi:[0,0,0]
	v_mfma_scale_f32_16x16x128_f8f6f4 v[92:95], v[20:27], v[188:195], v[92:95], v239, v238 op_sel_hi:[0,0,0]
	v_mfma_scale_f32_16x16x128_f8f6f4 v[88:91], v[28:35], v[188:195], v[88:91], v239, v238 op_sel_hi:[0,0,0]
	v_mfma_scale_f32_16x16x128_f8f6f4 v[84:87], v[36:43], v[188:195], v[84:87], v239, v238 op_sel_hi:[0,0,0]
	v_mfma_scale_f32_16x16x128_f8f6f4 v[112:115], v[44:51], v[180:187], v[112:115], v239, v238 op_sel_hi:[0,0,0]
	v_mfma_scale_f32_16x16x128_f8f6f4 v[108:111], v[20:27], v[180:187], v[108:111], v239, v238 op_sel_hi:[0,0,0]
	v_mfma_scale_f32_16x16x128_f8f6f4 v[104:107], v[28:35], v[180:187], v[104:107], v239, v238 op_sel_hi:[0,0,0]
	v_mfma_scale_f32_16x16x128_f8f6f4 v[100:103], v[36:43], v[180:187], v[100:103], v239, v238 op_sel_hi:[0,0,0]
	ds_read_b128 v[180:183], v221 offset:12288
	ds_read_b128 v[184:187], v220 offset:12288
	ds_read_b128 v[224:227], v221 offset:14336
	ds_read_b128 v[228:231], v220 offset:14336
	s_waitcnt lgkmcnt(2)
	v_mfma_scale_f32_16x16x128_f8f6f4 v[80:83], v[44:51], v[180:187], v[80:83], v239, v238 op_sel_hi:[0,0,0]
	v_mfma_scale_f32_16x16x128_f8f6f4 v[76:79], v[20:27], v[180:187], v[76:79], v239, v238 op_sel_hi:[0,0,0]
	v_mfma_scale_f32_16x16x128_f8f6f4 v[72:75], v[28:35], v[180:187], v[72:75], v239, v238 op_sel_hi:[0,0,0]
	v_mfma_scale_f32_16x16x128_f8f6f4 v[68:71], v[36:43], v[180:187], v[68:71], v239, v238 op_sel_hi:[0,0,0]
	s_waitcnt lgkmcnt(0)
	v_mfma_scale_f32_16x16x128_f8f6f4 v[64:67], v[44:51], v[224:231], v[64:67], v239, v238 op_sel_hi:[0,0,0]
	v_mfma_scale_f32_16x16x128_f8f6f4 v[60:63], v[20:27], v[224:231], v[60:63], v239, v238 op_sel_hi:[0,0,0]
	v_mfma_scale_f32_16x16x128_f8f6f4 v[56:59], v[28:35], v[224:231], v[56:59], v239, v238 op_sel_hi:[0,0,0]
	v_mfma_scale_f32_16x16x128_f8f6f4 v[52:55], v[36:43], v[224:231], v[52:55], v239, v238 op_sel_hi:[0,0,0]
	s_add_u32 s8, s8, 0x80
	s_addc_u32 s9, s9, 0
	s_cmpk_lg_i32 s8, 0x380
	s_cbranch_scc1 .LBB0_944
; template <int MI, bool SWAP, bool F8 = false>
; __device__ __forceinline__ void gemm_core(const bf16_t* __restrict__ A, int lda, const bf16_t* __restrict__ B, int ldb,
;                                           int K, char* smem, f32x4 (&acc)[MI][4]) {
;     ...
;   for (int kt = 0; kt < nk; ++kt) {
;     __syncthreads();
; #pragma unroll
;     for (int i = 0; i < MI; ++i) *(u32x4*)(smem + woff + i * 4096) = ra[i];
; #pragma unroll
;     for (int i = 0; i < 4; ++i) *(u32x4*)(smem + 32768 + woff + i * 4096) = rb[i];
;     __syncthreads();
;     if (kt + 1 < nk) {
; #pragma unroll
;       for (int i = 0; i < MI; ++i) ra[i] = *(const u32x4*)(ap + (size_t)(32 * i) * lda + (kt + 1) * 64);
; #pragma unroll
;       for (int i = 0; i < 4; ++i) rb[i] = *(const u32x4*)(bp + (size_t)(32 * i) * ldb + (kt + 1) * 64);
;     }
;     if (F8) {
;       const int c0 = (g ^ (li & 7)) << 4, c1 = ((4 + g) ^ (li & 7)) << 4;
;       i32x8 wf8[4];
; #pragma unroll
;       for (int j = 0; j < 4; ++j) {
;         const char* rp = smem + wrow + ((j & 1) * 16 + (j >> 1) * 64) * 128;
;         const u32x4 lo = *(const u32x4*)(rp + c0), hi = *(const u32x4*)(rp + c1);
;         wf8[j] = (i32x8){(int)lo.x, (int)lo.y, (int)lo.z, (int)lo.w, (int)hi.x, (int)hi.y, (int)hi.z, (int)hi.w};
;       }
; #pragma unroll
;       for (int i = 0; i < MI; ++i) {
;         const char* rp = smem + xrow + i * 2048;
;         const u32x4 lo = *(const u32x4*)(rp + c0), hi = *(const u32x4*)(rp + c1);
;         const i32x8 xf8 = {(int)lo.x, (int)lo.y, (int)lo.z, (int)lo.w, (int)hi.x, (int)hi.y, (int)hi.z, (int)hi.w};
; #pragma unroll
;         for (int j = 0; j < 4; ++j)
;           acc[i][j] = __builtin_amdgcn_mfma_scale_f32_16x16x128_f8f6f4(wf8[j], xf8, acc[i][j], 0, 0, 0, 0x77777777, 0, 0x7f7f7f7f);
;       }
	s_barrier
	s_mov_b32 m0, s62
	s_nop 0
	global_load_lds_dwordx4 v252, s[56:57]
	s_add_u32 m0, s62, 0x1000
	s_nop 0
	global_load_lds_dwordx4 v253, s[56:57]
	s_add_u32 s56, s56, 0x10000
	s_addc_u32 s57, s57, 0
	s_add_u32 m0, s62, 0x2000
	s_nop 0
	global_load_lds_dwordx4 v252, s[56:57]
	s_add_u32 m0, s62, 0x3000
	s_nop 0
	global_load_lds_dwordx4 v253, s[56:57]
	s_add_u32 s56, s56, 0x10000
	s_addc_u32 s57, s57, 0
	s_add_u32 m0, s62, 0x4000
	s_nop 0
	global_load_lds_dwordx4 v252, s[56:57]
	s_add_u32 m0, s62, 0x5000
	s_nop 0
	global_load_lds_dwordx4 v253, s[56:57]
	s_add_u32 s56, s56, 0x10000
	s_addc_u32 s57, s57, 0
	s_add_u32 m0, s62, 0x6000
	s_nop 0
	global_load_lds_dwordx4 v252, s[56:57]
	s_add_u32 m0, s62, 0x7000
	s_nop 0
	global_load_lds_dwordx4 v253, s[56:57]
	s_sub_u32 s56, s56, 0x30000
	s_subb_u32 s57, s57, 0
	s_add_u32 m0, s62, 0x8000
	s_nop 0
	global_load_lds_dwordx4 v252, s[58:59]
	s_add_u32 m0, s62, 0x9000
	s_nop 0
	global_load_lds_dwordx4 v253, s[58:59]
	s_add_u32 s58, s58, 0x10000
	s_addc_u32 s59, s59, 0
	s_add_u32 m0, s62, 0xa000
	s_nop 0
	global_load_lds_dwordx4 v252, s[58:59]
	s_add_u32 m0, s62, 0xb000
	s_nop 0
	global_load_lds_dwordx4 v253, s[58:59]
	s_sub_u32 s58, s58, 0x10000
	s_subb_u32 s59, s59, 0
	s_waitcnt vmcnt(0)
	s_barrier
	v_bfe_u32 v12, v208, 4, 1
	v_mul_u32_u24_e32 v12, 24, v12
	v_mov_b32_e32 v13, 0
	ds_read_b128 v[20:23], v222 offset:32768
	ds_read_b128 v[24:27], v223 offset:32768
	ds_read_b128 v[28:31], v222 offset:34816
	ds_read_b128 v[32:35], v223 offset:34816
	ds_read_b128 v[36:39], v222 offset:40960
	ds_read_b128 v[40:43], v223 offset:40960
	ds_read_b128 v[44:47], v222 offset:43008
	ds_read_b128 v[48:51], v223 offset:43008
	ds_read_b128 v[180:183], v221
	ds_read_b128 v[184:187], v220
	s_waitcnt lgkmcnt(0)
	v_mfma_scale_f32_16x16x128_f8f6f4 v[176:179], v[20:27], v[180:187], v[176:179], v239, v238 op_sel_hi:[0,0,0]
	s_lshl_b64 s[6:7], s[6:7], 20
	s_add_u32 s6, s42, s6
	s_addc_u32 s7, s43, s7
	s_lshl_b32 s8, s19, 1
	s_add_u32 s6, s6, s8
	s_addc_u32 s7, s7, 0
	s_add_i32 s18, s18, s78
	v_mfma_scale_f32_16x16x128_f8f6f4 v[172:175], v[28:35], v[180:187], v[172:175], v239, v238 op_sel_hi:[0,0,0]
	s_add_i32 s15, s15, s71
	s_add_i32 s14, s14, s76
	s_cmpk_gt_i32 s18, 0x3ff
	v_mfma_scale_f32_16x16x128_f8f6f4 v[168:171], v[36:43], v[180:187], v[168:171], v239, v238 op_sel_hi:[0,0,0]
	v_mfma_scale_f32_16x16x128_f8f6f4 v[164:167], v[44:51], v[180:187], v[164:167], v239, v238 op_sel_hi:[0,0,0]
	ds_read_b128 v[180:183], v221 offset:2048
	ds_read_b128 v[184:187], v220 offset:2048
	s_waitcnt lgkmcnt(0)
	v_mfma_scale_f32_16x16x128_f8f6f4 v[160:163], v[20:27], v[180:187], v[160:163], v239, v238 op_sel_hi:[0,0,0]
	v_mfma_scale_f32_16x16x128_f8f6f4 v[156:159], v[28:35], v[180:187], v[156:159], v239, v238 op_sel_hi:[0,0,0]
	v_mfma_scale_f32_16x16x128_f8f6f4 v[152:155], v[36:43], v[180:187], v[152:155], v239, v238 op_sel_hi:[0,0,0]
	v_mfma_scale_f32_16x16x128_f8f6f4 v[148:151], v[44:51], v[180:187], v[148:151], v239, v238 op_sel_hi:[0,0,0]
	ds_read_b128 v[180:183], v221 offset:4096
	ds_read_b128 v[184:187], v220 offset:4096
	s_waitcnt lgkmcnt(0)
	v_mfma_scale_f32_16x16x128_f8f6f4 v[144:147], v[20:27], v[180:187], v[144:147], v239, v238 op_sel_hi:[0,0,0]
	v_mfma_scale_f32_16x16x128_f8f6f4 v[140:143], v[28:35], v[180:187], v[140:143], v239, v238 op_sel_hi:[0,0,0]
	v_mfma_scale_f32_16x16x128_f8f6f4 v[136:139], v[36:43], v[180:187], v[136:139], v239, v238 op_sel_hi:[0,0,0]
	v_mfma_scale_f32_16x16x128_f8f6f4 v[132:135], v[44:51], v[180:187], v[132:135], v239, v238 op_sel_hi:[0,0,0]
	ds_read_b128 v[180:183], v221 offset:6144
	ds_read_b128 v[184:187], v220 offset:6144
	s_waitcnt lgkmcnt(0)
	v_mfma_scale_f32_16x16x128_f8f6f4 v[128:131], v[20:27], v[180:187], v[128:131], v239, v238 op_sel_hi:[0,0,0]
	v_mfma_scale_f32_16x16x128_f8f6f4 v[124:127], v[28:35], v[180:187], v[124:127], v239, v238 op_sel_hi:[0,0,0]
	v_mfma_scale_f32_16x16x128_f8f6f4 v[120:123], v[36:43], v[180:187], v[120:123], v239, v238 op_sel_hi:[0,0,0]
	v_mfma_scale_f32_16x16x128_f8f6f4 v[116:119], v[44:51], v[180:187], v[116:119], v239, v238 op_sel_hi:[0,0,0]
	ds_read_b128 v[180:183], v221 offset:8192
	ds_read_b128 v[184:187], v220 offset:8192
	s_waitcnt lgkmcnt(0)
	v_mfma_scale_f32_16x16x128_f8f6f4 v[112:115], v[20:27], v[180:187], v[112:115], v239, v238 op_sel_hi:[0,0,0]
	v_mfma_scale_f32_16x16x128_f8f6f4 v[108:111], v[28:35], v[180:187], v[108:111], v239, v238 op_sel_hi:[0,0,0]
	v_mfma_scale_f32_16x16x128_f8f6f4 v[104:107], v[36:43], v[180:187], v[104:107], v239, v238 op_sel_hi:[0,0,0]
	v_mfma_scale_f32_16x16x128_f8f6f4 v[100:103], v[44:51], v[180:187], v[100:103], v239, v238 op_sel_hi:[0,0,0]
	ds_read_b128 v[180:183], v221 offset:10240
	ds_read_b128 v[184:187], v220 offset:10240
	s_waitcnt lgkmcnt(0)
	v_mfma_scale_f32_16x16x128_f8f6f4 v[96:99], v[20:27], v[180:187], v[96:99], v239, v238 op_sel_hi:[0,0,0]
	v_mfma_scale_f32_16x16x128_f8f6f4 v[92:95], v[28:35], v[180:187], v[92:95], v239, v238 op_sel_hi:[0,0,0]
	v_mfma_scale_f32_16x16x128_f8f6f4 v[88:91], v[36:43], v[180:187], v[88:91], v239, v238 op_sel_hi:[0,0,0]
	v_mfma_scale_f32_16x16x128_f8f6f4 v[84:87], v[44:51], v[180:187], v[84:87], v239, v238 op_sel_hi:[0,0,0]
	ds_read_b128 v[180:183], v221 offset:12288
	ds_read_b128 v[184:187], v220 offset:12288
	s_waitcnt lgkmcnt(0)
	v_mfma_scale_f32_16x16x128_f8f6f4 v[80:83], v[20:27], v[180:187], v[80:83], v239, v238 op_sel_hi:[0,0,0]
	v_mfma_scale_f32_16x16x128_f8f6f4 v[76:79], v[28:35], v[180:187], v[76:79], v239, v238 op_sel_hi:[0,0,0]
	v_mfma_scale_f32_16x16x128_f8f6f4 v[72:75], v[36:43], v[180:187], v[72:75], v239, v238 op_sel_hi:[0,0,0]
	v_mfma_scale_f32_16x16x128_f8f6f4 v[68:71], v[44:51], v[180:187], v[68:71], v239, v238 op_sel_hi:[0,0,0]
	ds_read_b128 v[180:183], v221 offset:14336
	ds_read_b128 v[184:187], v220 offset:14336
	s_waitcnt lgkmcnt(0)
; template <int MI, bool F8 = false>
; __device__ void gemm_tile_bf16(const bf16_t* A, int lda, const bf16_t* B, int ldb, int K, bf16_t* C, int ldc, char* smem) {
;     ...
; #pragma unroll
;   for (int i = 0; i < MI; ++i)
; #pragma unroll
;     for (int j = 0; j < 4; ++j) {
;       u32x2 v;
;       v.x = pk_bf16(acc[i][j][0], acc[i][j][1]);
;       v.y = pk_bf16(acc[i][j][2], acc[i][j][3]);
;       *(u32x2*)(C + (size_t)MROW(i) * ldc + NCOL(j)) = v;
;     }
	v_mfma_scale_f32_16x16x128_f8f6f4 v[64:67], v[20:27], v[180:187], v[64:67], v239, v238 op_sel_hi:[0,0,0]
	v_mfma_scale_f32_16x16x128_f8f6f4 v[24:27], v[36:43], v[180:187], v[56:59], v239, v238 op_sel_hi:[0,0,0]
	v_mov_b32_e32 v36, v208
	s_nop 0
	v_lshrrev_b32_e32 v0, 1, v36
	v_and_b32_e32 v2, 0xffffff8f, v36
	v_and_b32_e32 v0, 32, v0
	v_lshrrev_b32_e32 v3, 2, v36
	v_and_or_b32 v0, v3, 12, v0
	v_ashrrev_i32_e32 v3, 31, v2
	v_mfma_scale_f32_16x16x128_f8f6f4 v[28:31], v[28:35], v[180:187], v[60:63], v239, v238 op_sel_hi:[0,0,0]
	v_lshlrev_b64 v[32:33], 12, v[2:3]
	v_lshl_add_u64 v[32:33], s[6:7], 0, v[32:33]
	v_lshlrev_b32_e32 v0, 1, v0
	v_cvt_pk_bf16_f32 v4, v176, v177
	v_cvt_pk_bf16_f32 v5, v178, v179
	v_lshl_add_u64 v[32:33], v[32:33], 0, v[0:1]
	v_cvt_pk_bf16_f32 v6, v172, v173
	v_cvt_pk_bf16_f32 v7, v174, v175
	s_nop 1
	v_permlane16_swap_b32_e32 v4, v6
	v_permlane16_swap_b32_e32 v5, v7
	v_lshl_add_u64 v[14:15], v[32:33], 0, v[12:13]
	global_store_dwordx4 v[14:15], v[4:7], off
	v_cvt_pk_bf16_f32 v8, v168, v169
	v_cvt_pk_bf16_f32 v9, v170, v171
	v_cvt_pk_bf16_f32 v10, v164, v165
	v_cvt_pk_bf16_f32 v11, v166, v167
	s_nop 1
	v_permlane16_swap_b32_e32 v8, v10
	v_permlane16_swap_b32_e32 v9, v11
	v_lshl_add_u64 v[14:15], v[32:33], 0, v[12:13]
	global_store_dwordx4 v[14:15], v[8:11], off offset:128
	v_or_b32_e32 v32, 16, v2
	v_ashrrev_i32_e32 v33, 31, v32
	v_lshlrev_b64 v[32:33], 12, v[32:33]
	v_lshl_add_u64 v[32:33], s[6:7], 0, v[32:33]
	v_cvt_pk_bf16_f32 v4, v160, v161
	v_cvt_pk_bf16_f32 v5, v162, v163
	v_lshl_add_u64 v[32:33], v[32:33], 0, v[0:1]
	v_cvt_pk_bf16_f32 v6, v156, v157
	v_cvt_pk_bf16_f32 v7, v158, v159
	s_nop 1
	v_permlane16_swap_b32_e32 v4, v6
	v_permlane16_swap_b32_e32 v5, v7
	v_lshl_add_u64 v[14:15], v[32:33], 0, v[12:13]
	global_store_dwordx4 v[14:15], v[4:7], off
	v_cvt_pk_bf16_f32 v8, v152, v153
	v_cvt_pk_bf16_f32 v9, v154, v155
	v_cvt_pk_bf16_f32 v10, v148, v149
	v_cvt_pk_bf16_f32 v11, v150, v151
	s_nop 1
	v_permlane16_swap_b32_e32 v8, v10
	v_permlane16_swap_b32_e32 v9, v11
	v_lshl_add_u64 v[14:15], v[32:33], 0, v[12:13]
	global_store_dwordx4 v[14:15], v[8:11], off offset:128
	v_or_b32_e32 v32, 32, v2
	v_ashrrev_i32_e32 v33, 31, v32
	v_lshlrev_b64 v[32:33], 12, v[32:33]
	v_lshl_add_u64 v[32:33], s[6:7], 0, v[32:33]
	v_cvt_pk_bf16_f32 v4, v144, v145
	v_cvt_pk_bf16_f32 v5, v146, v147
	v_lshl_add_u64 v[32:33], v[32:33], 0, v[0:1]
	v_cvt_pk_bf16_f32 v6, v140, v141
	v_cvt_pk_bf16_f32 v7, v142, v143
	s_nop 1
	v_permlane16_swap_b32_e32 v4, v6
	v_permlane16_swap_b32_e32 v5, v7
	v_lshl_add_u64 v[14:15], v[32:33], 0, v[12:13]
	global_store_dwordx4 v[14:15], v[4:7], off
	v_cvt_pk_bf16_f32 v8, v136, v137
	v_cvt_pk_bf16_f32 v9, v138, v139
	v_cvt_pk_bf16_f32 v10, v132, v133
	v_cvt_pk_bf16_f32 v11, v134, v135
	s_nop 1
	v_permlane16_swap_b32_e32 v8, v10
	v_permlane16_swap_b32_e32 v9, v11
	v_lshl_add_u64 v[14:15], v[32:33], 0, v[12:13]
	global_store_dwordx4 v[14:15], v[8:11], off offset:128
	v_or_b32_e32 v32, 48, v2
	v_ashrrev_i32_e32 v33, 31, v32
	v_lshlrev_b64 v[32:33], 12, v[32:33]
	v_lshl_add_u64 v[32:33], s[6:7], 0, v[32:33]
	v_cvt_pk_bf16_f32 v4, v128, v129
	v_cvt_pk_bf16_f32 v5, v130, v131
	v_lshl_add_u64 v[32:33], v[32:33], 0, v[0:1]
	v_cvt_pk_bf16_f32 v6, v124, v125
	v_cvt_pk_bf16_f32 v7, v126, v127
	s_nop 1
	v_permlane16_swap_b32_e32 v4, v6
	v_permlane16_swap_b32_e32 v5, v7
	v_lshl_add_u64 v[14:15], v[32:33], 0, v[12:13]
	global_store_dwordx4 v[14:15], v[4:7], off
	v_cvt_pk_bf16_f32 v8, v120, v121
	v_cvt_pk_bf16_f32 v9, v122, v123
	v_cvt_pk_bf16_f32 v10, v116, v117
	v_cvt_pk_bf16_f32 v11, v118, v119
	s_nop 1
	v_permlane16_swap_b32_e32 v8, v10
; template <int MI, bool F8 = false>
; __device__ void gemm_tile_bf16(const bf16_t* A, int lda, const bf16_t* B, int ldb, int K, bf16_t* C, int ldc, char* smem) {
;     ...
; #pragma unroll
;   for (int i = 0; i < MI; ++i)
; #pragma unroll
;     for (int j = 0; j < 4; ++j) {
;       u32x2 v;
;       v.x = pk_bf16(acc[i][j][0], acc[i][j][1]);
;       v.y = pk_bf16(acc[i][j][2], acc[i][j][3]);
;       *(u32x2*)(C + (size_t)MROW(i) * ldc + NCOL(j)) = v;
;     }
	v_permlane16_swap_b32_e32 v9, v11
	v_lshl_add_u64 v[14:15], v[32:33], 0, v[12:13]
	global_store_dwordx4 v[14:15], v[8:11], off offset:128
	v_or_b32_e32 v32, 64, v2
	v_ashrrev_i32_e32 v33, 31, v32
	v_lshlrev_b64 v[32:33], 12, v[32:33]
	v_lshl_add_u64 v[32:33], s[6:7], 0, v[32:33]
	v_cvt_pk_bf16_f32 v4, v112, v113
	v_cvt_pk_bf16_f32 v5, v114, v115
	v_lshl_add_u64 v[32:33], v[32:33], 0, v[0:1]
	v_cvt_pk_bf16_f32 v6, v108, v109
	v_cvt_pk_bf16_f32 v7, v110, v111
	s_nop 1
	v_permlane16_swap_b32_e32 v4, v6
	v_permlane16_swap_b32_e32 v5, v7
	v_lshl_add_u64 v[14:15], v[32:33], 0, v[12:13]
	global_store_dwordx4 v[14:15], v[4:7], off
	v_cvt_pk_bf16_f32 v8, v104, v105
	v_cvt_pk_bf16_f32 v9, v106, v107
	v_cvt_pk_bf16_f32 v10, v100, v101
	v_cvt_pk_bf16_f32 v11, v102, v103
	s_nop 1
	v_permlane16_swap_b32_e32 v8, v10
	v_permlane16_swap_b32_e32 v9, v11
	v_lshl_add_u64 v[14:15], v[32:33], 0, v[12:13]
	global_store_dwordx4 v[14:15], v[8:11], off offset:128
	v_or_b32_e32 v32, 0x50, v2
	v_ashrrev_i32_e32 v33, 31, v32
	v_lshlrev_b64 v[32:33], 12, v[32:33]
	v_lshl_add_u64 v[32:33], s[6:7], 0, v[32:33]
	v_cvt_pk_bf16_f32 v4, v96, v97
	v_cvt_pk_bf16_f32 v5, v98, v99
	v_lshl_add_u64 v[32:33], v[32:33], 0, v[0:1]
	v_or_b32_e32 v2, 0x60, v2
	v_cvt_pk_bf16_f32 v6, v92, v93
	v_cvt_pk_bf16_f32 v7, v94, v95
	v_ashrrev_i32_e32 v3, 31, v2
	s_nop 1
	v_permlane16_swap_b32_e32 v4, v6
	v_permlane16_swap_b32_e32 v5, v7
	v_lshl_add_u64 v[14:15], v[32:33], 0, v[12:13]
	global_store_dwordx4 v[14:15], v[4:7], off
	v_cvt_pk_bf16_f32 v8, v88, v89
	v_cvt_pk_bf16_f32 v9, v90, v91
	v_lshlrev_b64 v[2:3], 12, v[2:3]
	v_cvt_pk_bf16_f32 v10, v84, v85
	v_cvt_pk_bf16_f32 v11, v86, v87
	v_lshl_add_u64 v[2:3], s[6:7], 0, v[2:3]
	v_mfma_scale_f32_16x16x128_f8f6f4 v[20:23], v[44:51], v[180:187], v[52:55], v239, v238 op_sel_hi:[0,0,0]
	s_nop 1
	v_permlane16_swap_b32_e32 v8, v10
	v_permlane16_swap_b32_e32 v9, v11
	v_lshl_add_u64 v[14:15], v[32:33], 0, v[12:13]
	global_store_dwordx4 v[14:15], v[8:11], off offset:128
	v_cvt_pk_bf16_f32 v4, v80, v81
	v_cvt_pk_bf16_f32 v5, v82, v83
	v_lshl_add_u64 v[2:3], v[2:3], 0, v[0:1]
	v_cvt_pk_bf16_f32 v6, v76, v77
	v_cvt_pk_bf16_f32 v7, v78, v79
	s_nop 1
	v_permlane16_swap_b32_e32 v4, v6
	v_permlane16_swap_b32_e32 v5, v7
	v_lshl_add_u64 v[14:15], v[2:3], 0, v[12:13]
	global_store_dwordx4 v[14:15], v[4:7], off
	v_cvt_pk_bf16_f32 v8, v72, v73
	v_cvt_pk_bf16_f32 v9, v74, v75
	v_cvt_pk_bf16_f32 v10, v68, v69
	v_cvt_pk_bf16_f32 v11, v70, v71
	s_nop 1
	v_permlane16_swap_b32_e32 v8, v10
	v_permlane16_swap_b32_e32 v9, v11
	v_lshl_add_u64 v[14:15], v[2:3], 0, v[12:13]
	global_store_dwordx4 v[14:15], v[8:11], off offset:128
	v_or_b32_e32 v2, 0x70, v36
	v_ashrrev_i32_e32 v3, 31, v2
	v_lshlrev_b64 v[2:3], 12, v[2:3]
	v_lshl_add_u64 v[2:3], s[6:7], 0, v[2:3]
	v_cvt_pk_bf16_f32 v32, v64, v65
	v_cvt_pk_bf16_f32 v33, v66, v67
	v_lshl_add_u64 v[2:3], v[2:3], 0, v[0:1]
	v_cvt_pk_bf16_f32 v28, v28, v29
	v_cvt_pk_bf16_f32 v29, v30, v31
	v_cvt_pk_bf16_f32 v24, v24, v25
	v_cvt_pk_bf16_f32 v25, v26, v27
	v_cvt_pk_bf16_f32 v20, v20, v21
	v_cvt_pk_bf16_f32 v21, v22, v23
	v_mov_b64_e32 v[4:5], v[32:33]
	v_mov_b64_e32 v[6:7], v[28:29]
	s_nop 1
	v_permlane16_swap_b32_e32 v4, v6
	v_permlane16_swap_b32_e32 v5, v7
	v_lshl_add_u64 v[14:15], v[2:3], 0, v[12:13]
	global_store_dwordx4 v[14:15], v[4:7], off
	v_mov_b64_e32 v[8:9], v[24:25]
	v_mov_b64_e32 v[10:11], v[20:21]
	s_nop 1
	v_permlane16_swap_b32_e32 v8, v10
	v_permlane16_swap_b32_e32 v9, v11
	v_lshl_add_u64 v[14:15], v[2:3], 0, v[12:13]
	global_store_dwordx4 v[14:15], v[8:11], off offset:128
	s_cbranch_scc0 .LBB0_943
